# GEMM loops: wave priority raised during the load role (LDS reads + DMA issue) instead of during the MFMA block
# speedup vs baseline: 1.0001x; 1.0001x over previous
.LBB0_122:
	s_cmp_eq_u32 s89, 12
	s_cselect_b32 s42, s20, s65
	s_cselect_b32 s43, s16, s86
	s_cselect_b32 s45, s31, s88
	s_cselect_b32 s44, s59, s87
	s_add_u32 s38, s42, 0x80
	s_addc_u32 s39, s43, 0
	s_add_u32 s74, s44, 0x80
	s_addc_u32 s75, s45, 0
	s_add_i32 s35, 0, 0x10000
	s_mov_b64 s[18:19], s[68:69]
	v_add_u32_e32 v140, s35, v142
	s_add_i32 s49, 0, 0x14000
	ds_read_b128 v[136:139], v140
	ds_read_b128 v[144:147], v140 offset:1024
	ds_read_b128 v[148:151], v140 offset:2048
	ds_read_b128 v[152:155], v140 offset:3072
	v_add_u32_e32 v140, s49, v142
	ds_read_b128 v[156:159], v140
	ds_read_b128 v[160:163], v140 offset:1024
	ds_read_b128 v[164:167], v140 offset:2048
	ds_read_b128 v[168:171], v140 offset:3072
	s_mov_b32 m0, s81
	ds_read_b128 v[172:175], v143
	ds_read_b128 v[176:179], v143 offset:1024
	ds_read_b128 v[180:183], v143 offset:2048
	ds_read_b128 v[184:187], v143 offset:3072
	ds_read_b128 v[188:191], v143 offset:4096
	ds_read_b128 v[192:195], v143 offset:5120
	ds_read_b128 v[196:199], v143 offset:6144
	ds_read_b128 v[200:203], v143 offset:7168
	global_load_lds_dwordx4 v130, s[18:19]
	s_mov_b32 m0, s82
	s_nop 0
	global_load_lds_dwordx4 v132, s[18:19]
	s_add_u32 s18, s18, 0x40000
	s_addc_u32 s19, s19, 0
	s_add_i32 m0, s67, 0xc000
	s_nop 0
	global_load_lds_dwordx4 v130, s[18:19]
	s_add_i32 m0, s67, 0xe000
	s_nop 0
	global_load_lds_dwordx4 v132, s[18:19]
	s_waitcnt vmcnt(8)
	s_waitcnt lgkmcnt(0)
	s_barrier
	s_setprio 0
	s_waitcnt lgkmcnt(0)
	v_mfma_f32_16x16x32_bf16 v[126:129], v[136:139], v[172:175], v[126:129]
	v_mfma_f32_16x16x32_bf16 v[122:125], v[148:151], v[172:175], v[122:125]
	v_mfma_f32_16x16x32_bf16 v[110:113], v[136:139], v[180:183], v[110:113]
	v_mfma_f32_16x16x32_bf16 v[106:109], v[148:151], v[180:183], v[106:109]
	v_mfma_f32_16x16x32_bf16 v[92:95], v[136:139], v[188:191], v[92:95]
	v_mfma_f32_16x16x32_bf16 v[88:91], v[148:151], v[188:191], v[88:91]
	v_mfma_f32_16x16x32_bf16 v[76:79], v[136:139], v[196:199], v[76:79]
	v_mfma_f32_16x16x32_bf16 v[72:75], v[148:151], v[196:199], v[72:75]
	v_mfma_f32_16x16x32_bf16 v[126:129], v[144:147], v[176:179], v[126:129]
	v_mfma_f32_16x16x32_bf16 v[122:125], v[152:155], v[176:179], v[122:125]
	v_mfma_f32_16x16x32_bf16 v[110:113], v[144:147], v[184:187], v[110:113]
	v_mfma_f32_16x16x32_bf16 v[106:109], v[152:155], v[184:187], v[106:109]
	v_mfma_f32_16x16x32_bf16 v[92:95], v[144:147], v[192:195], v[92:95]
	v_mfma_f32_16x16x32_bf16 v[88:91], v[152:155], v[192:195], v[88:91]
	v_mfma_f32_16x16x32_bf16 v[76:79], v[144:147], v[200:203], v[76:79]
	v_mfma_f32_16x16x32_bf16 v[72:75], v[152:155], v[200:203], v[72:75]
	v_mfma_f32_16x16x32_bf16 v[118:121], v[156:159], v[172:175], v[118:121]
	v_mfma_f32_16x16x32_bf16 v[114:117], v[164:167], v[172:175], v[114:117]
	v_mfma_f32_16x16x32_bf16 v[102:105], v[156:159], v[180:183], v[102:105]
	v_mfma_f32_16x16x32_bf16 v[98:101], v[164:167], v[180:183], v[98:101]
	v_mfma_f32_16x16x32_bf16 v[84:87], v[156:159], v[188:191], v[84:87]
	v_mfma_f32_16x16x32_bf16 v[80:83], v[164:167], v[188:191], v[80:83]
	v_mfma_f32_16x16x32_bf16 v[68:71], v[156:159], v[196:199], v[68:71]
	v_mfma_f32_16x16x32_bf16 v[64:67], v[164:167], v[196:199], v[64:67]
	v_mfma_f32_16x16x32_bf16 v[118:121], v[160:163], v[176:179], v[118:121]
	v_mfma_f32_16x16x32_bf16 v[114:117], v[168:171], v[176:179], v[114:117]
	v_mfma_f32_16x16x32_bf16 v[102:105], v[160:163], v[184:187], v[102:105]
	v_mfma_f32_16x16x32_bf16 v[98:101], v[168:171], v[184:187], v[98:101]
	v_mfma_f32_16x16x32_bf16 v[84:87], v[160:163], v[192:195], v[84:87]
	v_mfma_f32_16x16x32_bf16 v[80:83], v[168:171], v[192:195], v[80:83]
	v_mfma_f32_16x16x32_bf16 v[68:71], v[160:163], v[200:203], v[68:71]
	v_mfma_f32_16x16x32_bf16 v[64:67], v[168:171], v[200:203], v[64:67]
	s_setprio 1
	s_barrier
	s_add_i32 s18, s35, s14
	s_mov_b32 m0, s18
	ds_read_b128 v[172:175], v143 offset:16384
	ds_read_b128 v[176:179], v143 offset:17408
	ds_read_b128 v[180:183], v143 offset:18432
	ds_read_b128 v[184:187], v143 offset:19456
	ds_read_b128 v[188:191], v143 offset:20480
	ds_read_b128 v[192:195], v143 offset:21504
	ds_read_b128 v[196:199], v143 offset:22528
	ds_read_b128 v[200:203], v143 offset:23552
	global_load_lds_dwordx4 v96, s[44:45]
	s_add_i32 m0, s18, 0x2000
	s_add_u32 s18, s44, 0x40000
	s_addc_u32 s19, s45, 0
	s_add_i32 s35, s49, s14
	global_load_lds_dwordx4 v134, s[44:45]
	s_mov_b32 m0, s35
	s_nop 0
	global_load_lds_dwordx4 v96, s[18:19]
	s_add_i32 m0, s35, 0x2000
	s_nop 0
	global_load_lds_dwordx4 v134, s[18:19]
	s_waitcnt vmcnt(6)
	s_waitcnt lgkmcnt(0)
	s_barrier
	s_setprio 0
	s_waitcnt lgkmcnt(0)
	v_mfma_f32_16x16x32_bf16 v[60:63], v[136:139], v[172:175], v[60:63]
	v_mfma_f32_16x16x32_bf16 v[56:59], v[148:151], v[172:175], v[56:59]
	v_mfma_f32_16x16x32_bf16 v[44:47], v[136:139], v[180:183], v[44:47]
	v_mfma_f32_16x16x32_bf16 v[40:43], v[148:151], v[180:183], v[40:43]
	v_mfma_f32_16x16x32_bf16 v[28:31], v[136:139], v[188:191], v[28:31]
	v_mfma_f32_16x16x32_bf16 v[24:27], v[148:151], v[188:191], v[24:27]
	v_mfma_f32_16x16x32_bf16 v[12:15], v[136:139], v[196:199], v[12:15]
	v_mfma_f32_16x16x32_bf16 v[8:11], v[148:151], v[196:199], v[8:11]
	v_mfma_f32_16x16x32_bf16 v[60:63], v[144:147], v[176:179], v[60:63]
	v_mfma_f32_16x16x32_bf16 v[56:59], v[152:155], v[176:179], v[56:59]
	v_mfma_f32_16x16x32_bf16 v[44:47], v[144:147], v[184:187], v[44:47]
	v_mfma_f32_16x16x32_bf16 v[40:43], v[152:155], v[184:187], v[40:43]
	v_mfma_f32_16x16x32_bf16 v[28:31], v[144:147], v[192:195], v[28:31]
	v_mfma_f32_16x16x32_bf16 v[24:27], v[152:155], v[192:195], v[24:27]
	v_mfma_f32_16x16x32_bf16 v[12:15], v[144:147], v[200:203], v[12:15]
	v_mfma_f32_16x16x32_bf16 v[8:11], v[152:155], v[200:203], v[8:11]
	v_mfma_f32_16x16x32_bf16 v[52:55], v[156:159], v[172:175], v[52:55]
	v_mfma_f32_16x16x32_bf16 v[48:51], v[164:167], v[172:175], v[48:51]
	v_mfma_f32_16x16x32_bf16 v[36:39], v[156:159], v[180:183], v[36:39]
	v_mfma_f32_16x16x32_bf16 v[32:35], v[164:167], v[180:183], v[32:35]
	v_mfma_f32_16x16x32_bf16 v[20:23], v[156:159], v[188:191], v[20:23]
	v_mfma_f32_16x16x32_bf16 v[16:19], v[164:167], v[188:191], v[16:19]
	v_mfma_f32_16x16x32_bf16 v[4:7], v[156:159], v[196:199], v[4:7]
	v_mfma_f32_16x16x32_bf16 v[0:3], v[164:167], v[196:199], v[0:3]
	v_mfma_f32_16x16x32_bf16 v[52:55], v[160:163], v[176:179], v[52:55]
	v_mfma_f32_16x16x32_bf16 v[48:51], v[168:171], v[176:179], v[48:51]
	v_mfma_f32_16x16x32_bf16 v[36:39], v[160:163], v[184:187], v[36:39]
	v_mfma_f32_16x16x32_bf16 v[32:35], v[168:171], v[184:187], v[32:35]
	v_mfma_f32_16x16x32_bf16 v[20:23], v[160:163], v[192:195], v[20:23]
	v_mfma_f32_16x16x32_bf16 v[16:19], v[168:171], v[192:195], v[16:19]
	v_mfma_f32_16x16x32_bf16 v[4:7], v[160:163], v[200:203], v[4:7]
	v_mfma_f32_16x16x32_bf16 v[0:3], v[168:171], v[200:203], v[0:3]
	s_setprio 1
	s_barrier
	s_add_i32 s35, 0, 0x18000
	v_add_u32_e32 v140, s35, v142
	s_add_i32 s44, 0, 0x1c000
	ds_read_b128 v[136:139], v140
	ds_read_b128 v[144:147], v140 offset:1024
	ds_read_b128 v[148:151], v140 offset:2048
	ds_read_b128 v[152:155], v140 offset:3072
	v_add_u32_e32 v140, s44, v142
	ds_read_b128 v[156:159], v140
	ds_read_b128 v[160:163], v140 offset:1024
	ds_read_b128 v[164:167], v140 offset:2048
	ds_read_b128 v[168:171], v140 offset:3072
	s_mov_b32 m0, s67
	s_nop 0
	global_load_lds_dwordx4 v130, s[42:43]
	s_mov_b32 m0, s73
	s_nop 0
	global_load_lds_dwordx4 v132, s[42:43]
	s_add_u32 s18, s42, 0x40000
	s_addc_u32 s19, s43, 0
	s_mov_b32 m0, s76
	ds_read_b128 v[172:175], v143 offset:32768
	ds_read_b128 v[176:179], v143 offset:33792
	ds_read_b128 v[180:183], v143 offset:34816
	ds_read_b128 v[184:187], v143 offset:35840
	ds_read_b128 v[188:191], v143 offset:36864
	ds_read_b128 v[192:195], v143 offset:37888
	ds_read_b128 v[196:199], v143 offset:38912
	ds_read_b128 v[200:203], v143 offset:39936
	global_load_lds_dwordx4 v130, s[18:19]
	s_mov_b32 m0, s77
	s_nop 0
	global_load_lds_dwordx4 v132, s[18:19]
	s_waitcnt vmcnt(8)
	s_waitcnt lgkmcnt(0)
	s_barrier
	s_setprio 0
	s_waitcnt lgkmcnt(0)
	v_mfma_f32_16x16x32_bf16 v[126:129], v[136:139], v[172:175], v[126:129]
	v_mfma_f32_16x16x32_bf16 v[122:125], v[148:151], v[172:175], v[122:125]
	v_mfma_f32_16x16x32_bf16 v[110:113], v[136:139], v[180:183], v[110:113]
	v_mfma_f32_16x16x32_bf16 v[106:109], v[148:151], v[180:183], v[106:109]
	v_mfma_f32_16x16x32_bf16 v[92:95], v[136:139], v[188:191], v[92:95]
	v_mfma_f32_16x16x32_bf16 v[88:91], v[148:151], v[188:191], v[88:91]
	v_mfma_f32_16x16x32_bf16 v[76:79], v[136:139], v[196:199], v[76:79]
	v_mfma_f32_16x16x32_bf16 v[72:75], v[148:151], v[196:199], v[72:75]
	v_mfma_f32_16x16x32_bf16 v[126:129], v[144:147], v[176:179], v[126:129]
	v_mfma_f32_16x16x32_bf16 v[122:125], v[152:155], v[176:179], v[122:125]
	v_mfma_f32_16x16x32_bf16 v[110:113], v[144:147], v[184:187], v[110:113]
	v_mfma_f32_16x16x32_bf16 v[106:109], v[152:155], v[184:187], v[106:109]
	v_mfma_f32_16x16x32_bf16 v[92:95], v[144:147], v[192:195], v[92:95]
	v_mfma_f32_16x16x32_bf16 v[88:91], v[152:155], v[192:195], v[88:91]
	v_mfma_f32_16x16x32_bf16 v[76:79], v[144:147], v[200:203], v[76:79]
	v_mfma_f32_16x16x32_bf16 v[72:75], v[152:155], v[200:203], v[72:75]
	v_mfma_f32_16x16x32_bf16 v[118:121], v[156:159], v[172:175], v[118:121]
	v_mfma_f32_16x16x32_bf16 v[114:117], v[164:167], v[172:175], v[114:117]
	v_mfma_f32_16x16x32_bf16 v[102:105], v[156:159], v[180:183], v[102:105]
	v_mfma_f32_16x16x32_bf16 v[98:101], v[164:167], v[180:183], v[98:101]
	v_mfma_f32_16x16x32_bf16 v[84:87], v[156:159], v[188:191], v[84:87]
	v_mfma_f32_16x16x32_bf16 v[80:83], v[164:167], v[188:191], v[80:83]
	v_mfma_f32_16x16x32_bf16 v[68:71], v[156:159], v[196:199], v[68:71]
	v_mfma_f32_16x16x32_bf16 v[64:67], v[164:167], v[196:199], v[64:67]
	v_mfma_f32_16x16x32_bf16 v[118:121], v[160:163], v[176:179], v[118:121]
	v_mfma_f32_16x16x32_bf16 v[114:117], v[168:171], v[176:179], v[114:117]
	v_mfma_f32_16x16x32_bf16 v[102:105], v[160:163], v[184:187], v[102:105]
	v_mfma_f32_16x16x32_bf16 v[98:101], v[168:171], v[184:187], v[98:101]
	v_mfma_f32_16x16x32_bf16 v[84:87], v[160:163], v[192:195], v[84:87]
	v_mfma_f32_16x16x32_bf16 v[80:83], v[168:171], v[192:195], v[80:83]
	v_mfma_f32_16x16x32_bf16 v[68:71], v[160:163], v[200:203], v[68:71]
	v_mfma_f32_16x16x32_bf16 v[64:67], v[168:171], v[200:203], v[64:67]
	s_setprio 1
	s_barrier
	s_add_i32 s18, s35, s14
	s_mov_b32 m0, s18
	ds_read_b128 v[172:175], v143 offset:49152
	ds_read_b128 v[176:179], v143 offset:50176
	ds_read_b128 v[180:183], v143 offset:51200
	ds_read_b128 v[184:187], v143 offset:52224
	ds_read_b128 v[188:191], v143 offset:53248
	ds_read_b128 v[192:195], v143 offset:54272
	ds_read_b128 v[196:199], v143 offset:55296
	ds_read_b128 v[200:203], v143 offset:56320
	global_load_lds_dwordx4 v96, s[74:75]
	s_add_i32 m0, s18, 0x2000
	s_add_u32 s18, s74, 0x40000
	s_addc_u32 s19, s75, 0
	s_add_i32 s35, s44, s14
	global_load_lds_dwordx4 v134, s[74:75]
	s_mov_b32 m0, s35
	s_nop 0
	global_load_lds_dwordx4 v96, s[18:19]
	s_add_i32 m0, s35, 0x2000
	s_nop 0
	global_load_lds_dwordx4 v134, s[18:19]
	s_waitcnt vmcnt(6)
	s_waitcnt lgkmcnt(0)
	s_barrier
	s_setprio 0
	s_waitcnt lgkmcnt(0)
	v_mfma_f32_16x16x32_bf16 v[60:63], v[136:139], v[172:175], v[60:63]
	v_mfma_f32_16x16x32_bf16 v[56:59], v[148:151], v[172:175], v[56:59]
	v_mfma_f32_16x16x32_bf16 v[44:47], v[136:139], v[180:183], v[44:47]
	v_mfma_f32_16x16x32_bf16 v[40:43], v[148:151], v[180:183], v[40:43]
	v_mfma_f32_16x16x32_bf16 v[28:31], v[136:139], v[188:191], v[28:31]
	v_mfma_f32_16x16x32_bf16 v[24:27], v[148:151], v[188:191], v[24:27]
	v_mfma_f32_16x16x32_bf16 v[12:15], v[136:139], v[196:199], v[12:15]
	v_mfma_f32_16x16x32_bf16 v[8:11], v[148:151], v[196:199], v[8:11]
	v_mfma_f32_16x16x32_bf16 v[60:63], v[144:147], v[176:179], v[60:63]
	v_mfma_f32_16x16x32_bf16 v[56:59], v[152:155], v[176:179], v[56:59]
	v_mfma_f32_16x16x32_bf16 v[44:47], v[144:147], v[184:187], v[44:47]
	v_mfma_f32_16x16x32_bf16 v[40:43], v[152:155], v[184:187], v[40:43]
	v_mfma_f32_16x16x32_bf16 v[28:31], v[144:147], v[192:195], v[28:31]
	v_mfma_f32_16x16x32_bf16 v[24:27], v[152:155], v[192:195], v[24:27]
	v_mfma_f32_16x16x32_bf16 v[12:15], v[144:147], v[200:203], v[12:15]
	v_mfma_f32_16x16x32_bf16 v[8:11], v[152:155], v[200:203], v[8:11]
	v_mfma_f32_16x16x32_bf16 v[52:55], v[156:159], v[172:175], v[52:55]
	v_mfma_f32_16x16x32_bf16 v[48:51], v[164:167], v[172:175], v[48:51]
	v_mfma_f32_16x16x32_bf16 v[36:39], v[156:159], v[180:183], v[36:39]
	v_mfma_f32_16x16x32_bf16 v[32:35], v[164:167], v[180:183], v[32:35]
	v_mfma_f32_16x16x32_bf16 v[20:23], v[156:159], v[188:191], v[20:23]
	v_mfma_f32_16x16x32_bf16 v[16:19], v[164:167], v[188:191], v[16:19]
	v_mfma_f32_16x16x32_bf16 v[4:7], v[156:159], v[196:199], v[4:7]
	v_mfma_f32_16x16x32_bf16 v[0:3], v[164:167], v[196:199], v[0:3]
	v_mfma_f32_16x16x32_bf16 v[52:55], v[160:163], v[176:179], v[52:55]
	v_mfma_f32_16x16x32_bf16 v[48:51], v[168:171], v[176:179], v[48:51]
	v_mfma_f32_16x16x32_bf16 v[36:39], v[160:163], v[184:187], v[36:39]
	v_mfma_f32_16x16x32_bf16 v[32:35], v[168:171], v[184:187], v[32:35]
	v_mfma_f32_16x16x32_bf16 v[20:23], v[160:163], v[192:195], v[20:23]
	v_mfma_f32_16x16x32_bf16 v[16:19], v[168:171], v[192:195], v[16:19]
	v_mfma_f32_16x16x32_bf16 v[4:7], v[160:163], v[200:203], v[4:7]
	v_mfma_f32_16x16x32_bf16 v[0:3], v[168:171], v[200:203], v[0:3]
	s_setprio 1
	s_barrier
	s_add_i32 s89, s89, 2
	s_add_u32 s65, s65, 0x100
	s_addc_u32 s86, s86, 0
	s_add_u32 s87, s87, 0x100
	s_addc_u32 s88, s88, 0
	s_add_u32 s68, s68, 0x100
	s_addc_u32 s69, s69, 0
	s_cmp_gt_u32 s89, 13
	s_cbranch_scc0 .LBB0_122
	s_and_b64 vcc, exec, s[28:29]
	s_cbranch_vccz .LBB0_125
	s_barrier

.LBB0_195:
	s_cmp_eq_u32 s72, s76
	s_cselect_b64 s[18:19], -1, 0
	s_add_i32 s76, s76, 2
	s_and_b64 s[42:43], s[18:19], exec
	s_cselect_b32 s44, s38, s73
	s_cselect_b32 s45, s39, s75
	s_cselect_b32 s47, s61, vcc_hi
	s_cselect_b32 s46, s60, vcc_lo
	s_add_u32 s58, s44, 0x80
	s_addc_u32 s59, s45, 0
	s_add_u32 s42, s46, 0x80
	s_addc_u32 s43, s47, 0
	s_add_i32 s35, 0, 0x10000
	s_and_b64 s[30:31], s[18:19], exec
	s_mov_b64 s[68:69], s[78:79]
	v_add_u32_e32 v144, s35, v170
	s_cselect_b32 s49, s29, s14
	s_add_i32 s70, 0, 0x14000
	ds_read_b128 v[132:135], v144
	ds_read_b128 v[136:139], v144 offset:1024
	ds_read_b128 v[140:143], v144 offset:2048
	ds_read_b128 v[150:153], v144 offset:3072
	v_add_u32_e32 v144, s70, v170
	ds_read_b128 v[154:157], v144
	ds_read_b128 v[158:161], v144 offset:1024
	ds_read_b128 v[162:165], v144 offset:2048
	ds_read_b128 v[172:175], v144 offset:3072
	s_and_b64 s[18:19], s[18:19], exec
	s_cselect_b32 s18, 0, s67
	s_cselect_b32 s19, s20, s66
	s_add_u32 s30, s68, s66
	s_addc_u32 s31, s69, s67
	s_add_i32 m0, s63, 0xc000
	ds_read_b128 v[176:179], v171
	ds_read_b128 v[180:183], v171 offset:1024
	ds_read_b128 v[184:187], v171 offset:2048
	ds_read_b128 v[188:191], v171 offset:3072
	ds_read_b128 v[192:195], v171 offset:4096
	ds_read_b128 v[196:199], v171 offset:5120
	ds_read_b128 v[200:203], v171 offset:6144
	ds_read_b128 v[204:207], v171 offset:7168
	global_load_lds_dwordx4 v96, s[30:31]
	s_add_i32 m0, s63, 0xe000
	s_nop 0
	global_load_lds_dwordx4 v130, s[30:31]
	s_waitcnt vmcnt(8)
	s_waitcnt lgkmcnt(0)
	s_barrier
	s_setprio 0
	s_waitcnt lgkmcnt(0)
	v_mfma_f32_16x16x32_bf16 v[126:129], v[132:135], v[176:179], v[126:129]
	v_mfma_f32_16x16x32_bf16 v[122:125], v[140:143], v[176:179], v[122:125]
	v_mfma_f32_16x16x32_bf16 v[110:113], v[132:135], v[184:187], v[110:113]
	v_mfma_f32_16x16x32_bf16 v[106:109], v[140:143], v[184:187], v[106:109]
	v_mfma_f32_16x16x32_bf16 v[92:95], v[132:135], v[192:195], v[92:95]
	v_mfma_f32_16x16x32_bf16 v[88:91], v[140:143], v[192:195], v[88:91]
	v_mfma_f32_16x16x32_bf16 v[76:79], v[132:135], v[200:203], v[76:79]
	v_mfma_f32_16x16x32_bf16 v[72:75], v[140:143], v[200:203], v[72:75]
	v_mfma_f32_16x16x32_bf16 v[126:129], v[136:139], v[180:183], v[126:129]
	v_mfma_f32_16x16x32_bf16 v[122:125], v[150:153], v[180:183], v[122:125]
	v_mfma_f32_16x16x32_bf16 v[110:113], v[136:139], v[188:191], v[110:113]
	v_mfma_f32_16x16x32_bf16 v[106:109], v[150:153], v[188:191], v[106:109]
	v_mfma_f32_16x16x32_bf16 v[92:95], v[136:139], v[196:199], v[92:95]
	v_mfma_f32_16x16x32_bf16 v[88:91], v[150:153], v[196:199], v[88:91]
	v_mfma_f32_16x16x32_bf16 v[76:79], v[136:139], v[204:207], v[76:79]
	v_mfma_f32_16x16x32_bf16 v[72:75], v[150:153], v[204:207], v[72:75]
	v_mfma_f32_16x16x32_bf16 v[118:121], v[154:157], v[176:179], v[118:121]
	v_mfma_f32_16x16x32_bf16 v[114:117], v[162:165], v[176:179], v[114:117]
	v_mfma_f32_16x16x32_bf16 v[102:105], v[154:157], v[184:187], v[102:105]
	v_mfma_f32_16x16x32_bf16 v[98:101], v[162:165], v[184:187], v[98:101]
	v_mfma_f32_16x16x32_bf16 v[84:87], v[154:157], v[192:195], v[84:87]
	v_mfma_f32_16x16x32_bf16 v[80:83], v[162:165], v[192:195], v[80:83]
	v_mfma_f32_16x16x32_bf16 v[68:71], v[154:157], v[200:203], v[68:71]
	v_mfma_f32_16x16x32_bf16 v[64:67], v[162:165], v[200:203], v[64:67]
	v_mfma_f32_16x16x32_bf16 v[118:121], v[158:161], v[180:183], v[118:121]
	v_mfma_f32_16x16x32_bf16 v[114:117], v[172:175], v[180:183], v[114:117]
	v_mfma_f32_16x16x32_bf16 v[102:105], v[158:161], v[188:191], v[102:105]
	v_mfma_f32_16x16x32_bf16 v[98:101], v[172:175], v[188:191], v[98:101]
	v_mfma_f32_16x16x32_bf16 v[84:87], v[158:161], v[196:199], v[84:87]
	v_mfma_f32_16x16x32_bf16 v[80:83], v[172:175], v[196:199], v[80:83]
	v_mfma_f32_16x16x32_bf16 v[68:71], v[158:161], v[204:207], v[68:71]
	v_mfma_f32_16x16x32_bf16 v[64:67], v[172:175], v[204:207], v[64:67]
	s_setprio 1
	s_barrier
	s_add_i32 s35, s35, s80
	v_mad_u64_u32 v[144:145], s[30:31], v168, s49, v[146:147]
	s_mov_b32 m0, s35
	ds_read_b128 v[176:179], v171 offset:16384
	ds_read_b128 v[180:183], v171 offset:17408
	ds_read_b128 v[184:187], v171 offset:18432
	ds_read_b128 v[188:191], v171 offset:19456
	ds_read_b128 v[192:195], v171 offset:20480
	ds_read_b128 v[196:199], v171 offset:21504
	ds_read_b128 v[200:203], v171 offset:22528
	ds_read_b128 v[204:207], v171 offset:23552
	global_load_lds_dwordx4 v144, s[46:47]
	v_mad_u64_u32 v[166:167], s[30:31], v169, s49, v[148:149]
	s_add_i32 m0, s35, 0x2000
	s_add_u32 s30, s46, s19
	s_addc_u32 s31, s47, s18
	s_add_i32 s35, s70, s80
	global_load_lds_dwordx4 v166, s[46:47]
	s_mov_b32 m0, s35
	s_nop 0
	global_load_lds_dwordx4 v144, s[30:31]
	s_add_i32 m0, s35, 0x2000
	s_nop 0
	global_load_lds_dwordx4 v166, s[30:31]
	v_mad_u64_u32 v[208:209], s[30:31], s49, v147, v[146:147]
	s_mov_b32 m0, s63
	v_mad_u64_u32 v[210:211], s[30:31], s49, v149, v[148:149]
	global_load_lds_dwordx4 v208, s[44:45]
	s_mov_b32 m0, s65
	s_nop 0
	global_load_lds_dwordx4 v210, s[44:45]
	s_waitcnt vmcnt(8)
	s_waitcnt lgkmcnt(0)
	s_barrier
	s_setprio 0
	s_waitcnt lgkmcnt(0)
	v_mfma_f32_16x16x32_bf16 v[60:63], v[132:135], v[176:179], v[60:63]
	v_mfma_f32_16x16x32_bf16 v[56:59], v[140:143], v[176:179], v[56:59]
	v_mfma_f32_16x16x32_bf16 v[44:47], v[132:135], v[184:187], v[44:47]
	v_mfma_f32_16x16x32_bf16 v[40:43], v[140:143], v[184:187], v[40:43]
	v_mfma_f32_16x16x32_bf16 v[28:31], v[132:135], v[192:195], v[28:31]
	v_mfma_f32_16x16x32_bf16 v[24:27], v[140:143], v[192:195], v[24:27]
	v_mfma_f32_16x16x32_bf16 v[12:15], v[132:135], v[200:203], v[12:15]
	v_mfma_f32_16x16x32_bf16 v[8:11], v[140:143], v[200:203], v[8:11]
	v_mfma_f32_16x16x32_bf16 v[60:63], v[136:139], v[180:183], v[60:63]
	v_mfma_f32_16x16x32_bf16 v[56:59], v[150:153], v[180:183], v[56:59]
	v_mfma_f32_16x16x32_bf16 v[44:47], v[136:139], v[188:191], v[44:47]
	v_mfma_f32_16x16x32_bf16 v[40:43], v[150:153], v[188:191], v[40:43]
	v_mfma_f32_16x16x32_bf16 v[28:31], v[136:139], v[196:199], v[28:31]
	v_mfma_f32_16x16x32_bf16 v[24:27], v[150:153], v[196:199], v[24:27]
	v_mfma_f32_16x16x32_bf16 v[12:15], v[136:139], v[204:207], v[12:15]
	v_mfma_f32_16x16x32_bf16 v[8:11], v[150:153], v[204:207], v[8:11]
	v_mfma_f32_16x16x32_bf16 v[52:55], v[154:157], v[176:179], v[52:55]
	v_mfma_f32_16x16x32_bf16 v[48:51], v[162:165], v[176:179], v[48:51]
	v_mfma_f32_16x16x32_bf16 v[36:39], v[154:157], v[184:187], v[36:39]
	v_mfma_f32_16x16x32_bf16 v[32:35], v[162:165], v[184:187], v[32:35]
	v_mfma_f32_16x16x32_bf16 v[20:23], v[154:157], v[192:195], v[20:23]
	v_mfma_f32_16x16x32_bf16 v[16:19], v[162:165], v[192:195], v[16:19]
	v_mfma_f32_16x16x32_bf16 v[4:7], v[154:157], v[200:203], v[4:7]
	v_mfma_f32_16x16x32_bf16 v[0:3], v[162:165], v[200:203], v[0:3]
	v_mfma_f32_16x16x32_bf16 v[52:55], v[158:161], v[180:183], v[52:55]
	v_mfma_f32_16x16x32_bf16 v[48:51], v[172:175], v[180:183], v[48:51]
	v_mfma_f32_16x16x32_bf16 v[36:39], v[158:161], v[188:191], v[36:39]
	v_mfma_f32_16x16x32_bf16 v[32:35], v[172:175], v[188:191], v[32:35]
	v_mfma_f32_16x16x32_bf16 v[20:23], v[158:161], v[196:199], v[20:23]
	v_mfma_f32_16x16x32_bf16 v[16:19], v[172:175], v[196:199], v[16:19]
	v_mfma_f32_16x16x32_bf16 v[4:7], v[158:161], v[204:207], v[4:7]
	v_mfma_f32_16x16x32_bf16 v[0:3], v[172:175], v[204:207], v[0:3]
	s_setprio 1
	s_barrier
	s_add_i32 s35, 0, 0x18000
	v_add_u32_e32 v145, s35, v170
	s_add_i32 s46, 0, 0x1c000
	ds_read_b128 v[132:135], v145
	ds_read_b128 v[136:139], v145 offset:1024
	ds_read_b128 v[140:143], v145 offset:2048
	ds_read_b128 v[150:153], v145 offset:3072
	v_add_u32_e32 v145, s46, v170
	ds_read_b128 v[154:157], v145
	ds_read_b128 v[158:161], v145 offset:1024
	ds_read_b128 v[162:165], v145 offset:2048
	ds_read_b128 v[172:175], v145 offset:3072
	s_add_u32 s30, s44, s19
	s_addc_u32 s31, s45, s18
	s_mov_b32 m0, s81
	ds_read_b128 v[176:179], v171 offset:32768
	ds_read_b128 v[180:183], v171 offset:33792
	ds_read_b128 v[184:187], v171 offset:34816
	ds_read_b128 v[188:191], v171 offset:35840
	ds_read_b128 v[192:195], v171 offset:36864
	ds_read_b128 v[196:199], v171 offset:37888
	ds_read_b128 v[200:203], v171 offset:38912
	ds_read_b128 v[204:207], v171 offset:39936
	global_load_lds_dwordx4 v208, s[30:31]
	s_mov_b32 m0, s90
	s_nop 0
	global_load_lds_dwordx4 v210, s[30:31]
	s_waitcnt vmcnt(8)
	s_waitcnt lgkmcnt(0)
	s_barrier
	s_setprio 0
	s_waitcnt lgkmcnt(0)
	v_mfma_f32_16x16x32_bf16 v[126:129], v[132:135], v[176:179], v[126:129]
	v_mfma_f32_16x16x32_bf16 v[122:125], v[140:143], v[176:179], v[122:125]
	v_mfma_f32_16x16x32_bf16 v[110:113], v[132:135], v[184:187], v[110:113]
	v_mfma_f32_16x16x32_bf16 v[106:109], v[140:143], v[184:187], v[106:109]
	v_mfma_f32_16x16x32_bf16 v[92:95], v[132:135], v[192:195], v[92:95]
	v_mfma_f32_16x16x32_bf16 v[88:91], v[140:143], v[192:195], v[88:91]
	v_mfma_f32_16x16x32_bf16 v[76:79], v[132:135], v[200:203], v[76:79]
	v_mfma_f32_16x16x32_bf16 v[72:75], v[140:143], v[200:203], v[72:75]
	v_mfma_f32_16x16x32_bf16 v[126:129], v[136:139], v[180:183], v[126:129]
	v_mfma_f32_16x16x32_bf16 v[122:125], v[150:153], v[180:183], v[122:125]
	v_mfma_f32_16x16x32_bf16 v[110:113], v[136:139], v[188:191], v[110:113]
	v_mfma_f32_16x16x32_bf16 v[106:109], v[150:153], v[188:191], v[106:109]
	v_mfma_f32_16x16x32_bf16 v[92:95], v[136:139], v[196:199], v[92:95]
	v_mfma_f32_16x16x32_bf16 v[88:91], v[150:153], v[196:199], v[88:91]
	v_mfma_f32_16x16x32_bf16 v[76:79], v[136:139], v[204:207], v[76:79]
	v_mfma_f32_16x16x32_bf16 v[72:75], v[150:153], v[204:207], v[72:75]
	v_mfma_f32_16x16x32_bf16 v[118:121], v[154:157], v[176:179], v[118:121]
	v_mfma_f32_16x16x32_bf16 v[114:117], v[162:165], v[176:179], v[114:117]
	v_mfma_f32_16x16x32_bf16 v[102:105], v[154:157], v[184:187], v[102:105]
	v_mfma_f32_16x16x32_bf16 v[98:101], v[162:165], v[184:187], v[98:101]
	v_mfma_f32_16x16x32_bf16 v[84:87], v[154:157], v[192:195], v[84:87]
	v_mfma_f32_16x16x32_bf16 v[80:83], v[162:165], v[192:195], v[80:83]
	v_mfma_f32_16x16x32_bf16 v[68:71], v[154:157], v[200:203], v[68:71]
	v_mfma_f32_16x16x32_bf16 v[64:67], v[162:165], v[200:203], v[64:67]
	v_mfma_f32_16x16x32_bf16 v[118:121], v[158:161], v[180:183], v[118:121]
	v_mfma_f32_16x16x32_bf16 v[114:117], v[172:175], v[180:183], v[114:117]
	v_mfma_f32_16x16x32_bf16 v[102:105], v[158:161], v[188:191], v[102:105]
	v_mfma_f32_16x16x32_bf16 v[98:101], v[172:175], v[188:191], v[98:101]
	v_mfma_f32_16x16x32_bf16 v[84:87], v[158:161], v[196:199], v[84:87]
	v_mfma_f32_16x16x32_bf16 v[80:83], v[172:175], v[196:199], v[80:83]
	v_mfma_f32_16x16x32_bf16 v[68:71], v[158:161], v[204:207], v[68:71]
	v_mfma_f32_16x16x32_bf16 v[64:67], v[172:175], v[204:207], v[64:67]
	s_setprio 1
	s_barrier
	s_add_i32 s30, s35, s80
	s_mov_b32 m0, s30
	ds_read_b128 v[176:179], v171 offset:49152
	ds_read_b128 v[180:183], v171 offset:50176
	ds_read_b128 v[184:187], v171 offset:51200
	ds_read_b128 v[188:191], v171 offset:52224
	ds_read_b128 v[192:195], v171 offset:53248
	ds_read_b128 v[196:199], v171 offset:54272
	ds_read_b128 v[200:203], v171 offset:55296
	ds_read_b128 v[204:207], v171 offset:56320
	global_load_lds_dwordx4 v144, s[42:43]
	s_add_i32 m0, s30, 0x2000
	s_add_u32 s30, s42, s19
	s_addc_u32 s31, s43, s18
	s_add_i32 s18, s46, s80
	global_load_lds_dwordx4 v166, s[42:43]
	s_mov_b32 m0, s18
	s_nop 0
	global_load_lds_dwordx4 v144, s[30:31]
	s_add_i32 m0, s18, 0x2000
	s_nop 0
	global_load_lds_dwordx4 v166, s[30:31]
	s_mov_b32 m0, s82
	s_nop 0
	global_load_lds_dwordx4 v208, s[58:59]
	s_mov_b32 m0, s83
	s_nop 0
	global_load_lds_dwordx4 v210, s[58:59]
	s_waitcnt vmcnt(8)
	s_waitcnt lgkmcnt(0)
	s_barrier
	s_setprio 0
	s_waitcnt lgkmcnt(0)
	v_mfma_f32_16x16x32_bf16 v[60:63], v[132:135], v[176:179], v[60:63]
	v_mfma_f32_16x16x32_bf16 v[56:59], v[140:143], v[176:179], v[56:59]
	v_mfma_f32_16x16x32_bf16 v[44:47], v[132:135], v[184:187], v[44:47]
	v_mfma_f32_16x16x32_bf16 v[40:43], v[140:143], v[184:187], v[40:43]
	v_mfma_f32_16x16x32_bf16 v[28:31], v[132:135], v[192:195], v[28:31]
	v_mfma_f32_16x16x32_bf16 v[24:27], v[140:143], v[192:195], v[24:27]
	v_mfma_f32_16x16x32_bf16 v[12:15], v[132:135], v[200:203], v[12:15]
	v_mfma_f32_16x16x32_bf16 v[8:11], v[140:143], v[200:203], v[8:11]
	v_mfma_f32_16x16x32_bf16 v[60:63], v[136:139], v[180:183], v[60:63]
	v_mfma_f32_16x16x32_bf16 v[56:59], v[150:153], v[180:183], v[56:59]
	v_mfma_f32_16x16x32_bf16 v[44:47], v[136:139], v[188:191], v[44:47]
	v_mfma_f32_16x16x32_bf16 v[40:43], v[150:153], v[188:191], v[40:43]
	v_mfma_f32_16x16x32_bf16 v[28:31], v[136:139], v[196:199], v[28:31]
	v_mfma_f32_16x16x32_bf16 v[24:27], v[150:153], v[196:199], v[24:27]
	v_mfma_f32_16x16x32_bf16 v[12:15], v[136:139], v[204:207], v[12:15]
	v_mfma_f32_16x16x32_bf16 v[8:11], v[150:153], v[204:207], v[8:11]
	v_mfma_f32_16x16x32_bf16 v[52:55], v[154:157], v[176:179], v[52:55]
	v_mfma_f32_16x16x32_bf16 v[48:51], v[162:165], v[176:179], v[48:51]
	v_mfma_f32_16x16x32_bf16 v[36:39], v[154:157], v[184:187], v[36:39]
	v_mfma_f32_16x16x32_bf16 v[32:35], v[162:165], v[184:187], v[32:35]
	v_mfma_f32_16x16x32_bf16 v[20:23], v[154:157], v[192:195], v[20:23]
	v_mfma_f32_16x16x32_bf16 v[16:19], v[162:165], v[192:195], v[16:19]
	v_mfma_f32_16x16x32_bf16 v[4:7], v[154:157], v[200:203], v[4:7]
	v_mfma_f32_16x16x32_bf16 v[0:3], v[162:165], v[200:203], v[0:3]
	v_mfma_f32_16x16x32_bf16 v[52:55], v[158:161], v[180:183], v[52:55]
	v_mfma_f32_16x16x32_bf16 v[48:51], v[172:175], v[180:183], v[48:51]
	v_mfma_f32_16x16x32_bf16 v[36:39], v[158:161], v[188:191], v[36:39]
	v_mfma_f32_16x16x32_bf16 v[32:35], v[172:175], v[188:191], v[32:35]
	v_mfma_f32_16x16x32_bf16 v[20:23], v[158:161], v[196:199], v[20:23]
	v_mfma_f32_16x16x32_bf16 v[16:19], v[172:175], v[196:199], v[16:19]
	v_mfma_f32_16x16x32_bf16 v[4:7], v[158:161], v[204:207], v[4:7]
	v_mfma_f32_16x16x32_bf16 v[0:3], v[172:175], v[204:207], v[0:3]
	s_setprio 1
	s_barrier
	s_add_u32 s73, s73, 0x100
	s_addc_u32 s75, s75, 0
	s_add_u32 vcc_lo, vcc_lo, 0x100
	s_addc_u32 vcc_hi, vcc_hi, 0
	s_add_u32 s78, s78, 0x100
	s_addc_u32 s79, s79, 0
	s_cmp_ge_u32 s76, s16
	s_cbranch_scc0 .LBB0_195
	s_and_b64 vcc, exec, s[96:97]
	s_cbranch_vccz .LBB0_198
	s_barrier

.LBB0_383:
	s_add_u32 s18, s78, 0x80
	s_addc_u32 s19, s79, 0
	s_add_u32 s42, s78, 0x100
	s_addc_u32 s43, s79, 0
	s_add_u32 s44, s76, 0x100
	s_addc_u32 s45, s77, 0
	s_add_u32 s80, s78, 0x180
	s_addc_u32 s81, s79, 0
	s_add_u32 s84, s76, 0x180
	s_addc_u32 s85, s77, 0
	s_add_i32 vcc_hi, 0, 0x10000
	s_add_i32 s22, 0, 0x14000
	s_mov_b64 s[82:83], s[80:81]
	v_add_u32_e32 v0, vcc_hi, v155
	v_add_u32_e32 v1, s22, v155
	ds_read_b128 v[2:5], v0
	ds_read_b128 v[6:9], v0 offset:1024
	ds_read_b128 v[10:13], v0 offset:2048
	ds_read_b128 v[14:17], v0 offset:3072
	ds_read_b128 v[18:21], v1
	ds_read_b128 v[22:25], v1 offset:1024
	ds_read_b128 v[26:29], v1 offset:2048
	ds_read_b128 v[30:33], v1 offset:3072
	s_add_u32 s18, s18, 0x18000
	s_addc_u32 s19, s19, 0
	s_add_i32 s88, s49, 0xc000
	s_mov_b32 m0, s88
	s_add_i32 vcc_lo, s49, 0xe000
	ds_read_b128 v[34:37], v157
	ds_read_b128 v[38:41], v157 offset:1024
	ds_read_b128 v[42:45], v157 offset:2048
	ds_read_b128 v[46:49], v157 offset:3072
	ds_read_b128 v[50:53], v157 offset:4096
	ds_read_b128 v[54:57], v157 offset:5120
	ds_read_b128 v[58:61], v157 offset:6144
	ds_read_b128 v[62:65], v157 offset:7168
	global_load_lds_dwordx4 v136, s[18:19]
	s_mov_b32 m0, vcc_lo
	s_nop 0
	global_load_lds_dwordx4 v132, s[18:19]
	s_waitcnt vmcnt(8)
	s_waitcnt lgkmcnt(0)
	s_barrier
	s_setprio 0
	s_waitcnt lgkmcnt(0)
	v_mfma_f32_16x16x32_bf16 v[66:69], v[2:5], v[34:37], 0
	v_mfma_f32_16x16x32_bf16 v[70:73], v[10:13], v[34:37], 0
	v_mfma_f32_16x16x32_bf16 v[74:77], v[2:5], v[42:45], 0
	v_mfma_f32_16x16x32_bf16 v[78:81], v[10:13], v[42:45], 0
	v_mfma_f32_16x16x32_bf16 v[82:85], v[2:5], v[50:53], 0
	v_mfma_f32_16x16x32_bf16 v[86:89], v[10:13], v[50:53], 0
	v_mfma_f32_16x16x32_bf16 v[90:93], v[2:5], v[58:61], 0
	v_mfma_f32_16x16x32_bf16 v[98:101], v[10:13], v[58:61], 0
	v_mfma_f32_16x16x32_bf16 v[66:69], v[6:9], v[38:41], v[66:69]
	v_mfma_f32_16x16x32_bf16 v[70:73], v[14:17], v[38:41], v[70:73]
	v_mfma_f32_16x16x32_bf16 v[74:77], v[6:9], v[46:49], v[74:77]
	v_mfma_f32_16x16x32_bf16 v[78:81], v[14:17], v[46:49], v[78:81]
	v_mfma_f32_16x16x32_bf16 v[82:85], v[6:9], v[54:57], v[82:85]
	v_mfma_f32_16x16x32_bf16 v[86:89], v[14:17], v[54:57], v[86:89]
	v_mfma_f32_16x16x32_bf16 v[90:93], v[6:9], v[62:65], v[90:93]
	v_mfma_f32_16x16x32_bf16 v[98:101], v[14:17], v[62:65], v[98:101]
	v_mfma_f32_16x16x32_bf16 v[102:105], v[18:21], v[34:37], 0
	v_mfma_f32_16x16x32_bf16 v[34:37], v[26:29], v[34:37], 0
	v_mfma_f32_16x16x32_bf16 v[102:105], v[22:25], v[38:41], v[102:105]
	v_mfma_f32_16x16x32_bf16 v[34:37], v[30:33], v[38:41], v[34:37]
	v_mfma_f32_16x16x32_bf16 v[38:41], v[18:21], v[42:45], 0
	v_mfma_f32_16x16x32_bf16 v[42:45], v[26:29], v[42:45], 0
	v_mfma_f32_16x16x32_bf16 v[38:41], v[22:25], v[46:49], v[38:41]
	v_mfma_f32_16x16x32_bf16 v[42:45], v[30:33], v[46:49], v[42:45]
	v_mfma_f32_16x16x32_bf16 v[46:49], v[18:21], v[50:53], 0
	v_mfma_f32_16x16x32_bf16 v[50:53], v[26:29], v[50:53], 0
	v_mfma_f32_16x16x32_bf16 v[46:49], v[22:25], v[54:57], v[46:49]
	v_mfma_f32_16x16x32_bf16 v[50:53], v[30:33], v[54:57], v[50:53]
	v_mfma_f32_16x16x32_bf16 v[54:57], v[18:21], v[58:61], 0
	v_mfma_f32_16x16x32_bf16 v[58:61], v[26:29], v[58:61], 0
	v_mfma_f32_16x16x32_bf16 v[54:57], v[22:25], v[62:65], v[54:57]
	v_mfma_f32_16x16x32_bf16 v[58:61], v[30:33], v[62:65], v[58:61]
	s_setprio 1
	s_barrier
	s_add_i32 vcc_hi, vcc_hi, s75
	s_add_i32 s70, vcc_hi, 0x2000
	s_mov_b32 m0, vcc_hi
	s_add_u32 s18, s44, 0x18000
	ds_read_b128 v[62:65], v157 offset:16384
	ds_read_b128 v[106:109], v157 offset:17408
	ds_read_b128 v[110:113], v157 offset:18432
	ds_read_b128 v[114:117], v157 offset:19456
	ds_read_b128 v[118:121], v157 offset:20480
	ds_read_b128 v[122:125], v157 offset:21504
	ds_read_b128 v[126:129], v157 offset:22528
	ds_read_b128 v[138:141], v157 offset:23552
	global_load_lds_dwordx4 v134, s[44:45]
	s_mov_b32 m0, s70
	s_addc_u32 s19, s45, 0
	s_add_i32 s22, s22, s75
	global_load_lds_dwordx4 v130, s[44:45]
	s_mov_b32 m0, s22
	s_add_i32 s23, s22, 0x2000
	global_load_lds_dwordx4 v134, s[18:19]
	s_mov_b32 m0, s23
	s_nop 0
	global_load_lds_dwordx4 v130, s[18:19]
	s_mov_b32 m0, s49
	s_nop 0
	global_load_lds_dwordx4 v136, s[42:43]
	s_mov_b32 m0, s89
	s_nop 0
	global_load_lds_dwordx4 v132, s[42:43]
	s_waitcnt vmcnt(8)
	s_waitcnt lgkmcnt(0)
	s_barrier
	s_setprio 0
	s_waitcnt lgkmcnt(0)
	v_mfma_f32_16x16x32_bf16 v[142:145], v[2:5], v[62:65], 0
	v_mfma_f32_16x16x32_bf16 v[150:153], v[2:5], v[110:113], 0
	v_mfma_f32_16x16x32_bf16 v[162:165], v[2:5], v[118:121], 0
	v_mfma_f32_16x16x32_bf16 v[2:5], v[2:5], v[126:129], 0
	v_mfma_f32_16x16x32_bf16 v[142:145], v[6:9], v[106:109], v[142:145]
	v_mfma_f32_16x16x32_bf16 v[146:149], v[10:13], v[62:65], 0
	v_mfma_f32_16x16x32_bf16 v[150:153], v[6:9], v[114:117], v[150:153]
	v_mfma_f32_16x16x32_bf16 v[158:161], v[10:13], v[110:113], 0
	v_mfma_f32_16x16x32_bf16 v[162:165], v[6:9], v[122:125], v[162:165]
	v_mfma_f32_16x16x32_bf16 v[166:169], v[10:13], v[118:121], 0
	v_mfma_f32_16x16x32_bf16 v[4:7], v[6:9], v[138:141], v[2:5]
	v_mfma_f32_16x16x32_bf16 v[8:11], v[10:13], v[126:129], 0
	v_mfma_f32_16x16x32_bf16 v[8:11], v[14:17], v[138:141], v[8:11]
	v_mfma_f32_16x16x32_bf16 v[146:149], v[14:17], v[106:109], v[146:149]
	v_mfma_f32_16x16x32_bf16 v[158:161], v[14:17], v[114:117], v[158:161]
	v_mfma_f32_16x16x32_bf16 v[166:169], v[14:17], v[122:125], v[166:169]
	v_mfma_f32_16x16x32_bf16 v[12:15], v[18:21], v[62:65], 0
	v_mfma_f32_16x16x32_bf16 v[62:65], v[26:29], v[62:65], 0
	v_mfma_f32_16x16x32_bf16 v[12:15], v[22:25], v[106:109], v[12:15]
	v_mfma_f32_16x16x32_bf16 v[62:65], v[30:33], v[106:109], v[62:65]
	v_mfma_f32_16x16x32_bf16 v[106:109], v[18:21], v[110:113], 0
	v_mfma_f32_16x16x32_bf16 v[110:113], v[26:29], v[110:113], 0
	v_mfma_f32_16x16x32_bf16 v[106:109], v[22:25], v[114:117], v[106:109]
	v_mfma_f32_16x16x32_bf16 v[110:113], v[30:33], v[114:117], v[110:113]
	v_mfma_f32_16x16x32_bf16 v[114:117], v[18:21], v[118:121], 0
	v_mfma_f32_16x16x32_bf16 v[16:19], v[18:21], v[126:129], 0
	v_mfma_f32_16x16x32_bf16 v[114:117], v[22:25], v[122:125], v[114:117]
	v_mfma_f32_16x16x32_bf16 v[118:121], v[26:29], v[118:121], 0
	v_mfma_f32_16x16x32_bf16 v[16:19], v[22:25], v[138:141], v[16:19]
	v_mfma_f32_16x16x32_bf16 v[20:23], v[26:29], v[126:129], 0
	v_mfma_f32_16x16x32_bf16 v[118:121], v[30:33], v[122:125], v[118:121]
	v_mfma_f32_16x16x32_bf16 v[20:23], v[30:33], v[138:141], v[20:23]
	s_setprio 1
	s_barrier
	s_add_i32 s35, 0, 0x18000
	s_add_i32 s44, 0, 0x1c000
	v_add_u32_e32 v2, s35, v155
	v_add_u32_e32 v3, s44, v155
	ds_read_b128 v[24:27], v2
	ds_read_b128 v[28:31], v2 offset:1024
	ds_read_b128 v[122:125], v2 offset:2048
	ds_read_b128 v[126:129], v2 offset:3072
	ds_read_b128 v[138:141], v3
	ds_read_b128 v[170:173], v3 offset:1024
	ds_read_b128 v[174:177], v3 offset:2048
	ds_read_b128 v[178:181], v3 offset:3072
	s_add_u32 s18, s42, 0x18000
	s_addc_u32 s19, s43, 0
	s_mov_b32 m0, s90
	ds_read_b128 v[182:185], v157 offset:32768
	ds_read_b128 v[190:193], v157 offset:33792
	ds_read_b128 v[194:197], v157 offset:34816
	ds_read_b128 v[198:201], v157 offset:35840
	ds_read_b128 v[202:205], v157 offset:36864
	ds_read_b128 v[206:209], v157 offset:37888
	ds_read_b128 v[210:213], v157 offset:38912
	ds_read_b128 v[220:223], v157 offset:39936
	global_load_lds_dwordx4 v136, s[18:19]
	s_mov_b32 m0, s91
	s_nop 0
	global_load_lds_dwordx4 v132, s[18:19]
	s_waitcnt vmcnt(8)
	s_waitcnt lgkmcnt(0)
	s_barrier
	s_setprio 0
	s_waitcnt lgkmcnt(0)
	v_mfma_f32_16x16x32_bf16 v[66:69], v[24:27], v[182:185], v[66:69]
	v_mfma_f32_16x16x32_bf16 v[70:73], v[122:125], v[182:185], v[70:73]
	v_mfma_f32_16x16x32_bf16 v[74:77], v[24:27], v[194:197], v[74:77]
	v_mfma_f32_16x16x32_bf16 v[78:81], v[122:125], v[194:197], v[78:81]
	v_mfma_f32_16x16x32_bf16 v[82:85], v[24:27], v[202:205], v[82:85]
	v_mfma_f32_16x16x32_bf16 v[86:89], v[122:125], v[202:205], v[86:89]
	v_mfma_f32_16x16x32_bf16 v[90:93], v[24:27], v[210:213], v[90:93]
	v_mfma_f32_16x16x32_bf16 v[98:101], v[122:125], v[210:213], v[98:101]
	v_mfma_f32_16x16x32_bf16 v[66:69], v[28:31], v[190:193], v[66:69]
	v_mfma_f32_16x16x32_bf16 v[70:73], v[126:129], v[190:193], v[70:73]
	v_mfma_f32_16x16x32_bf16 v[74:77], v[28:31], v[198:201], v[74:77]
	v_mfma_f32_16x16x32_bf16 v[78:81], v[126:129], v[198:201], v[78:81]
	v_mfma_f32_16x16x32_bf16 v[82:85], v[28:31], v[206:209], v[82:85]
	v_mfma_f32_16x16x32_bf16 v[86:89], v[126:129], v[206:209], v[86:89]
	v_mfma_f32_16x16x32_bf16 v[90:93], v[28:31], v[220:223], v[90:93]
	v_mfma_f32_16x16x32_bf16 v[98:101], v[126:129], v[220:223], v[98:101]
	v_mfma_f32_16x16x32_bf16 v[102:105], v[138:141], v[182:185], v[102:105]
	v_mfma_f32_16x16x32_bf16 v[32:35], v[174:177], v[182:185], v[34:37]
	v_mfma_f32_16x16x32_bf16 v[36:39], v[138:141], v[194:197], v[38:41]
	v_mfma_f32_16x16x32_bf16 v[40:43], v[174:177], v[194:197], v[42:45]
	v_mfma_f32_16x16x32_bf16 v[44:47], v[138:141], v[202:205], v[46:49]
	v_mfma_f32_16x16x32_bf16 v[48:51], v[174:177], v[202:205], v[50:53]
	v_mfma_f32_16x16x32_bf16 v[52:55], v[138:141], v[210:213], v[54:57]
	v_mfma_f32_16x16x32_bf16 v[56:59], v[174:177], v[210:213], v[58:61]
	v_mfma_f32_16x16x32_bf16 v[102:105], v[170:173], v[190:193], v[102:105]
	v_mfma_f32_16x16x32_bf16 v[32:35], v[178:181], v[190:193], v[32:35]
	v_mfma_f32_16x16x32_bf16 v[36:39], v[170:173], v[198:201], v[36:39]
	v_mfma_f32_16x16x32_bf16 v[40:43], v[178:181], v[198:201], v[40:43]
	v_mfma_f32_16x16x32_bf16 v[44:47], v[170:173], v[206:209], v[44:47]
	v_mfma_f32_16x16x32_bf16 v[52:55], v[170:173], v[220:223], v[52:55]
	v_mfma_f32_16x16x32_bf16 v[56:59], v[178:181], v[220:223], v[56:59]
	v_mfma_f32_16x16x32_bf16 v[48:51], v[178:181], v[206:209], v[48:51]
	s_setprio 1
	s_barrier
	s_add_i32 s18, s35, s75
	s_add_i32 s35, s18, 0x2000
	s_mov_b32 m0, s18
	s_add_u32 s42, s84, 0x18000
	ds_read_b128 v[182:185], v157 offset:49152
	ds_read_b128 v[190:193], v157 offset:50176
	ds_read_b128 v[194:197], v157 offset:51200
	ds_read_b128 v[198:201], v157 offset:52224
	ds_read_b128 v[202:205], v157 offset:53248
	ds_read_b128 v[206:209], v157 offset:54272
	ds_read_b128 v[210:213], v157 offset:55296
	ds_read_b128 v[220:223], v157 offset:56320
	global_load_lds_dwordx4 v134, s[84:85]
	s_mov_b32 m0, s35
	s_addc_u32 s43, s85, 0
	s_add_i32 s19, s44, s75
	global_load_lds_dwordx4 v130, s[84:85]
	s_mov_b32 m0, s19
	s_add_i32 s84, s19, 0x2000
	global_load_lds_dwordx4 v134, s[42:43]
	s_mov_b32 m0, s84
	s_nop 0
	global_load_lds_dwordx4 v130, s[42:43]
	s_mov_b32 m0, s93
	s_nop 0
	global_load_lds_dwordx4 v136, s[82:83]
	s_mov_b32 m0, s94
	s_nop 0
	global_load_lds_dwordx4 v132, s[82:83]
	s_waitcnt vmcnt(8)
	s_waitcnt lgkmcnt(0)
	s_barrier
	s_setprio 0
	s_waitcnt lgkmcnt(0)
	v_mfma_f32_16x16x32_bf16 v[4:7], v[24:27], v[210:213], v[4:7]
	v_mfma_f32_16x16x32_bf16 v[8:11], v[122:125], v[210:213], v[8:11]
	v_mfma_f32_16x16x32_bf16 v[142:145], v[24:27], v[182:185], v[142:145]
	v_mfma_f32_16x16x32_bf16 v[146:149], v[122:125], v[182:185], v[146:149]
	v_mfma_f32_16x16x32_bf16 v[150:153], v[24:27], v[194:197], v[150:153]
	v_mfma_f32_16x16x32_bf16 v[158:161], v[122:125], v[194:197], v[158:161]
	v_mfma_f32_16x16x32_bf16 v[162:165], v[24:27], v[202:205], v[162:165]
	v_mfma_f32_16x16x32_bf16 v[166:169], v[122:125], v[202:205], v[166:169]
	v_mfma_f32_16x16x32_bf16 v[4:7], v[28:31], v[220:223], v[4:7]
	v_mfma_f32_16x16x32_bf16 v[8:11], v[126:129], v[220:223], v[8:11]
	v_mfma_f32_16x16x32_bf16 v[142:145], v[28:31], v[190:193], v[142:145]
	v_mfma_f32_16x16x32_bf16 v[146:149], v[126:129], v[190:193], v[146:149]
	v_mfma_f32_16x16x32_bf16 v[150:153], v[28:31], v[198:201], v[150:153]
	v_mfma_f32_16x16x32_bf16 v[158:161], v[126:129], v[198:201], v[158:161]
	v_mfma_f32_16x16x32_bf16 v[162:165], v[28:31], v[206:209], v[162:165]
	v_mfma_f32_16x16x32_bf16 v[166:169], v[126:129], v[206:209], v[166:169]
	v_mfma_f32_16x16x32_bf16 v[12:15], v[138:141], v[182:185], v[12:15]
	v_mfma_f32_16x16x32_bf16 v[24:27], v[174:177], v[182:185], v[62:65]
	v_mfma_f32_16x16x32_bf16 v[28:31], v[138:141], v[194:197], v[106:109]
	v_mfma_f32_16x16x32_bf16 v[60:63], v[174:177], v[194:197], v[110:113]
	v_mfma_f32_16x16x32_bf16 v[106:109], v[138:141], v[202:205], v[114:117]
	v_mfma_f32_16x16x32_bf16 v[110:113], v[174:177], v[202:205], v[118:121]
	v_mfma_f32_16x16x32_bf16 v[16:19], v[138:141], v[210:213], v[16:19]
	v_mfma_f32_16x16x32_bf16 v[20:23], v[174:177], v[210:213], v[20:23]
	v_mfma_f32_16x16x32_bf16 v[12:15], v[170:173], v[190:193], v[12:15]
	v_mfma_f32_16x16x32_bf16 v[24:27], v[178:181], v[190:193], v[24:27]
	v_mfma_f32_16x16x32_bf16 v[28:31], v[170:173], v[198:201], v[28:31]
	v_mfma_f32_16x16x32_bf16 v[60:63], v[178:181], v[198:201], v[60:63]
	v_mfma_f32_16x16x32_bf16 v[106:109], v[170:173], v[206:209], v[106:109]
	v_mfma_f32_16x16x32_bf16 v[110:113], v[178:181], v[206:209], v[110:113]
	v_mfma_f32_16x16x32_bf16 v[16:19], v[170:173], v[220:223], v[16:19]
	v_mfma_f32_16x16x32_bf16 v[20:23], v[178:181], v[220:223], v[20:23]
	s_setprio 1
	s_barrier
	s_add_u32 s44, s78, 0x200
	s_addc_u32 s45, s79, 0
	s_add_u32 s46, s76, 0x200
	s_addc_u32 s47, s77, 0
	s_add_u32 s78, s78, 0x280
	s_addc_u32 s79, s79, 0
	s_add_u32 s76, s76, 0x280
	s_addc_u32 s77, s77, 0
	s_mov_b64 s[42:43], s[78:79]
	ds_read_b128 v[114:117], v0
	ds_read_b128 v[118:121], v0 offset:1024
	ds_read_b128 v[122:125], v0 offset:2048
	ds_read_b128 v[126:129], v0 offset:3072
	ds_read_b128 v[138:141], v1
	ds_read_b128 v[170:173], v1 offset:1024
	ds_read_b128 v[174:177], v1 offset:2048
	ds_read_b128 v[178:181], v1 offset:3072
	s_add_u32 s80, s80, 0x18000
	s_addc_u32 s81, s81, 0
	s_mov_b32 m0, s88
	ds_read_b128 v[182:185], v157
	ds_read_b128 v[190:193], v157 offset:1024
	ds_read_b128 v[194:197], v157 offset:2048
	ds_read_b128 v[198:201], v157 offset:3072
	ds_read_b128 v[202:205], v157 offset:4096
	ds_read_b128 v[206:209], v157 offset:5120
	ds_read_b128 v[210:213], v157 offset:6144
	ds_read_b128 v[220:223], v157 offset:7168
	global_load_lds_dwordx4 v136, s[80:81]
	s_mov_b32 m0, vcc_lo
	s_nop 0
	global_load_lds_dwordx4 v132, s[80:81]
	s_waitcnt vmcnt(8)
	s_waitcnt lgkmcnt(0)
	s_barrier
	s_setprio 0
	s_waitcnt lgkmcnt(0)
	v_mfma_f32_16x16x32_bf16 v[64:67], v[114:117], v[182:185], v[66:69]
	v_mfma_f32_16x16x32_bf16 v[68:71], v[122:125], v[182:185], v[70:73]
	v_mfma_f32_16x16x32_bf16 v[72:75], v[114:117], v[194:197], v[74:77]
	v_mfma_f32_16x16x32_bf16 v[76:79], v[122:125], v[194:197], v[78:81]
	v_mfma_f32_16x16x32_bf16 v[80:83], v[114:117], v[202:205], v[82:85]
	v_mfma_f32_16x16x32_bf16 v[84:87], v[122:125], v[202:205], v[86:89]
	v_mfma_f32_16x16x32_bf16 v[88:91], v[114:117], v[210:213], v[90:93]
	v_mfma_f32_16x16x32_bf16 v[92:95], v[122:125], v[210:213], v[98:101]
	v_mfma_f32_16x16x32_bf16 v[64:67], v[118:121], v[190:193], v[64:67]
	v_mfma_f32_16x16x32_bf16 v[68:71], v[126:129], v[190:193], v[68:71]
	v_mfma_f32_16x16x32_bf16 v[72:75], v[118:121], v[198:201], v[72:75]
	v_mfma_f32_16x16x32_bf16 v[76:79], v[126:129], v[198:201], v[76:79]
	v_mfma_f32_16x16x32_bf16 v[80:83], v[118:121], v[206:209], v[80:83]
	v_mfma_f32_16x16x32_bf16 v[84:87], v[126:129], v[206:209], v[84:87]
	v_mfma_f32_16x16x32_bf16 v[88:91], v[118:121], v[220:223], v[88:91]
	v_mfma_f32_16x16x32_bf16 v[92:95], v[126:129], v[220:223], v[92:95]
	v_mfma_f32_16x16x32_bf16 v[98:101], v[138:141], v[182:185], v[102:105]
	v_mfma_f32_16x16x32_bf16 v[32:35], v[174:177], v[182:185], v[32:35]
	v_mfma_f32_16x16x32_bf16 v[36:39], v[138:141], v[194:197], v[36:39]
	v_mfma_f32_16x16x32_bf16 v[40:43], v[174:177], v[194:197], v[40:43]
	v_mfma_f32_16x16x32_bf16 v[44:47], v[138:141], v[202:205], v[44:47]
	v_mfma_f32_16x16x32_bf16 v[52:55], v[138:141], v[210:213], v[52:55]
	v_mfma_f32_16x16x32_bf16 v[56:59], v[174:177], v[210:213], v[56:59]
	v_mfma_f32_16x16x32_bf16 v[98:101], v[170:173], v[190:193], v[98:101]
	v_mfma_f32_16x16x32_bf16 v[32:35], v[178:181], v[190:193], v[32:35]
	v_mfma_f32_16x16x32_bf16 v[36:39], v[170:173], v[198:201], v[36:39]
	v_mfma_f32_16x16x32_bf16 v[40:43], v[178:181], v[198:201], v[40:43]
	v_mfma_f32_16x16x32_bf16 v[44:47], v[170:173], v[206:209], v[44:47]
	v_mfma_f32_16x16x32_bf16 v[48:51], v[174:177], v[202:205], v[48:51]
	v_mfma_f32_16x16x32_bf16 v[52:55], v[170:173], v[220:223], v[52:55]
	v_mfma_f32_16x16x32_bf16 v[56:59], v[178:181], v[220:223], v[56:59]
	v_mfma_f32_16x16x32_bf16 v[48:51], v[178:181], v[206:209], v[48:51]
	s_setprio 1
	s_barrier
	s_mov_b32 m0, vcc_hi
	ds_read_b128 v[102:105], v157 offset:16384
	ds_read_b128 v[182:185], v157 offset:17408
	ds_read_b128 v[190:193], v157 offset:18432
	ds_read_b128 v[194:197], v157 offset:19456
	ds_read_b128 v[198:201], v157 offset:20480
	ds_read_b128 v[202:205], v157 offset:21504
	ds_read_b128 v[206:209], v157 offset:22528
	ds_read_b128 v[210:213], v157 offset:23552
	global_load_lds_dwordx4 v134, s[46:47]
	v_lshl_add_u64 v[186:187], s[46:47], 0, v[130:131]
	s_add_u32 s46, s46, 0x18000
	s_mov_b32 m0, s70
	s_addc_u32 s47, s47, 0
	global_load_lds_dwordx4 v[186:187], off
	s_mov_b32 m0, s22
	s_nop 0
	global_load_lds_dwordx4 v134, s[46:47]
	s_mov_b32 m0, s23
	s_nop 0
	global_load_lds_dwordx4 v130, s[46:47]
	s_mov_b32 m0, s49
	s_nop 0
	global_load_lds_dwordx4 v136, s[44:45]
	s_mov_b32 m0, s89
	s_nop 0
	global_load_lds_dwordx4 v132, s[44:45]
	s_waitcnt vmcnt(8)
	s_waitcnt lgkmcnt(0)
	s_barrier
	s_setprio 0
	s_waitcnt lgkmcnt(0)
	v_mfma_f32_16x16x32_bf16 v[4:7], v[114:117], v[206:209], v[4:7]
	v_mfma_f32_16x16x32_bf16 v[8:11], v[122:125], v[206:209], v[8:11]
	v_mfma_f32_16x16x32_bf16 v[142:145], v[114:117], v[102:105], v[142:145]
	v_mfma_f32_16x16x32_bf16 v[146:149], v[122:125], v[102:105], v[146:149]
	v_mfma_f32_16x16x32_bf16 v[150:153], v[114:117], v[190:193], v[150:153]
	v_mfma_f32_16x16x32_bf16 v[158:161], v[122:125], v[190:193], v[158:161]
	v_mfma_f32_16x16x32_bf16 v[162:165], v[114:117], v[198:201], v[162:165]
	v_mfma_f32_16x16x32_bf16 v[166:169], v[122:125], v[198:201], v[166:169]
	v_mfma_f32_16x16x32_bf16 v[4:7], v[118:121], v[210:213], v[4:7]
	v_mfma_f32_16x16x32_bf16 v[8:11], v[126:129], v[210:213], v[8:11]
	v_mfma_f32_16x16x32_bf16 v[142:145], v[118:121], v[182:185], v[142:145]
	v_mfma_f32_16x16x32_bf16 v[146:149], v[126:129], v[182:185], v[146:149]
	v_mfma_f32_16x16x32_bf16 v[150:153], v[118:121], v[194:197], v[150:153]
	v_mfma_f32_16x16x32_bf16 v[158:161], v[126:129], v[194:197], v[158:161]
	v_mfma_f32_16x16x32_bf16 v[162:165], v[118:121], v[202:205], v[162:165]
	v_mfma_f32_16x16x32_bf16 v[166:169], v[126:129], v[202:205], v[166:169]
	v_mfma_f32_16x16x32_bf16 v[12:15], v[138:141], v[102:105], v[12:15]
	v_mfma_f32_16x16x32_bf16 v[24:27], v[174:177], v[102:105], v[24:27]
	v_mfma_f32_16x16x32_bf16 v[28:31], v[138:141], v[190:193], v[28:31]
	v_mfma_f32_16x16x32_bf16 v[60:63], v[174:177], v[190:193], v[60:63]
	v_mfma_f32_16x16x32_bf16 v[102:105], v[138:141], v[198:201], v[106:109]
	v_mfma_f32_16x16x32_bf16 v[106:109], v[174:177], v[198:201], v[110:113]
	v_mfma_f32_16x16x32_bf16 v[16:19], v[138:141], v[206:209], v[16:19]
	v_mfma_f32_16x16x32_bf16 v[20:23], v[174:177], v[206:209], v[20:23]
	v_mfma_f32_16x16x32_bf16 v[12:15], v[170:173], v[182:185], v[12:15]
	v_mfma_f32_16x16x32_bf16 v[24:27], v[178:181], v[182:185], v[24:27]
	v_mfma_f32_16x16x32_bf16 v[28:31], v[170:173], v[194:197], v[28:31]
	v_mfma_f32_16x16x32_bf16 v[60:63], v[178:181], v[194:197], v[60:63]
	v_mfma_f32_16x16x32_bf16 v[102:105], v[170:173], v[202:205], v[102:105]
	v_mfma_f32_16x16x32_bf16 v[106:109], v[178:181], v[202:205], v[106:109]
	v_mfma_f32_16x16x32_bf16 v[16:19], v[170:173], v[210:213], v[16:19]
	v_mfma_f32_16x16x32_bf16 v[20:23], v[178:181], v[210:213], v[20:23]
	s_setprio 1
	s_barrier
	ds_read_b128 v[110:113], v2
	ds_read_b128 v[114:117], v2 offset:1024
	ds_read_b128 v[118:121], v2 offset:2048
	ds_read_b128 v[122:125], v2 offset:3072
	ds_read_b128 v[126:129], v3
	ds_read_b128 v[138:141], v3 offset:1024
	ds_read_b128 v[170:173], v3 offset:2048
	ds_read_b128 v[174:177], v3 offset:3072
	s_add_u32 s44, s44, 0x18000
	s_addc_u32 s45, s45, 0
	s_mov_b32 m0, s90
	ds_read_b128 v[178:181], v157 offset:32768
	ds_read_b128 v[182:185], v157 offset:33792
	ds_read_b128 v[190:193], v157 offset:34816
	ds_read_b128 v[194:197], v157 offset:35840
	ds_read_b128 v[198:201], v157 offset:36864
	ds_read_b128 v[202:205], v157 offset:37888
	ds_read_b128 v[206:209], v157 offset:38912
	ds_read_b128 v[210:213], v157 offset:39936
	global_load_lds_dwordx4 v136, s[44:45]
	s_mov_b32 m0, s91
	s_nop 0
	global_load_lds_dwordx4 v132, s[44:45]
	s_waitcnt vmcnt(8)
	s_waitcnt lgkmcnt(0)
	s_barrier
	s_setprio 0
	s_waitcnt lgkmcnt(0)
	v_mfma_f32_16x16x32_bf16 v[64:67], v[110:113], v[178:181], v[64:67]
	v_mfma_f32_16x16x32_bf16 v[68:71], v[118:121], v[178:181], v[68:71]
	v_mfma_f32_16x16x32_bf16 v[72:75], v[110:113], v[190:193], v[72:75]
	v_mfma_f32_16x16x32_bf16 v[76:79], v[118:121], v[190:193], v[76:79]
	v_mfma_f32_16x16x32_bf16 v[80:83], v[110:113], v[198:201], v[80:83]
	v_mfma_f32_16x16x32_bf16 v[84:87], v[118:121], v[198:201], v[84:87]
	v_mfma_f32_16x16x32_bf16 v[88:91], v[110:113], v[206:209], v[88:91]
	v_mfma_f32_16x16x32_bf16 v[92:95], v[118:121], v[206:209], v[92:95]
	v_mfma_f32_16x16x32_bf16 v[64:67], v[114:117], v[182:185], v[64:67]
	v_mfma_f32_16x16x32_bf16 v[68:71], v[122:125], v[182:185], v[68:71]
	v_mfma_f32_16x16x32_bf16 v[72:75], v[114:117], v[194:197], v[72:75]
	v_mfma_f32_16x16x32_bf16 v[76:79], v[122:125], v[194:197], v[76:79]
	v_mfma_f32_16x16x32_bf16 v[80:83], v[114:117], v[202:205], v[80:83]
	v_mfma_f32_16x16x32_bf16 v[84:87], v[122:125], v[202:205], v[84:87]
	v_mfma_f32_16x16x32_bf16 v[88:91], v[114:117], v[210:213], v[88:91]
	v_mfma_f32_16x16x32_bf16 v[92:95], v[122:125], v[210:213], v[92:95]
	v_mfma_f32_16x16x32_bf16 v[98:101], v[126:129], v[178:181], v[98:101]
	v_mfma_f32_16x16x32_bf16 v[32:35], v[170:173], v[178:181], v[32:35]
	v_mfma_f32_16x16x32_bf16 v[36:39], v[126:129], v[190:193], v[36:39]
	v_mfma_f32_16x16x32_bf16 v[40:43], v[170:173], v[190:193], v[40:43]
	v_mfma_f32_16x16x32_bf16 v[44:47], v[126:129], v[198:201], v[44:47]
	v_mfma_f32_16x16x32_bf16 v[52:55], v[126:129], v[206:209], v[52:55]
	v_mfma_f32_16x16x32_bf16 v[56:59], v[170:173], v[206:209], v[56:59]
	v_mfma_f32_16x16x32_bf16 v[98:101], v[138:141], v[182:185], v[98:101]
	v_mfma_f32_16x16x32_bf16 v[32:35], v[174:177], v[182:185], v[32:35]
	v_mfma_f32_16x16x32_bf16 v[36:39], v[138:141], v[194:197], v[36:39]
	v_mfma_f32_16x16x32_bf16 v[40:43], v[174:177], v[194:197], v[40:43]
	v_mfma_f32_16x16x32_bf16 v[44:47], v[138:141], v[202:205], v[44:47]
	v_mfma_f32_16x16x32_bf16 v[48:51], v[170:173], v[198:201], v[48:51]
	v_mfma_f32_16x16x32_bf16 v[52:55], v[138:141], v[210:213], v[52:55]
	v_mfma_f32_16x16x32_bf16 v[56:59], v[174:177], v[210:213], v[56:59]
	v_mfma_f32_16x16x32_bf16 v[48:51], v[174:177], v[202:205], v[48:51]
	s_setprio 1
	s_barrier
	s_mov_b32 m0, s18
	s_add_u32 s44, s76, 0x18000
	ds_read_b128 v[178:181], v157 offset:49152
	ds_read_b128 v[182:185], v157 offset:50176
	ds_read_b128 v[190:193], v157 offset:51200
	ds_read_b128 v[194:197], v157 offset:52224
	ds_read_b128 v[198:201], v157 offset:53248
	ds_read_b128 v[202:205], v157 offset:54272
	ds_read_b128 v[206:209], v157 offset:55296
	ds_read_b128 v[210:213], v157 offset:56320
	global_load_lds_dwordx4 v134, s[76:77]
	s_mov_b32 m0, s35
	s_addc_u32 s45, s77, 0
	global_load_lds_dwordx4 v130, s[76:77]
	s_mov_b32 m0, s19
	s_nop 0
	global_load_lds_dwordx4 v134, s[44:45]
	s_mov_b32 m0, s84
	s_nop 0
	global_load_lds_dwordx4 v130, s[44:45]
	s_mov_b32 m0, s93
	s_nop 0
	global_load_lds_dwordx4 v136, s[42:43]
	s_mov_b32 m0, s94
	s_nop 0
	global_load_lds_dwordx4 v132, s[42:43]
	s_waitcnt vmcnt(8)
	s_waitcnt lgkmcnt(0)
	s_barrier
	s_setprio 0
	s_waitcnt lgkmcnt(0)
	v_mfma_f32_16x16x32_bf16 v[4:7], v[110:113], v[206:209], v[4:7]
	v_mfma_f32_16x16x32_bf16 v[8:11], v[118:121], v[206:209], v[8:11]
	v_mfma_f32_16x16x32_bf16 v[142:145], v[110:113], v[178:181], v[142:145]
	v_mfma_f32_16x16x32_bf16 v[146:149], v[118:121], v[178:181], v[146:149]
	v_mfma_f32_16x16x32_bf16 v[150:153], v[110:113], v[190:193], v[150:153]
	v_mfma_f32_16x16x32_bf16 v[158:161], v[118:121], v[190:193], v[158:161]
	v_mfma_f32_16x16x32_bf16 v[162:165], v[110:113], v[198:201], v[162:165]
	v_mfma_f32_16x16x32_bf16 v[166:169], v[118:121], v[198:201], v[166:169]
	v_mfma_f32_16x16x32_bf16 v[4:7], v[114:117], v[210:213], v[4:7]
	v_mfma_f32_16x16x32_bf16 v[8:11], v[122:125], v[210:213], v[8:11]
	v_mfma_f32_16x16x32_bf16 v[142:145], v[114:117], v[182:185], v[142:145]
	v_mfma_f32_16x16x32_bf16 v[146:149], v[122:125], v[182:185], v[146:149]
	v_mfma_f32_16x16x32_bf16 v[150:153], v[114:117], v[194:197], v[150:153]
	v_mfma_f32_16x16x32_bf16 v[158:161], v[122:125], v[194:197], v[158:161]
	v_mfma_f32_16x16x32_bf16 v[162:165], v[114:117], v[202:205], v[162:165]
	v_mfma_f32_16x16x32_bf16 v[166:169], v[122:125], v[202:205], v[166:169]
	v_mfma_f32_16x16x32_bf16 v[12:15], v[126:129], v[178:181], v[12:15]
	v_mfma_f32_16x16x32_bf16 v[24:27], v[170:173], v[178:181], v[24:27]
	v_mfma_f32_16x16x32_bf16 v[28:31], v[126:129], v[190:193], v[28:31]
	v_mfma_f32_16x16x32_bf16 v[60:63], v[170:173], v[190:193], v[60:63]
	v_mfma_f32_16x16x32_bf16 v[102:105], v[126:129], v[198:201], v[102:105]
	v_mfma_f32_16x16x32_bf16 v[106:109], v[170:173], v[198:201], v[106:109]
	v_mfma_f32_16x16x32_bf16 v[16:19], v[126:129], v[206:209], v[16:19]
	v_mfma_f32_16x16x32_bf16 v[20:23], v[170:173], v[206:209], v[20:23]
	v_mfma_f32_16x16x32_bf16 v[12:15], v[138:141], v[182:185], v[12:15]
	v_mfma_f32_16x16x32_bf16 v[24:27], v[174:177], v[182:185], v[24:27]
	v_mfma_f32_16x16x32_bf16 v[28:31], v[138:141], v[194:197], v[28:31]
	v_mfma_f32_16x16x32_bf16 v[60:63], v[174:177], v[194:197], v[60:63]
	v_mfma_f32_16x16x32_bf16 v[102:105], v[138:141], v[202:205], v[102:105]
	v_mfma_f32_16x16x32_bf16 v[106:109], v[174:177], v[202:205], v[106:109]
	v_mfma_f32_16x16x32_bf16 v[16:19], v[138:141], v[210:213], v[16:19]
	v_mfma_f32_16x16x32_bf16 v[20:23], v[174:177], v[210:213], v[20:23]
	s_setprio 1
	s_barrier
	s_add_u32 s76, s38, 0x80
	s_addc_u32 s77, s39, 0
	s_add_u32 s42, s68, 0x80
	s_addc_u32 s43, s69, 0
	ds_read_b128 v[110:113], v0
	ds_read_b128 v[114:117], v0 offset:1024
	ds_read_b128 v[118:121], v0 offset:2048
	ds_read_b128 v[122:125], v0 offset:3072
	ds_read_b128 v[126:129], v1
	ds_read_b128 v[138:141], v1 offset:1024
	ds_read_b128 v[170:173], v1 offset:2048
	ds_read_b128 v[174:177], v1 offset:3072
	s_add_u32 s44, s78, 0x18000
	s_addc_u32 s45, s79, 0
	s_mov_b32 m0, s88
	ds_read_b128 v[178:181], v157
	ds_read_b128 v[182:185], v157 offset:1024
	ds_read_b128 v[190:193], v157 offset:2048
	ds_read_b128 v[194:197], v157 offset:3072
	ds_read_b128 v[198:201], v157 offset:4096
	ds_read_b128 v[202:205], v157 offset:5120
	ds_read_b128 v[206:209], v157 offset:6144
	ds_read_b128 v[210:213], v157 offset:7168
	global_load_lds_dwordx4 v136, s[44:45]
	s_mov_b32 m0, vcc_lo
	s_nop 0
	global_load_lds_dwordx4 v132, s[44:45]
	s_waitcnt vmcnt(8)
	s_waitcnt lgkmcnt(0)
	s_barrier
	s_setprio 0
	s_waitcnt lgkmcnt(0)
	v_mfma_f32_16x16x32_bf16 v[88:91], v[110:113], v[206:209], v[88:91]
	v_mfma_f32_16x16x32_bf16 v[64:67], v[110:113], v[178:181], v[64:67]
	v_mfma_f32_16x16x32_bf16 v[68:71], v[118:121], v[178:181], v[68:71]
	v_mfma_f32_16x16x32_bf16 v[72:75], v[110:113], v[190:193], v[72:75]
	v_mfma_f32_16x16x32_bf16 v[76:79], v[118:121], v[190:193], v[76:79]
	v_mfma_f32_16x16x32_bf16 v[80:83], v[110:113], v[198:201], v[80:83]
	v_mfma_f32_16x16x32_bf16 v[84:87], v[118:121], v[198:201], v[84:87]
	v_mfma_f32_16x16x32_bf16 v[220:223], v[114:117], v[210:213], v[88:91]
	v_mfma_f32_16x16x32_bf16 v[88:91], v[118:121], v[206:209], v[92:95]
	v_mfma_f32_16x16x32_bf16 v[64:67], v[114:117], v[182:185], v[64:67]
	v_mfma_f32_16x16x32_bf16 v[68:71], v[122:125], v[182:185], v[68:71]
	v_mfma_f32_16x16x32_bf16 v[72:75], v[114:117], v[194:197], v[72:75]
	v_mfma_f32_16x16x32_bf16 v[76:79], v[122:125], v[194:197], v[76:79]
	v_mfma_f32_16x16x32_bf16 v[80:83], v[114:117], v[202:205], v[80:83]
	v_mfma_f32_16x16x32_bf16 v[84:87], v[122:125], v[202:205], v[84:87]
	v_mfma_f32_16x16x32_bf16 v[92:95], v[122:125], v[210:213], v[88:91]
	v_mfma_f32_16x16x32_bf16 v[48:51], v[170:173], v[198:201], v[48:51]
	v_mfma_f32_16x16x32_bf16 v[88:91], v[126:129], v[178:181], v[98:101]
	v_mfma_f32_16x16x32_bf16 v[32:35], v[170:173], v[178:181], v[32:35]
	v_mfma_f32_16x16x32_bf16 v[36:39], v[126:129], v[190:193], v[36:39]
	v_mfma_f32_16x16x32_bf16 v[40:43], v[170:173], v[190:193], v[40:43]
	v_mfma_f32_16x16x32_bf16 v[44:47], v[126:129], v[198:201], v[44:47]
	v_mfma_f32_16x16x32_bf16 v[178:181], v[174:177], v[202:205], v[48:51]
	v_mfma_f32_16x16x32_bf16 v[48:51], v[126:129], v[206:209], v[52:55]
	v_mfma_f32_16x16x32_bf16 v[32:35], v[174:177], v[182:185], v[32:35]
	v_mfma_f32_16x16x32_bf16 v[36:39], v[138:141], v[194:197], v[36:39]
	v_mfma_f32_16x16x32_bf16 v[40:43], v[174:177], v[194:197], v[40:43]
	v_mfma_f32_16x16x32_bf16 v[44:47], v[138:141], v[202:205], v[44:47]
	v_mfma_f32_16x16x32_bf16 v[52:55], v[138:141], v[210:213], v[48:51]
	v_mfma_f32_16x16x32_bf16 v[48:51], v[170:173], v[206:209], v[56:59]
	v_mfma_f32_16x16x32_bf16 v[224:227], v[138:141], v[182:185], v[88:91]
	v_mfma_f32_16x16x32_bf16 v[182:185], v[174:177], v[210:213], v[48:51]
	s_setprio 1
	s_barrier
	s_mov_b32 m0, vcc_hi
	s_add_u32 s44, s68, 0x18000
	s_nop 0
	ds_read_b128 v[48:51], v157 offset:16384
	ds_read_b128 v[56:59], v157 offset:17408
	ds_read_b128 v[88:91], v157 offset:18432
	ds_read_b128 v[98:101], v157 offset:19456
	ds_read_b128 v[190:193], v157 offset:20480
	ds_read_b128 v[194:197], v157 offset:21504
	ds_read_b128 v[198:201], v157 offset:22528
	ds_read_b128 v[202:205], v157 offset:23552
	global_load_lds_dwordx4 v134, s[68:69]
	s_mov_b32 m0, s70
	s_addc_u32 s45, s69, 0
	global_load_lds_dwordx4 v130, s[68:69]
	s_mov_b32 m0, s22
	s_nop 0
	global_load_lds_dwordx4 v134, s[44:45]
	s_mov_b32 m0, s23
	s_nop 0
	global_load_lds_dwordx4 v130, s[44:45]
	s_mov_b32 m0, s49
	s_nop 0
	global_load_lds_dwordx4 v136, s[38:39]
	s_mov_b32 m0, s89
	s_nop 0
	global_load_lds_dwordx4 v132, s[38:39]
	s_waitcnt vmcnt(8)
	s_waitcnt lgkmcnt(0)
	s_barrier
	s_setprio 0
	s_waitcnt lgkmcnt(0)
	v_mfma_f32_16x16x32_bf16 v[4:7], v[110:113], v[198:201], v[4:7]
	v_mfma_f32_16x16x32_bf16 v[142:145], v[110:113], v[48:51], v[142:145]
	v_mfma_f32_16x16x32_bf16 v[146:149], v[118:121], v[48:51], v[146:149]
	v_mfma_f32_16x16x32_bf16 v[150:153], v[110:113], v[88:91], v[150:153]
	v_mfma_f32_16x16x32_bf16 v[158:161], v[118:121], v[88:91], v[158:161]
	v_mfma_f32_16x16x32_bf16 v[162:165], v[110:113], v[190:193], v[162:165]
	v_mfma_f32_16x16x32_bf16 v[166:169], v[118:121], v[190:193], v[166:169]
	v_mfma_f32_16x16x32_bf16 v[4:7], v[114:117], v[202:205], v[4:7]
	v_mfma_f32_16x16x32_bf16 v[8:11], v[118:121], v[198:201], v[8:11]
	v_mfma_f32_16x16x32_bf16 v[142:145], v[114:117], v[56:59], v[142:145]
	v_mfma_f32_16x16x32_bf16 v[146:149], v[122:125], v[56:59], v[146:149]
	v_mfma_f32_16x16x32_bf16 v[150:153], v[114:117], v[98:101], v[150:153]
	v_mfma_f32_16x16x32_bf16 v[158:161], v[122:125], v[98:101], v[158:161]
	v_mfma_f32_16x16x32_bf16 v[162:165], v[114:117], v[194:197], v[162:165]
	v_mfma_f32_16x16x32_bf16 v[166:169], v[122:125], v[194:197], v[166:169]
	v_mfma_f32_16x16x32_bf16 v[206:209], v[122:125], v[202:205], v[8:11]
	v_mfma_f32_16x16x32_bf16 v[8:11], v[126:129], v[48:51], v[12:15]
	v_mfma_f32_16x16x32_bf16 v[12:15], v[138:141], v[56:59], v[8:11]
	v_mfma_f32_16x16x32_bf16 v[8:11], v[170:173], v[48:51], v[24:27]
	v_mfma_f32_16x16x32_bf16 v[210:213], v[174:177], v[56:59], v[8:11]
	v_mfma_f32_16x16x32_bf16 v[8:11], v[126:129], v[88:91], v[28:31]
	v_mfma_f32_16x16x32_bf16 v[28:31], v[138:141], v[98:101], v[8:11]
	v_mfma_f32_16x16x32_bf16 v[8:11], v[170:173], v[88:91], v[60:63]
	v_mfma_f32_16x16x32_bf16 v[228:231], v[174:177], v[98:101], v[8:11]
	v_mfma_f32_16x16x32_bf16 v[8:11], v[126:129], v[190:193], v[102:105]
	v_mfma_f32_16x16x32_bf16 v[232:235], v[138:141], v[194:197], v[8:11]
	v_mfma_f32_16x16x32_bf16 v[8:11], v[170:173], v[190:193], v[106:109]
	v_mfma_f32_16x16x32_bf16 v[190:193], v[174:177], v[194:197], v[8:11]
	v_mfma_f32_16x16x32_bf16 v[8:11], v[126:129], v[198:201], v[16:19]
	v_mfma_f32_16x16x32_bf16 v[138:141], v[138:141], v[202:205], v[8:11]
	v_mfma_f32_16x16x32_bf16 v[8:11], v[170:173], v[198:201], v[20:23]
	v_mfma_f32_16x16x32_bf16 v[170:173], v[174:177], v[202:205], v[8:11]
	s_setprio 1
	s_barrier
	s_nop 4
	ds_read_b128 v[8:11], v2
	ds_read_b128 v[20:23], v2 offset:1024
	ds_read_b128 v[174:177], v2 offset:2048
	ds_read_b128 v[194:197], v2 offset:3072
	ds_read_b128 v[198:201], v3
	ds_read_b128 v[202:205], v3 offset:1024
	ds_read_b128 v[236:239], v3 offset:2048
	ds_read_b128 v[240:243], v3 offset:3072
	s_add_u32 s22, s38, 0x18000
	s_addc_u32 s23, s39, 0
	s_mov_b32 m0, s90
	ds_read_b128 v[0:3], v157 offset:32768
	ds_read_b128 v[16:19], v157 offset:33792
	ds_read_b128 v[24:27], v157 offset:34816
	ds_read_b128 v[60:63], v157 offset:35840
	ds_read_b128 v[244:247], v157 offset:36864
	ds_read_b128 v[248:251], v157 offset:37888
	ds_read_b128 v[186:189], v157 offset:38912
	ds_read_b128 v[48:51], v157 offset:39936
	global_load_lds_dwordx4 v136, s[22:23]
	s_mov_b32 m0, s91
	s_nop 0
	global_load_lds_dwordx4 v132, s[22:23]
	s_waitcnt vmcnt(8)
	s_waitcnt lgkmcnt(0)
	s_barrier
	s_setprio 0
	s_waitcnt lgkmcnt(0)
	v_mfma_f32_16x16x32_bf16 v[56:59], v[8:11], v[0:3], v[64:67]
	v_mfma_f32_16x16x32_bf16 v[122:125], v[20:23], v[16:19], v[56:59]
	v_mfma_f32_16x16x32_bf16 v[56:59], v[174:177], v[0:3], v[68:71]
	v_mfma_f32_16x16x32_bf16 v[114:117], v[194:197], v[16:19], v[56:59]
	v_mfma_f32_16x16x32_bf16 v[56:59], v[8:11], v[24:27], v[72:75]
	v_mfma_f32_16x16x32_bf16 v[106:109], v[20:23], v[60:63], v[56:59]
	v_mfma_f32_16x16x32_bf16 v[56:59], v[174:177], v[24:27], v[76:79]
	v_mfma_f32_16x16x32_bf16 v[98:101], v[194:197], v[60:63], v[56:59]
	v_mfma_f32_16x16x32_bf16 v[56:59], v[8:11], v[244:247], v[80:83]
	v_mfma_f32_16x16x32_bf16 v[88:91], v[20:23], v[248:251], v[56:59]
	v_mfma_f32_16x16x32_bf16 v[56:59], v[174:177], v[244:247], v[84:87]
	v_mfma_f32_16x16x32_bf16 v[80:83], v[194:197], v[248:251], v[56:59]
	v_mfma_f32_16x16x32_bf16 v[56:59], v[8:11], v[186:189], v[220:223]
	v_mfma_f32_16x16x32_bf16 v[64:67], v[174:177], v[186:189], v[92:95]
	v_mfma_f32_16x16x32_bf16 v[56:59], v[20:23], v[48:51], v[56:59]
	v_mfma_f32_16x16x32_bf16 v[220:223], v[194:197], v[48:51], v[64:67]
	v_mfma_f32_16x16x32_bf16 v[64:67], v[198:201], v[0:3], v[224:227]
	v_mfma_f32_16x16x32_bf16 v[0:3], v[236:239], v[0:3], v[32:35]
	v_mfma_f32_16x16x32_bf16 v[118:121], v[240:243], v[16:19], v[0:3]
	v_mfma_f32_16x16x32_bf16 v[0:3], v[198:201], v[24:27], v[36:39]
	v_mfma_f32_16x16x32_bf16 v[110:113], v[202:205], v[60:63], v[0:3]
	v_mfma_f32_16x16x32_bf16 v[0:3], v[236:239], v[24:27], v[40:43]
	v_mfma_f32_16x16x32_bf16 v[102:105], v[240:243], v[60:63], v[0:3]
	v_mfma_f32_16x16x32_bf16 v[0:3], v[198:201], v[244:247], v[44:47]
	v_mfma_f32_16x16x32_bf16 v[92:95], v[202:205], v[248:251], v[0:3]
	v_mfma_f32_16x16x32_bf16 v[0:3], v[236:239], v[244:247], v[178:181]
	v_mfma_f32_16x16x32_bf16 v[84:87], v[240:243], v[248:251], v[0:3]
	v_mfma_f32_16x16x32_bf16 v[0:3], v[198:201], v[186:189], v[52:55]
	v_mfma_f32_16x16x32_bf16 v[60:63], v[202:205], v[48:51], v[0:3]
	v_mfma_f32_16x16x32_bf16 v[0:3], v[236:239], v[186:189], v[182:185]
	v_mfma_f32_16x16x32_bf16 v[126:129], v[202:205], v[16:19], v[64:67]
	v_mfma_f32_16x16x32_bf16 v[52:55], v[240:243], v[48:51], v[0:3]
	s_setprio 1
	s_barrier
	s_mov_b32 m0, s18
	s_nop 2
	s_add_u32 s22, s42, 0x18000
	ds_read_b128 v[36:39], v157 offset:49152
	ds_read_b128 v[44:47], v157 offset:50176
	ds_read_b128 v[48:51], v157 offset:51200
	ds_read_b128 v[178:181], v157 offset:52224
	ds_read_b128 v[182:185], v157 offset:53248
	ds_read_b128 v[186:189], v157 offset:54272
	ds_read_b128 v[224:227], v157 offset:55296
	ds_read_b128 v[244:247], v157 offset:56320
	global_load_lds_dwordx4 v134, s[42:43]
	s_mov_b32 m0, s35
	s_addc_u32 s23, s43, 0
	global_load_lds_dwordx4 v130, s[42:43]
	s_mov_b32 m0, s19
	s_nop 0
	global_load_lds_dwordx4 v134, s[22:23]
	s_mov_b32 m0, s84
	s_nop 0
	global_load_lds_dwordx4 v130, s[22:23]
	s_mov_b32 m0, s93
	s_nop 0
	global_load_lds_dwordx4 v136, s[76:77]
	s_mov_b32 m0, s94
	s_nop 0
	global_load_lds_dwordx4 v132, s[76:77]
	s_waitcnt vmcnt(8)
	s_waitcnt lgkmcnt(0)
	s_barrier
	s_setprio 0
	s_waitcnt lgkmcnt(0)
	v_mfma_f32_16x16x32_bf16 v[0:3], v[8:11], v[36:39], v[142:145]
	v_mfma_f32_16x16x32_bf16 v[72:75], v[20:23], v[44:47], v[0:3]
	v_mfma_f32_16x16x32_bf16 v[0:3], v[174:177], v[36:39], v[146:149]
	v_mfma_f32_16x16x32_bf16 v[64:67], v[194:197], v[44:47], v[0:3]
	v_mfma_f32_16x16x32_bf16 v[0:3], v[8:11], v[48:51], v[150:153]
	v_mfma_f32_16x16x32_bf16 v[40:43], v[20:23], v[178:181], v[0:3]
	v_mfma_f32_16x16x32_bf16 v[0:3], v[174:177], v[48:51], v[158:161]
	v_mfma_f32_16x16x32_bf16 v[32:35], v[194:197], v[178:181], v[0:3]
	v_mfma_f32_16x16x32_bf16 v[0:3], v[8:11], v[182:185], v[162:165]
	v_mfma_f32_16x16x32_bf16 v[24:27], v[20:23], v[186:189], v[0:3]
	v_mfma_f32_16x16x32_bf16 v[0:3], v[174:177], v[182:185], v[166:169]
	v_mfma_f32_16x16x32_bf16 v[16:19], v[194:197], v[186:189], v[0:3]
	v_mfma_f32_16x16x32_bf16 v[0:3], v[8:11], v[224:227], v[4:7]
	v_mfma_f32_16x16x32_bf16 v[8:11], v[20:23], v[244:247], v[0:3]
	v_mfma_f32_16x16x32_bf16 v[0:3], v[174:177], v[224:227], v[206:209]
	v_mfma_f32_16x16x32_bf16 v[0:3], v[194:197], v[244:247], v[0:3]
	v_mfma_f32_16x16x32_bf16 v[4:7], v[198:201], v[36:39], v[12:15]
	v_mfma_f32_16x16x32_bf16 v[76:79], v[202:205], v[44:47], v[4:7]
	v_mfma_f32_16x16x32_bf16 v[4:7], v[236:239], v[36:39], v[210:213]
	v_mfma_f32_16x16x32_bf16 v[68:71], v[240:243], v[44:47], v[4:7]
	v_mfma_f32_16x16x32_bf16 v[4:7], v[198:201], v[48:51], v[28:31]
	v_mfma_f32_16x16x32_bf16 v[44:47], v[202:205], v[178:181], v[4:7]
	v_mfma_f32_16x16x32_bf16 v[4:7], v[236:239], v[48:51], v[228:231]
	v_mfma_f32_16x16x32_bf16 v[36:39], v[240:243], v[178:181], v[4:7]
	v_mfma_f32_16x16x32_bf16 v[4:7], v[198:201], v[182:185], v[232:235]
	v_mfma_f32_16x16x32_bf16 v[28:31], v[202:205], v[186:189], v[4:7]
	v_mfma_f32_16x16x32_bf16 v[4:7], v[236:239], v[182:185], v[190:193]
	v_mfma_f32_16x16x32_bf16 v[20:23], v[240:243], v[186:189], v[4:7]
	v_mfma_f32_16x16x32_bf16 v[4:7], v[198:201], v[224:227], v[138:141]
	v_mfma_f32_16x16x32_bf16 v[12:15], v[202:205], v[244:247], v[4:7]
	v_mfma_f32_16x16x32_bf16 v[4:7], v[236:239], v[224:227], v[170:173]
	v_mfma_f32_16x16x32_bf16 v[4:7], v[240:243], v[244:247], v[4:7]
	s_setprio 1
	s_barrier
	s_andn2_b64 vcc, exec, s[62:63]
	s_cbranch_vccnz .LBB0_385
	s_barrier

.LBB0_409:
	s_ashr_i32 s61, s60, 31
	s_lshl_b64 s[18:19], s[60:61], 17
	s_add_u32 s62, s47, s18
	s_addc_u32 s63, s71, s19
	s_and_b64 s[18:19], s[6:7], exec
	s_cselect_b32 s39, s63, s79
	s_cselect_b32 s38, s62, s78
	s_ashr_i32 s59, s58, 31
	s_lshl_b64 s[18:19], s[58:59], 17
	s_add_u32 s64, s14, s18
	s_addc_u32 s65, s16, s19
	s_and_b64 s[18:19], s[6:7], exec
	s_cselect_b32 s69, s65, s77
	s_cselect_b32 s68, s64, s76
	s_add_u32 s18, s78, 0x80
	s_addc_u32 s19, s79, 0
	s_add_u32 s42, s78, 0x100
	s_addc_u32 s43, s79, 0
	s_add_u32 s44, s76, 0x100
	s_addc_u32 s45, s77, 0
	s_add_u32 s78, s78, 0x180
	s_addc_u32 s79, s79, 0
	s_add_u32 s80, s76, 0x180
	s_addc_u32 s81, s77, 0
	s_add_i32 s49, 0, 0x10000
	s_add_i32 s20, 0, 0x14000
	s_mov_b64 s[76:77], s[78:79]
	v_add_u32_e32 v96, s49, v139
	v_add_u32_e32 v138, s20, v139
	ds_read_b128 v[0:3], v96
	ds_read_b128 v[4:7], v96 offset:1024
	ds_read_b128 v[8:11], v96 offset:2048
	ds_read_b128 v[12:15], v96 offset:3072
	ds_read_b128 v[16:19], v138
	ds_read_b128 v[20:23], v138 offset:1024
	ds_read_b128 v[24:27], v138 offset:2048
	ds_read_b128 v[28:31], v138 offset:3072
	s_add_u32 s18, s18, 0x10000
	s_addc_u32 s19, s19, 0
	s_add_i32 s59, s67, 0xc000
	s_mov_b32 m0, s59
	ds_read_b128 v[32:35], v141
	ds_read_b128 v[36:39], v141 offset:1024
	ds_read_b128 v[40:43], v141 offset:2048
	ds_read_b128 v[44:47], v141 offset:3072
	ds_read_b128 v[48:51], v141 offset:4096
	ds_read_b128 v[52:55], v141 offset:5120
	ds_read_b128 v[56:59], v141 offset:6144
	ds_read_b128 v[60:63], v141 offset:7168
	global_load_lds_dwordx4 v130, s[18:19]
	v_lshl_add_u64 v[64:65], s[18:19], 0, v[134:135]
	s_add_i32 s18, s67, 0xe000
	s_mov_b32 m0, s18
	s_nop 0
	global_load_lds_dwordx4 v[64:65], off
	s_waitcnt vmcnt(8)
	s_waitcnt lgkmcnt(0)
	s_barrier
	s_setprio 0
	s_waitcnt lgkmcnt(0)
	v_mfma_f32_16x16x32_bf16 v[64:67], v[0:3], v[32:35], 0
	v_mfma_f32_16x16x32_bf16 v[68:71], v[8:11], v[32:35], 0
	v_mfma_f32_16x16x32_bf16 v[72:75], v[0:3], v[40:43], 0
	v_mfma_f32_16x16x32_bf16 v[76:79], v[8:11], v[40:43], 0
	v_mfma_f32_16x16x32_bf16 v[80:83], v[0:3], v[48:51], 0
	v_mfma_f32_16x16x32_bf16 v[84:87], v[8:11], v[48:51], 0
	v_mfma_f32_16x16x32_bf16 v[88:91], v[0:3], v[56:59], 0
	v_mfma_f32_16x16x32_bf16 v[92:95], v[8:11], v[56:59], 0
	v_mfma_f32_16x16x32_bf16 v[64:67], v[4:7], v[36:39], v[64:67]
	v_mfma_f32_16x16x32_bf16 v[68:71], v[12:15], v[36:39], v[68:71]
	v_mfma_f32_16x16x32_bf16 v[72:75], v[4:7], v[44:47], v[72:75]
	v_mfma_f32_16x16x32_bf16 v[76:79], v[12:15], v[44:47], v[76:79]
	v_mfma_f32_16x16x32_bf16 v[80:83], v[4:7], v[52:55], v[80:83]
	v_mfma_f32_16x16x32_bf16 v[84:87], v[12:15], v[52:55], v[84:87]
	v_mfma_f32_16x16x32_bf16 v[88:91], v[4:7], v[60:63], v[88:91]
	v_mfma_f32_16x16x32_bf16 v[92:95], v[12:15], v[60:63], v[92:95]
	v_mfma_f32_16x16x32_bf16 v[98:101], v[16:19], v[32:35], 0
	v_mfma_f32_16x16x32_bf16 v[32:35], v[24:27], v[32:35], 0
	v_mfma_f32_16x16x32_bf16 v[98:101], v[20:23], v[36:39], v[98:101]
	v_mfma_f32_16x16x32_bf16 v[32:35], v[28:31], v[36:39], v[32:35]
	v_mfma_f32_16x16x32_bf16 v[36:39], v[16:19], v[40:43], 0
	v_mfma_f32_16x16x32_bf16 v[40:43], v[24:27], v[40:43], 0
	v_mfma_f32_16x16x32_bf16 v[36:39], v[20:23], v[44:47], v[36:39]
	v_mfma_f32_16x16x32_bf16 v[40:43], v[28:31], v[44:47], v[40:43]
	v_mfma_f32_16x16x32_bf16 v[44:47], v[16:19], v[48:51], 0
	v_mfma_f32_16x16x32_bf16 v[48:51], v[24:27], v[48:51], 0
	v_mfma_f32_16x16x32_bf16 v[44:47], v[20:23], v[52:55], v[44:47]
	v_mfma_f32_16x16x32_bf16 v[48:51], v[28:31], v[52:55], v[48:51]
	v_mfma_f32_16x16x32_bf16 v[52:55], v[16:19], v[56:59], 0
	v_mfma_f32_16x16x32_bf16 v[56:59], v[24:27], v[56:59], 0
	v_mfma_f32_16x16x32_bf16 v[52:55], v[20:23], v[60:63], v[52:55]
	v_mfma_f32_16x16x32_bf16 v[56:59], v[28:31], v[60:63], v[56:59]
	s_setprio 1
	s_barrier
	s_add_i32 s49, s49, s46
	s_mov_b32 m0, s49
	s_add_i32 s19, s49, 0x2000
	ds_read_b128 v[60:63], v141 offset:16384
	ds_read_b128 v[102:105], v141 offset:17408
	ds_read_b128 v[106:109], v141 offset:18432
	ds_read_b128 v[110:113], v141 offset:19456
	ds_read_b128 v[114:117], v141 offset:20480
	ds_read_b128 v[118:121], v141 offset:21504
	ds_read_b128 v[122:125], v141 offset:22528
	ds_read_b128 v[126:129], v141 offset:23552
	global_load_lds_dwordx4 v132, s[44:45]
	v_lshl_add_u64 v[142:143], s[44:45], 0, v[136:137]
	s_add_u32 s44, s44, 0x10000
	s_mov_b32 m0, s19
	s_addc_u32 s45, s45, 0
	s_add_i32 s20, s20, s46
	global_load_lds_dwordx4 v[142:143], off
	s_mov_b32 m0, s20
	s_add_i32 s33, s20, 0x2000
	global_load_lds_dwordx4 v132, s[44:45]
	s_mov_b32 m0, s33
	s_nop 0
	global_load_lds_dwordx4 v136, s[44:45]
	s_mov_b32 m0, s67
	s_nop 0
	global_load_lds_dwordx4 v130, s[42:43]
	s_mov_b32 m0, s72
	s_nop 0
	global_load_lds_dwordx4 v134, s[42:43]
	s_waitcnt vmcnt(8)
	s_waitcnt lgkmcnt(0)
	s_barrier
	s_setprio 0
	s_waitcnt lgkmcnt(0)
	v_mfma_f32_16x16x32_bf16 v[142:145], v[0:3], v[60:63], 0
	v_mfma_f32_16x16x32_bf16 v[150:153], v[0:3], v[106:109], 0
	v_mfma_f32_16x16x32_bf16 v[158:161], v[0:3], v[114:117], 0
	v_mfma_f32_16x16x32_bf16 v[0:3], v[0:3], v[122:125], 0
	v_mfma_f32_16x16x32_bf16 v[142:145], v[4:7], v[102:105], v[142:145]
	v_mfma_f32_16x16x32_bf16 v[150:153], v[4:7], v[110:113], v[150:153]
	v_mfma_f32_16x16x32_bf16 v[158:161], v[4:7], v[118:121], v[158:161]
	v_mfma_f32_16x16x32_bf16 v[0:3], v[4:7], v[126:129], v[0:3]
	v_mfma_f32_16x16x32_bf16 v[4:7], v[8:11], v[122:125], 0
	v_mfma_f32_16x16x32_bf16 v[146:149], v[8:11], v[60:63], 0
	v_mfma_f32_16x16x32_bf16 v[154:157], v[8:11], v[106:109], 0
	v_mfma_f32_16x16x32_bf16 v[162:165], v[8:11], v[114:117], 0
	v_mfma_f32_16x16x32_bf16 v[4:7], v[12:15], v[126:129], v[4:7]
	v_mfma_f32_16x16x32_bf16 v[146:149], v[12:15], v[102:105], v[146:149]
	v_mfma_f32_16x16x32_bf16 v[154:157], v[12:15], v[110:113], v[154:157]
	v_mfma_f32_16x16x32_bf16 v[162:165], v[12:15], v[118:121], v[162:165]
	v_mfma_f32_16x16x32_bf16 v[8:11], v[16:19], v[60:63], 0
	v_mfma_f32_16x16x32_bf16 v[12:15], v[24:27], v[60:63], 0
	v_mfma_f32_16x16x32_bf16 v[8:11], v[20:23], v[102:105], v[8:11]
	v_mfma_f32_16x16x32_bf16 v[12:15], v[28:31], v[102:105], v[12:15]
	v_mfma_f32_16x16x32_bf16 v[60:63], v[16:19], v[106:109], 0
	v_mfma_f32_16x16x32_bf16 v[102:105], v[24:27], v[106:109], 0
	v_mfma_f32_16x16x32_bf16 v[106:109], v[16:19], v[114:117], 0
	v_mfma_f32_16x16x32_bf16 v[16:19], v[16:19], v[122:125], 0
	v_mfma_f32_16x16x32_bf16 v[60:63], v[20:23], v[110:113], v[60:63]
	v_mfma_f32_16x16x32_bf16 v[102:105], v[28:31], v[110:113], v[102:105]
	v_mfma_f32_16x16x32_bf16 v[106:109], v[20:23], v[118:121], v[106:109]
	v_mfma_f32_16x16x32_bf16 v[110:113], v[24:27], v[114:117], 0
	v_mfma_f32_16x16x32_bf16 v[16:19], v[20:23], v[126:129], v[16:19]
	v_mfma_f32_16x16x32_bf16 v[20:23], v[24:27], v[122:125], 0
	v_mfma_f32_16x16x32_bf16 v[110:113], v[28:31], v[118:121], v[110:113]
	v_mfma_f32_16x16x32_bf16 v[20:23], v[28:31], v[126:129], v[20:23]
	s_setprio 1
	s_barrier
	s_add_i32 s61, 0, 0x18000
	s_add_i32 s44, 0, 0x1c000
	v_add_u32_e32 v140, s61, v139
	v_add_u32_e32 v236, s44, v139
	ds_read_b128 v[24:27], v140
	ds_read_b128 v[28:31], v140 offset:1024
	ds_read_b128 v[114:117], v140 offset:2048
	ds_read_b128 v[118:121], v140 offset:3072
	ds_read_b128 v[122:125], v236
	ds_read_b128 v[126:129], v236 offset:1024
	ds_read_b128 v[166:169], v236 offset:2048
	ds_read_b128 v[170:173], v236 offset:3072
	s_add_u32 s42, s42, 0x10000
	s_addc_u32 s43, s43, 0
	s_mov_b32 m0, s73
	ds_read_b128 v[174:177], v141 offset:32768
	ds_read_b128 v[178:181], v141 offset:33792
	ds_read_b128 v[182:185], v141 offset:34816
	ds_read_b128 v[186:189], v141 offset:35840
	ds_read_b128 v[190:193], v141 offset:36864
	ds_read_b128 v[194:197], v141 offset:37888
	ds_read_b128 v[198:201], v141 offset:38912
	ds_read_b128 v[202:205], v141 offset:39936
	global_load_lds_dwordx4 v130, s[42:43]
	s_mov_b32 m0, s74
	s_nop 0
	global_load_lds_dwordx4 v134, s[42:43]
	s_waitcnt vmcnt(8)
	s_waitcnt lgkmcnt(0)
	s_barrier
	s_setprio 0
	s_waitcnt lgkmcnt(0)
	v_mfma_f32_16x16x32_bf16 v[64:67], v[24:27], v[174:177], v[64:67]
	v_mfma_f32_16x16x32_bf16 v[68:71], v[114:117], v[174:177], v[68:71]
	v_mfma_f32_16x16x32_bf16 v[72:75], v[24:27], v[182:185], v[72:75]
	v_mfma_f32_16x16x32_bf16 v[76:79], v[114:117], v[182:185], v[76:79]
	v_mfma_f32_16x16x32_bf16 v[80:83], v[24:27], v[190:193], v[80:83]
	v_mfma_f32_16x16x32_bf16 v[84:87], v[114:117], v[190:193], v[84:87]
	v_mfma_f32_16x16x32_bf16 v[88:91], v[24:27], v[198:201], v[88:91]
	v_mfma_f32_16x16x32_bf16 v[92:95], v[114:117], v[198:201], v[92:95]
	v_mfma_f32_16x16x32_bf16 v[64:67], v[28:31], v[178:181], v[64:67]
	v_mfma_f32_16x16x32_bf16 v[68:71], v[118:121], v[178:181], v[68:71]
	v_mfma_f32_16x16x32_bf16 v[72:75], v[28:31], v[186:189], v[72:75]
	v_mfma_f32_16x16x32_bf16 v[76:79], v[118:121], v[186:189], v[76:79]
	v_mfma_f32_16x16x32_bf16 v[80:83], v[28:31], v[194:197], v[80:83]
	v_mfma_f32_16x16x32_bf16 v[84:87], v[118:121], v[194:197], v[84:87]
	v_mfma_f32_16x16x32_bf16 v[88:91], v[28:31], v[202:205], v[88:91]
	v_mfma_f32_16x16x32_bf16 v[92:95], v[118:121], v[202:205], v[92:95]
	v_mfma_f32_16x16x32_bf16 v[98:101], v[122:125], v[174:177], v[98:101]
	v_mfma_f32_16x16x32_bf16 v[32:35], v[166:169], v[174:177], v[32:35]
	v_mfma_f32_16x16x32_bf16 v[36:39], v[122:125], v[182:185], v[36:39]
	v_mfma_f32_16x16x32_bf16 v[40:43], v[166:169], v[182:185], v[40:43]
	v_mfma_f32_16x16x32_bf16 v[44:47], v[122:125], v[190:193], v[44:47]
	v_mfma_f32_16x16x32_bf16 v[48:51], v[166:169], v[190:193], v[48:51]
	v_mfma_f32_16x16x32_bf16 v[52:55], v[122:125], v[198:201], v[52:55]
	v_mfma_f32_16x16x32_bf16 v[56:59], v[166:169], v[198:201], v[56:59]
	v_mfma_f32_16x16x32_bf16 v[98:101], v[126:129], v[178:181], v[98:101]
	v_mfma_f32_16x16x32_bf16 v[32:35], v[170:173], v[178:181], v[32:35]
	v_mfma_f32_16x16x32_bf16 v[36:39], v[126:129], v[186:189], v[36:39]
	v_mfma_f32_16x16x32_bf16 v[40:43], v[170:173], v[186:189], v[40:43]
	v_mfma_f32_16x16x32_bf16 v[44:47], v[126:129], v[194:197], v[44:47]
	v_mfma_f32_16x16x32_bf16 v[48:51], v[170:173], v[194:197], v[48:51]
	v_mfma_f32_16x16x32_bf16 v[52:55], v[126:129], v[202:205], v[52:55]
	v_mfma_f32_16x16x32_bf16 v[56:59], v[170:173], v[202:205], v[56:59]
	s_setprio 1
	s_barrier
	s_add_i32 s61, s61, s46
	s_add_i32 s35, s61, 0x2000
	s_mov_b32 m0, s61
	s_add_u32 s42, s80, 0x10000
	ds_read_b128 v[174:177], v141 offset:49152
	ds_read_b128 v[178:181], v141 offset:50176
	ds_read_b128 v[182:185], v141 offset:51200
	ds_read_b128 v[186:189], v141 offset:52224
	ds_read_b128 v[190:193], v141 offset:53248
	ds_read_b128 v[194:197], v141 offset:54272
	ds_read_b128 v[198:201], v141 offset:55296
	ds_read_b128 v[202:205], v141 offset:56320
	global_load_lds_dwordx4 v132, s[80:81]
	s_mov_b32 m0, s35
	s_addc_u32 s43, s81, 0
	s_add_i32 s44, s44, s46
	global_load_lds_dwordx4 v136, s[80:81]
	s_mov_b32 m0, s44
	s_add_i32 s45, s44, 0x2000
	global_load_lds_dwordx4 v132, s[42:43]
	s_mov_b32 m0, s45
	s_nop 0
	global_load_lds_dwordx4 v136, s[42:43]
	s_mov_b32 m0, s85
	s_nop 0
	global_load_lds_dwordx4 v130, s[76:77]
	s_mov_b32 m0, s86
	s_nop 0
	global_load_lds_dwordx4 v134, s[76:77]
	s_waitcnt vmcnt(8)
	s_waitcnt lgkmcnt(0)
	s_barrier
	s_setprio 0
	s_waitcnt lgkmcnt(0)
	v_mfma_f32_16x16x32_bf16 v[0:3], v[24:27], v[198:201], v[0:3]
	v_mfma_f32_16x16x32_bf16 v[4:7], v[114:117], v[198:201], v[4:7]
	v_mfma_f32_16x16x32_bf16 v[142:145], v[24:27], v[174:177], v[142:145]
	v_mfma_f32_16x16x32_bf16 v[146:149], v[114:117], v[174:177], v[146:149]
	v_mfma_f32_16x16x32_bf16 v[150:153], v[24:27], v[182:185], v[150:153]
	v_mfma_f32_16x16x32_bf16 v[154:157], v[114:117], v[182:185], v[154:157]
	v_mfma_f32_16x16x32_bf16 v[158:161], v[24:27], v[190:193], v[158:161]
	v_mfma_f32_16x16x32_bf16 v[162:165], v[114:117], v[190:193], v[162:165]
	v_mfma_f32_16x16x32_bf16 v[0:3], v[28:31], v[202:205], v[0:3]
	v_mfma_f32_16x16x32_bf16 v[4:7], v[118:121], v[202:205], v[4:7]
	v_mfma_f32_16x16x32_bf16 v[142:145], v[28:31], v[178:181], v[142:145]
	v_mfma_f32_16x16x32_bf16 v[146:149], v[118:121], v[178:181], v[146:149]
	v_mfma_f32_16x16x32_bf16 v[150:153], v[28:31], v[186:189], v[150:153]
	v_mfma_f32_16x16x32_bf16 v[154:157], v[118:121], v[186:189], v[154:157]
	v_mfma_f32_16x16x32_bf16 v[158:161], v[28:31], v[194:197], v[158:161]
	v_mfma_f32_16x16x32_bf16 v[162:165], v[118:121], v[194:197], v[162:165]
	v_mfma_f32_16x16x32_bf16 v[8:11], v[122:125], v[174:177], v[8:11]
	v_mfma_f32_16x16x32_bf16 v[12:15], v[166:169], v[174:177], v[12:15]
	v_mfma_f32_16x16x32_bf16 v[24:27], v[122:125], v[182:185], v[60:63]
	v_mfma_f32_16x16x32_bf16 v[28:31], v[166:169], v[182:185], v[102:105]
	v_mfma_f32_16x16x32_bf16 v[60:63], v[122:125], v[190:193], v[106:109]
	v_mfma_f32_16x16x32_bf16 v[102:105], v[166:169], v[190:193], v[110:113]
	v_mfma_f32_16x16x32_bf16 v[16:19], v[122:125], v[198:201], v[16:19]
	v_mfma_f32_16x16x32_bf16 v[20:23], v[166:169], v[198:201], v[20:23]
	v_mfma_f32_16x16x32_bf16 v[8:11], v[126:129], v[178:181], v[8:11]
	v_mfma_f32_16x16x32_bf16 v[12:15], v[170:173], v[178:181], v[12:15]
	v_mfma_f32_16x16x32_bf16 v[24:27], v[126:129], v[186:189], v[24:27]
	v_mfma_f32_16x16x32_bf16 v[28:31], v[170:173], v[186:189], v[28:31]
	v_mfma_f32_16x16x32_bf16 v[60:63], v[126:129], v[194:197], v[60:63]
	v_mfma_f32_16x16x32_bf16 v[102:105], v[170:173], v[194:197], v[102:105]
	v_mfma_f32_16x16x32_bf16 v[16:19], v[126:129], v[202:205], v[16:19]
	v_mfma_f32_16x16x32_bf16 v[20:23], v[170:173], v[202:205], v[20:23]
	s_setprio 1
	s_barrier
	s_add_u32 s76, s38, 0x80
	s_addc_u32 s77, s39, 0
	s_add_u32 s42, s68, 0x80
	s_addc_u32 s43, s69, 0
	ds_read_b128 v[106:109], v96
	ds_read_b128 v[110:113], v96 offset:1024
	ds_read_b128 v[114:117], v96 offset:2048
	ds_read_b128 v[118:121], v96 offset:3072
	ds_read_b128 v[122:125], v138
	ds_read_b128 v[126:129], v138 offset:1024
	ds_read_b128 v[166:169], v138 offset:2048
	ds_read_b128 v[170:173], v138 offset:3072
	s_add_u32 s78, s78, 0x10000
	s_addc_u32 s79, s79, 0
	s_mov_b32 m0, s59
	ds_read_b128 v[174:177], v141
	ds_read_b128 v[178:181], v141 offset:1024
	ds_read_b128 v[182:185], v141 offset:2048
	ds_read_b128 v[186:189], v141 offset:3072
	ds_read_b128 v[190:193], v141 offset:4096
	ds_read_b128 v[194:197], v141 offset:5120
	ds_read_b128 v[198:201], v141 offset:6144
	ds_read_b128 v[202:205], v141 offset:7168
	global_load_lds_dwordx4 v130, s[78:79]
	s_mov_b32 m0, s18
	s_nop 0
	global_load_lds_dwordx4 v134, s[78:79]
	s_waitcnt vmcnt(8)
	s_waitcnt lgkmcnt(0)
	s_barrier
	s_setprio 0
	s_waitcnt lgkmcnt(0)
	v_mfma_f32_16x16x32_bf16 v[88:91], v[106:109], v[198:201], v[88:91]
	v_mfma_f32_16x16x32_bf16 v[64:67], v[106:109], v[174:177], v[64:67]
	v_mfma_f32_16x16x32_bf16 v[68:71], v[114:117], v[174:177], v[68:71]
	v_mfma_f32_16x16x32_bf16 v[72:75], v[106:109], v[182:185], v[72:75]
	v_mfma_f32_16x16x32_bf16 v[76:79], v[114:117], v[182:185], v[76:79]
	v_mfma_f32_16x16x32_bf16 v[80:83], v[106:109], v[190:193], v[80:83]
	v_mfma_f32_16x16x32_bf16 v[84:87], v[114:117], v[190:193], v[84:87]
	v_mfma_f32_16x16x32_bf16 v[206:209], v[110:113], v[202:205], v[88:91]
	v_mfma_f32_16x16x32_bf16 v[88:91], v[114:117], v[198:201], v[92:95]
	v_mfma_f32_16x16x32_bf16 v[64:67], v[110:113], v[178:181], v[64:67]
	v_mfma_f32_16x16x32_bf16 v[68:71], v[118:121], v[178:181], v[68:71]
	v_mfma_f32_16x16x32_bf16 v[72:75], v[110:113], v[186:189], v[72:75]
	v_mfma_f32_16x16x32_bf16 v[76:79], v[118:121], v[186:189], v[76:79]
	v_mfma_f32_16x16x32_bf16 v[80:83], v[110:113], v[194:197], v[80:83]
	v_mfma_f32_16x16x32_bf16 v[84:87], v[118:121], v[194:197], v[84:87]
	v_mfma_f32_16x16x32_bf16 v[92:95], v[118:121], v[202:205], v[88:91]
	v_mfma_f32_16x16x32_bf16 v[44:47], v[122:125], v[190:193], v[44:47]
	v_mfma_f32_16x16x32_bf16 v[88:91], v[122:125], v[174:177], v[98:101]
	v_mfma_f32_16x16x32_bf16 v[32:35], v[166:169], v[174:177], v[32:35]
	v_mfma_f32_16x16x32_bf16 v[174:177], v[126:129], v[194:197], v[44:47]
	v_mfma_f32_16x16x32_bf16 v[44:47], v[166:169], v[190:193], v[48:51]
	v_mfma_f32_16x16x32_bf16 v[36:39], v[122:125], v[182:185], v[36:39]
	v_mfma_f32_16x16x32_bf16 v[40:43], v[166:169], v[182:185], v[40:43]
	v_mfma_f32_16x16x32_bf16 v[48:51], v[170:173], v[194:197], v[44:47]
	v_mfma_f32_16x16x32_bf16 v[44:47], v[122:125], v[198:201], v[52:55]
	v_mfma_f32_16x16x32_bf16 v[210:213], v[126:129], v[178:181], v[88:91]
	v_mfma_f32_16x16x32_bf16 v[32:35], v[170:173], v[178:181], v[32:35]
	v_mfma_f32_16x16x32_bf16 v[36:39], v[126:129], v[186:189], v[36:39]
	v_mfma_f32_16x16x32_bf16 v[40:43], v[170:173], v[186:189], v[40:43]
	v_mfma_f32_16x16x32_bf16 v[178:181], v[126:129], v[202:205], v[44:47]
	v_mfma_f32_16x16x32_bf16 v[44:47], v[166:169], v[198:201], v[56:59]
	v_mfma_f32_16x16x32_bf16 v[182:185], v[170:173], v[202:205], v[44:47]
	s_setprio 1
	s_barrier
	s_mov_b32 m0, s49
	s_add_u32 s18, s68, 0x10000
	s_nop 1
	ds_read_b128 v[44:47], v141 offset:16384
	ds_read_b128 v[52:55], v141 offset:17408
	ds_read_b128 v[56:59], v141 offset:18432
	ds_read_b128 v[88:91], v141 offset:19456
	ds_read_b128 v[98:101], v141 offset:20480
	ds_read_b128 v[186:189], v141 offset:21504
	ds_read_b128 v[190:193], v141 offset:22528
	ds_read_b128 v[194:197], v141 offset:23552
	global_load_lds_dwordx4 v132, s[68:69]
	s_mov_b32 m0, s19
	s_addc_u32 s19, s69, 0
	global_load_lds_dwordx4 v136, s[68:69]
	s_mov_b32 m0, s20
	s_nop 0
	global_load_lds_dwordx4 v132, s[18:19]
	s_mov_b32 m0, s33
	s_nop 0
	global_load_lds_dwordx4 v136, s[18:19]
	s_mov_b32 m0, s67
	s_nop 0
	global_load_lds_dwordx4 v130, s[38:39]
	s_mov_b32 m0, s72
	s_nop 0
	global_load_lds_dwordx4 v134, s[38:39]
	s_waitcnt vmcnt(8)
	s_waitcnt lgkmcnt(0)
	s_barrier
	s_setprio 0
	s_waitcnt lgkmcnt(0)
	v_mfma_f32_16x16x32_bf16 v[0:3], v[106:109], v[190:193], v[0:3]
	v_mfma_f32_16x16x32_bf16 v[4:7], v[114:117], v[190:193], v[4:7]
	v_mfma_f32_16x16x32_bf16 v[142:145], v[106:109], v[44:47], v[142:145]
	v_mfma_f32_16x16x32_bf16 v[146:149], v[114:117], v[44:47], v[146:149]
	v_mfma_f32_16x16x32_bf16 v[150:153], v[106:109], v[56:59], v[150:153]
	v_mfma_f32_16x16x32_bf16 v[154:157], v[114:117], v[56:59], v[154:157]
	v_mfma_f32_16x16x32_bf16 v[158:161], v[106:109], v[98:101], v[158:161]
	v_mfma_f32_16x16x32_bf16 v[162:165], v[114:117], v[98:101], v[162:165]
	v_mfma_f32_16x16x32_bf16 v[0:3], v[110:113], v[194:197], v[0:3]
	v_mfma_f32_16x16x32_bf16 v[4:7], v[118:121], v[194:197], v[4:7]
	v_mfma_f32_16x16x32_bf16 v[142:145], v[110:113], v[52:55], v[142:145]
	v_mfma_f32_16x16x32_bf16 v[146:149], v[118:121], v[52:55], v[146:149]
	v_mfma_f32_16x16x32_bf16 v[150:153], v[110:113], v[88:91], v[150:153]
	v_mfma_f32_16x16x32_bf16 v[154:157], v[118:121], v[88:91], v[154:157]
	v_mfma_f32_16x16x32_bf16 v[158:161], v[110:113], v[186:189], v[158:161]
	v_mfma_f32_16x16x32_bf16 v[162:165], v[118:121], v[186:189], v[162:165]
	v_mfma_f32_16x16x32_bf16 v[28:31], v[166:169], v[56:59], v[28:31]
	v_mfma_f32_16x16x32_bf16 v[8:11], v[122:125], v[44:47], v[8:11]
	v_mfma_f32_16x16x32_bf16 v[12:15], v[166:169], v[44:47], v[12:15]
	v_mfma_f32_16x16x32_bf16 v[24:27], v[122:125], v[56:59], v[24:27]
	v_mfma_f32_16x16x32_bf16 v[198:201], v[170:173], v[88:91], v[28:31]
	v_mfma_f32_16x16x32_bf16 v[28:31], v[122:125], v[98:101], v[60:63]
	v_mfma_f32_16x16x32_bf16 v[16:19], v[122:125], v[190:193], v[16:19]
	v_mfma_f32_16x16x32_bf16 v[8:11], v[126:129], v[52:55], v[8:11]
	v_mfma_f32_16x16x32_bf16 v[12:15], v[170:173], v[52:55], v[12:15]
	v_mfma_f32_16x16x32_bf16 v[24:27], v[126:129], v[88:91], v[24:27]
	v_mfma_f32_16x16x32_bf16 v[202:205], v[126:129], v[186:189], v[28:31]
	v_mfma_f32_16x16x32_bf16 v[28:31], v[166:169], v[98:101], v[102:105]
	v_mfma_f32_16x16x32_bf16 v[16:19], v[126:129], v[194:197], v[16:19]
	v_mfma_f32_16x16x32_bf16 v[20:23], v[166:169], v[190:193], v[20:23]
	v_mfma_f32_16x16x32_bf16 v[186:189], v[170:173], v[186:189], v[28:31]
	v_mfma_f32_16x16x32_bf16 v[166:169], v[170:173], v[194:197], v[20:23]
	s_setprio 1
	s_barrier
	ds_read_b128 v[170:173], v140
	ds_read_b128 v[190:193], v140 offset:1024
	ds_read_b128 v[194:197], v140 offset:2048
	ds_read_b128 v[220:223], v140 offset:3072
	ds_read_b128 v[224:227], v236
	ds_read_b128 v[228:231], v236 offset:1024
	ds_read_b128 v[232:235], v236 offset:2048
	ds_read_b128 v[236:239], v236 offset:3072
	s_add_u32 s18, s38, 0x10000
	s_addc_u32 s19, s39, 0
	s_mov_b32 m0, s73
	ds_read_b128 v[20:23], v141 offset:32768
	ds_read_b128 v[28:31], v141 offset:33792
	ds_read_b128 v[52:55], v141 offset:34816
	ds_read_b128 v[102:105], v141 offset:35840
	ds_read_b128 v[110:113], v141 offset:36864
	ds_read_b128 v[118:121], v141 offset:37888
	ds_read_b128 v[240:243], v141 offset:38912
	ds_read_b128 v[244:247], v141 offset:39936
	global_load_lds_dwordx4 v130, s[18:19]
	s_mov_b32 m0, s74
	s_nop 0
	global_load_lds_dwordx4 v134, s[18:19]
	s_waitcnt vmcnt(8)
	s_waitcnt lgkmcnt(0)
	s_barrier
	s_setprio 0
	s_waitcnt lgkmcnt(0)
	v_mfma_f32_16x16x32_bf16 v[44:47], v[170:173], v[20:23], v[64:67]
	v_mfma_f32_16x16x32_bf16 v[126:129], v[190:193], v[28:31], v[44:47]
	v_mfma_f32_16x16x32_bf16 v[44:47], v[194:197], v[20:23], v[68:71]
	v_mfma_f32_16x16x32_bf16 v[122:125], v[220:223], v[28:31], v[44:47]
	v_mfma_f32_16x16x32_bf16 v[44:47], v[170:173], v[52:55], v[72:75]
	v_mfma_f32_16x16x32_bf16 v[114:117], v[190:193], v[102:105], v[44:47]
	v_mfma_f32_16x16x32_bf16 v[44:47], v[194:197], v[52:55], v[76:79]
	v_mfma_f32_16x16x32_bf16 v[106:109], v[220:223], v[102:105], v[44:47]
	v_mfma_f32_16x16x32_bf16 v[44:47], v[170:173], v[110:113], v[80:83]
	v_mfma_f32_16x16x32_bf16 v[98:101], v[190:193], v[118:121], v[44:47]
	v_mfma_f32_16x16x32_bf16 v[44:47], v[194:197], v[110:113], v[84:87]
	v_mfma_f32_16x16x32_bf16 v[88:91], v[220:223], v[118:121], v[44:47]
	v_mfma_f32_16x16x32_bf16 v[44:47], v[170:173], v[240:243], v[206:209]
	v_mfma_f32_16x16x32_bf16 v[80:83], v[190:193], v[244:247], v[44:47]
	v_mfma_f32_16x16x32_bf16 v[44:47], v[194:197], v[240:243], v[92:95]
	v_mfma_f32_16x16x32_bf16 v[72:75], v[220:223], v[244:247], v[44:47]
	v_mfma_f32_16x16x32_bf16 v[44:47], v[224:227], v[20:23], v[210:213]
	v_mfma_f32_16x16x32_bf16 v[20:23], v[232:235], v[20:23], v[32:35]
	v_mfma_f32_16x16x32_bf16 v[60:63], v[228:231], v[28:31], v[44:47]
	v_mfma_f32_16x16x32_bf16 v[44:47], v[236:239], v[28:31], v[20:23]
	v_mfma_f32_16x16x32_bf16 v[20:23], v[224:227], v[52:55], v[36:39]
	v_mfma_f32_16x16x32_bf16 v[56:59], v[228:231], v[102:105], v[20:23]
	v_mfma_f32_16x16x32_bf16 v[20:23], v[232:235], v[52:55], v[40:43]
	v_mfma_f32_16x16x32_bf16 v[36:39], v[236:239], v[102:105], v[20:23]
	v_mfma_f32_16x16x32_bf16 v[20:23], v[224:227], v[110:113], v[174:177]
	v_mfma_f32_16x16x32_bf16 v[52:55], v[228:231], v[118:121], v[20:23]
	v_mfma_f32_16x16x32_bf16 v[20:23], v[232:235], v[110:113], v[48:51]
	v_mfma_f32_16x16x32_bf16 v[28:31], v[236:239], v[118:121], v[20:23]
	v_mfma_f32_16x16x32_bf16 v[20:23], v[224:227], v[240:243], v[178:181]
	v_mfma_f32_16x16x32_bf16 v[48:51], v[228:231], v[244:247], v[20:23]
	v_mfma_f32_16x16x32_bf16 v[20:23], v[232:235], v[240:243], v[182:185]
	v_mfma_f32_16x16x32_bf16 v[20:23], v[236:239], v[244:247], v[20:23]
	s_setprio 1
	s_barrier
	s_mov_b32 m0, s61
	s_add_u32 s18, s42, 0x10000
	ds_read_b128 v[32:35], v141 offset:49152
	ds_read_b128 v[174:177], v141 offset:50176
	ds_read_b128 v[178:181], v141 offset:51200
	ds_read_b128 v[182:185], v141 offset:52224
	ds_read_b128 v[206:209], v141 offset:53248
	ds_read_b128 v[210:213], v141 offset:54272
	ds_read_b128 v[240:243], v141 offset:55296
	ds_read_b128 v[244:247], v141 offset:56320
	global_load_lds_dwordx4 v132, s[42:43]
	s_mov_b32 m0, s35
	s_addc_u32 s19, s43, 0
	global_load_lds_dwordx4 v136, s[42:43]
	s_mov_b32 m0, s44
	s_nop 0
	global_load_lds_dwordx4 v132, s[18:19]
	s_mov_b32 m0, s45
	s_nop 0
	global_load_lds_dwordx4 v136, s[18:19]
	s_mov_b32 m0, s85
	s_nop 0
	global_load_lds_dwordx4 v130, s[76:77]
	s_mov_b32 m0, s86
	s_nop 0
	global_load_lds_dwordx4 v134, s[76:77]
	s_waitcnt vmcnt(8)
	s_waitcnt lgkmcnt(0)
	s_barrier
	s_setprio 0
	s_waitcnt lgkmcnt(0)
	v_mfma_f32_16x16x32_bf16 v[40:43], v[170:173], v[32:35], v[142:145]
	v_mfma_f32_16x16x32_bf16 v[118:121], v[190:193], v[174:177], v[40:43]
	v_mfma_f32_16x16x32_bf16 v[40:43], v[194:197], v[32:35], v[146:149]
	v_mfma_f32_16x16x32_bf16 v[110:113], v[220:223], v[174:177], v[40:43]
	v_mfma_f32_16x16x32_bf16 v[40:43], v[170:173], v[178:181], v[150:153]
	v_mfma_f32_16x16x32_bf16 v[102:105], v[190:193], v[182:185], v[40:43]
	v_mfma_f32_16x16x32_bf16 v[40:43], v[194:197], v[178:181], v[154:157]
	v_mfma_f32_16x16x32_bf16 v[92:95], v[220:223], v[182:185], v[40:43]
	v_mfma_f32_16x16x32_bf16 v[40:43], v[170:173], v[206:209], v[158:161]
	v_mfma_f32_16x16x32_bf16 v[0:3], v[170:173], v[240:243], v[0:3]
	v_mfma_f32_16x16x32_bf16 v[84:87], v[190:193], v[210:213], v[40:43]
	v_mfma_f32_16x16x32_bf16 v[40:43], v[194:197], v[206:209], v[162:165]
	v_mfma_f32_16x16x32_bf16 v[68:71], v[190:193], v[244:247], v[0:3]
	v_mfma_f32_16x16x32_bf16 v[0:3], v[194:197], v[240:243], v[4:7]
	v_mfma_f32_16x16x32_bf16 v[76:79], v[220:223], v[210:213], v[40:43]
	v_mfma_f32_16x16x32_bf16 v[64:67], v[220:223], v[244:247], v[0:3]
	v_mfma_f32_16x16x32_bf16 v[0:3], v[224:227], v[32:35], v[8:11]
	v_mfma_f32_16x16x32_bf16 v[40:43], v[228:231], v[174:177], v[0:3]
	v_mfma_f32_16x16x32_bf16 v[0:3], v[232:235], v[32:35], v[12:15]
	v_mfma_f32_16x16x32_bf16 v[12:15], v[236:239], v[174:177], v[0:3]
	v_mfma_f32_16x16x32_bf16 v[0:3], v[224:227], v[178:181], v[24:27]
	v_mfma_f32_16x16x32_bf16 v[32:35], v[228:231], v[182:185], v[0:3]
	v_mfma_f32_16x16x32_bf16 v[0:3], v[232:235], v[178:181], v[198:201]
	v_mfma_f32_16x16x32_bf16 v[8:11], v[236:239], v[182:185], v[0:3]
	v_mfma_f32_16x16x32_bf16 v[0:3], v[224:227], v[206:209], v[202:205]
	v_mfma_f32_16x16x32_bf16 v[24:27], v[228:231], v[210:213], v[0:3]
	v_mfma_f32_16x16x32_bf16 v[0:3], v[232:235], v[206:209], v[186:189]
	v_mfma_f32_16x16x32_bf16 v[4:7], v[236:239], v[210:213], v[0:3]
	v_mfma_f32_16x16x32_bf16 v[0:3], v[224:227], v[240:243], v[16:19]
	v_mfma_f32_16x16x32_bf16 v[16:19], v[228:231], v[244:247], v[0:3]
	v_mfma_f32_16x16x32_bf16 v[0:3], v[232:235], v[240:243], v[166:169]
	v_mfma_f32_16x16x32_bf16 v[0:3], v[236:239], v[244:247], v[0:3]
	s_setprio 1
	s_barrier
	s_andn2_b64 vcc, exec, s[10:11]
	s_cbranch_vccnz .LBB0_411
	s_barrier

.LBB0_433:
	s_add_u32 s18, s10, 0x80
	s_addc_u32 s19, s11, 0
	s_add_u32 s10, s10, 0x100
	s_addc_u32 s11, s11, 0
	s_cmp_eq_u32 s92, 12
	s_cselect_b32 s42, s87, s10
	s_cselect_b32 s43, s9, s11
	s_cselect_b32 s45, s85, s94
	s_cselect_b32 s44, vcc_lo, vcc_hi
	s_add_u32 s38, s42, 0x80
	s_addc_u32 s39, s43, 0
	s_add_u32 s68, s44, 0x80
	s_addc_u32 s69, s45, 0
	s_add_i32 s35, 0, 0x10000
	s_add_i32 s49, 0, 0x14000
	v_add_u32_e32 v96, s35, v199
	v_add_u32_e32 v166, s49, v199
	ds_read_b128 v[138:141], v96
	ds_read_b128 v[142:145], v96 offset:1024
	ds_read_b128 v[146:149], v96 offset:2048
	ds_read_b128 v[150:153], v96 offset:3072
	s_waitcnt lgkmcnt(0)
	ds_read_b128 v[154:157], v166
	ds_read_b128 v[158:161], v166 offset:1024
	ds_read_b128 v[162:165], v166 offset:2048
	ds_read_b128 v[166:169], v166 offset:3072
	s_mov_b32 m0, s29
	ds_read_b128 v[170:173], v200
	ds_read_b128 v[174:177], v200 offset:1024
	ds_read_b128 v[178:181], v200 offset:2048
	ds_read_b128 v[182:185], v200 offset:3072
	ds_read_b128 v[190:193], v200 offset:4096
	ds_read_b128 v[194:197], v200 offset:5120
	ds_read_b128 v[202:205], v200 offset:6144
	ds_read_b128 v[206:209], v200 offset:7168
	global_load_lds_dwordx4 v130, s[18:19]
	s_mov_b32 m0, s16
	s_nop 0
	global_load_lds_dwordx4 v134, s[18:19]
	s_add_u32 s18, s18, 0x40000
	s_addc_u32 s19, s19, 0
	s_add_i32 m0, s73, 0xc000
	s_nop 0
	global_load_lds_dwordx4 v130, s[18:19]
	s_add_i32 m0, s73, 0xe000
	s_nop 0
	global_load_lds_dwordx4 v134, s[18:19]
	s_waitcnt vmcnt(8)
	s_waitcnt lgkmcnt(0)
	s_barrier
	s_setprio 0
	s_waitcnt lgkmcnt(0)
	v_mfma_f32_16x16x32_bf16 v[126:129], v[138:141], v[170:173], v[126:129]
	v_mfma_f32_16x16x32_bf16 v[122:125], v[146:149], v[170:173], v[122:125]
	v_mfma_f32_16x16x32_bf16 v[118:121], v[138:141], v[178:181], v[118:121]
	v_mfma_f32_16x16x32_bf16 v[110:113], v[146:149], v[178:181], v[110:113]
	v_mfma_f32_16x16x32_bf16 v[102:105], v[138:141], v[190:193], v[102:105]
	v_mfma_f32_16x16x32_bf16 v[92:95], v[146:149], v[190:193], v[92:95]
	v_mfma_f32_16x16x32_bf16 v[84:87], v[138:141], v[202:205], v[84:87]
	v_mfma_f32_16x16x32_bf16 v[76:79], v[146:149], v[202:205], v[76:79]
	v_mfma_f32_16x16x32_bf16 v[126:129], v[142:145], v[174:177], v[126:129]
	v_mfma_f32_16x16x32_bf16 v[122:125], v[150:153], v[174:177], v[122:125]
	v_mfma_f32_16x16x32_bf16 v[118:121], v[142:145], v[182:185], v[118:121]
	v_mfma_f32_16x16x32_bf16 v[110:113], v[150:153], v[182:185], v[110:113]
	v_mfma_f32_16x16x32_bf16 v[102:105], v[142:145], v[194:197], v[102:105]
	v_mfma_f32_16x16x32_bf16 v[92:95], v[150:153], v[194:197], v[92:95]
	v_mfma_f32_16x16x32_bf16 v[84:87], v[142:145], v[206:209], v[84:87]
	v_mfma_f32_16x16x32_bf16 v[76:79], v[150:153], v[206:209], v[76:79]
	v_mfma_f32_16x16x32_bf16 v[114:117], v[154:157], v[170:173], v[114:117]
	v_mfma_f32_16x16x32_bf16 v[106:109], v[162:165], v[170:173], v[106:109]
	v_mfma_f32_16x16x32_bf16 v[98:101], v[154:157], v[178:181], v[98:101]
	v_mfma_f32_16x16x32_bf16 v[88:91], v[162:165], v[178:181], v[88:91]
	v_mfma_f32_16x16x32_bf16 v[80:83], v[154:157], v[190:193], v[80:83]
	v_mfma_f32_16x16x32_bf16 v[72:75], v[162:165], v[190:193], v[72:75]
	v_mfma_f32_16x16x32_bf16 v[68:71], v[154:157], v[202:205], v[68:71]
	v_mfma_f32_16x16x32_bf16 v[64:67], v[162:165], v[202:205], v[64:67]
	v_mfma_f32_16x16x32_bf16 v[114:117], v[158:161], v[174:177], v[114:117]
	v_mfma_f32_16x16x32_bf16 v[106:109], v[166:169], v[174:177], v[106:109]
	v_mfma_f32_16x16x32_bf16 v[98:101], v[158:161], v[182:185], v[98:101]
	v_mfma_f32_16x16x32_bf16 v[88:91], v[166:169], v[182:185], v[88:91]
	v_mfma_f32_16x16x32_bf16 v[80:83], v[158:161], v[194:197], v[80:83]
	v_mfma_f32_16x16x32_bf16 v[72:75], v[166:169], v[194:197], v[72:75]
	v_mfma_f32_16x16x32_bf16 v[68:71], v[158:161], v[206:209], v[68:71]
	v_mfma_f32_16x16x32_bf16 v[64:67], v[166:169], v[206:209], v[64:67]
	s_setprio 1
	s_barrier
	s_add_i32 s18, s35, s72
	s_mov_b32 m0, s18
	ds_read_b128 v[170:173], v200 offset:16384
	ds_read_b128 v[174:177], v200 offset:17408
	ds_read_b128 v[178:181], v200 offset:18432
	ds_read_b128 v[182:185], v200 offset:19456
	ds_read_b128 v[190:193], v200 offset:20480
	ds_read_b128 v[194:197], v200 offset:21504
	ds_read_b128 v[202:205], v200 offset:22528
	ds_read_b128 v[206:209], v200 offset:23552
	global_load_lds_dwordx4 v132, s[44:45]
	s_add_i32 m0, s18, 0x2000
	s_add_u32 s18, s44, 0x40000
	s_addc_u32 s19, s45, 0
	s_add_i32 s35, s49, s72
	global_load_lds_dwordx4 v136, s[44:45]
	s_mov_b32 m0, s35
	s_nop 0
	global_load_lds_dwordx4 v132, s[18:19]
	s_add_i32 m0, s35, 0x2000
	s_nop 0
	global_load_lds_dwordx4 v136, s[18:19]
	s_waitcnt vmcnt(6)
	s_waitcnt lgkmcnt(0)
	s_barrier
	s_setprio 0
	s_waitcnt lgkmcnt(0)
	v_mfma_f32_16x16x32_bf16 v[60:63], v[138:141], v[170:173], v[60:63]
	v_mfma_f32_16x16x32_bf16 v[56:59], v[146:149], v[170:173], v[56:59]
	v_mfma_f32_16x16x32_bf16 v[52:55], v[138:141], v[178:181], v[52:55]
	v_mfma_f32_16x16x32_bf16 v[44:47], v[146:149], v[178:181], v[44:47]
	v_mfma_f32_16x16x32_bf16 v[36:39], v[138:141], v[190:193], v[36:39]
	v_mfma_f32_16x16x32_bf16 v[28:31], v[146:149], v[190:193], v[28:31]
	v_mfma_f32_16x16x32_bf16 v[20:23], v[138:141], v[202:205], v[20:23]
	v_mfma_f32_16x16x32_bf16 v[12:15], v[146:149], v[202:205], v[12:15]
	v_mfma_f32_16x16x32_bf16 v[60:63], v[142:145], v[174:177], v[60:63]
	v_mfma_f32_16x16x32_bf16 v[56:59], v[150:153], v[174:177], v[56:59]
	v_mfma_f32_16x16x32_bf16 v[52:55], v[142:145], v[182:185], v[52:55]
	v_mfma_f32_16x16x32_bf16 v[44:47], v[150:153], v[182:185], v[44:47]
	v_mfma_f32_16x16x32_bf16 v[36:39], v[142:145], v[194:197], v[36:39]
	v_mfma_f32_16x16x32_bf16 v[28:31], v[150:153], v[194:197], v[28:31]
	v_mfma_f32_16x16x32_bf16 v[20:23], v[142:145], v[206:209], v[20:23]
	v_mfma_f32_16x16x32_bf16 v[12:15], v[150:153], v[206:209], v[12:15]
	v_mfma_f32_16x16x32_bf16 v[48:51], v[154:157], v[170:173], v[48:51]
	v_mfma_f32_16x16x32_bf16 v[40:43], v[162:165], v[170:173], v[40:43]
	v_mfma_f32_16x16x32_bf16 v[32:35], v[154:157], v[178:181], v[32:35]
	v_mfma_f32_16x16x32_bf16 v[24:27], v[162:165], v[178:181], v[24:27]
	v_mfma_f32_16x16x32_bf16 v[16:19], v[154:157], v[190:193], v[16:19]
	v_mfma_f32_16x16x32_bf16 v[8:11], v[162:165], v[190:193], v[8:11]
	v_mfma_f32_16x16x32_bf16 v[4:7], v[154:157], v[202:205], v[4:7]
	v_mfma_f32_16x16x32_bf16 v[0:3], v[162:165], v[202:205], v[0:3]
	v_mfma_f32_16x16x32_bf16 v[48:51], v[158:161], v[174:177], v[48:51]
	v_mfma_f32_16x16x32_bf16 v[40:43], v[166:169], v[174:177], v[40:43]
	v_mfma_f32_16x16x32_bf16 v[32:35], v[158:161], v[182:185], v[32:35]
	v_mfma_f32_16x16x32_bf16 v[24:27], v[166:169], v[182:185], v[24:27]
	v_mfma_f32_16x16x32_bf16 v[16:19], v[158:161], v[194:197], v[16:19]
	v_mfma_f32_16x16x32_bf16 v[8:11], v[166:169], v[194:197], v[8:11]
	v_mfma_f32_16x16x32_bf16 v[4:7], v[158:161], v[206:209], v[4:7]
	v_mfma_f32_16x16x32_bf16 v[0:3], v[166:169], v[206:209], v[0:3]
	s_setprio 1
	s_barrier
	s_add_i32 s35, 0, 0x18000
	v_add_u32_e32 v96, s35, v199
	s_add_i32 s44, 0, 0x1c000
	ds_read_b128 v[138:141], v96
	ds_read_b128 v[142:145], v96 offset:1024
	ds_read_b128 v[146:149], v96 offset:2048
	ds_read_b128 v[150:153], v96 offset:3072
	v_add_u32_e32 v96, s44, v199
	ds_read_b128 v[154:157], v96
	ds_read_b128 v[158:161], v96 offset:1024
	ds_read_b128 v[162:165], v96 offset:2048
	ds_read_b128 v[166:169], v96 offset:3072
	s_mov_b32 m0, s73
	s_nop 0
	global_load_lds_dwordx4 v130, s[42:43]
	s_mov_b32 m0, s74
	s_nop 0
	global_load_lds_dwordx4 v134, s[42:43]
	s_add_u32 s18, s42, 0x40000
	s_addc_u32 s19, s43, 0
	s_mov_b32 m0, s75
	ds_read_b128 v[170:173], v200 offset:32768
	ds_read_b128 v[174:177], v200 offset:33792
	ds_read_b128 v[178:181], v200 offset:34816
	ds_read_b128 v[182:185], v200 offset:35840
	ds_read_b128 v[190:193], v200 offset:36864
	ds_read_b128 v[194:197], v200 offset:37888
	ds_read_b128 v[202:205], v200 offset:38912
	ds_read_b128 v[206:209], v200 offset:39936
	global_load_lds_dwordx4 v130, s[18:19]
	s_mov_b32 m0, s83
	s_nop 0
	global_load_lds_dwordx4 v134, s[18:19]
	s_waitcnt vmcnt(8)
	s_waitcnt lgkmcnt(0)
	s_barrier
	s_setprio 0
	s_waitcnt lgkmcnt(0)
	v_mfma_f32_16x16x32_bf16 v[126:129], v[138:141], v[170:173], v[126:129]
	v_mfma_f32_16x16x32_bf16 v[122:125], v[146:149], v[170:173], v[122:125]
	v_mfma_f32_16x16x32_bf16 v[118:121], v[138:141], v[178:181], v[118:121]
	v_mfma_f32_16x16x32_bf16 v[110:113], v[146:149], v[178:181], v[110:113]
	v_mfma_f32_16x16x32_bf16 v[102:105], v[138:141], v[190:193], v[102:105]
	v_mfma_f32_16x16x32_bf16 v[92:95], v[146:149], v[190:193], v[92:95]
	v_mfma_f32_16x16x32_bf16 v[84:87], v[138:141], v[202:205], v[84:87]
	v_mfma_f32_16x16x32_bf16 v[76:79], v[146:149], v[202:205], v[76:79]
	v_mfma_f32_16x16x32_bf16 v[126:129], v[142:145], v[174:177], v[126:129]
	v_mfma_f32_16x16x32_bf16 v[122:125], v[150:153], v[174:177], v[122:125]
	v_mfma_f32_16x16x32_bf16 v[118:121], v[142:145], v[182:185], v[118:121]
	v_mfma_f32_16x16x32_bf16 v[110:113], v[150:153], v[182:185], v[110:113]
	v_mfma_f32_16x16x32_bf16 v[102:105], v[142:145], v[194:197], v[102:105]
	v_mfma_f32_16x16x32_bf16 v[92:95], v[150:153], v[194:197], v[92:95]
	v_mfma_f32_16x16x32_bf16 v[84:87], v[142:145], v[206:209], v[84:87]
	v_mfma_f32_16x16x32_bf16 v[76:79], v[150:153], v[206:209], v[76:79]
	v_mfma_f32_16x16x32_bf16 v[114:117], v[154:157], v[170:173], v[114:117]
	v_mfma_f32_16x16x32_bf16 v[106:109], v[162:165], v[170:173], v[106:109]
	v_mfma_f32_16x16x32_bf16 v[98:101], v[154:157], v[178:181], v[98:101]
	v_mfma_f32_16x16x32_bf16 v[88:91], v[162:165], v[178:181], v[88:91]
	v_mfma_f32_16x16x32_bf16 v[80:83], v[154:157], v[190:193], v[80:83]
	v_mfma_f32_16x16x32_bf16 v[72:75], v[162:165], v[190:193], v[72:75]
	v_mfma_f32_16x16x32_bf16 v[68:71], v[154:157], v[202:205], v[68:71]
	v_mfma_f32_16x16x32_bf16 v[64:67], v[162:165], v[202:205], v[64:67]
	v_mfma_f32_16x16x32_bf16 v[114:117], v[158:161], v[174:177], v[114:117]
	v_mfma_f32_16x16x32_bf16 v[106:109], v[166:169], v[174:177], v[106:109]
	v_mfma_f32_16x16x32_bf16 v[98:101], v[158:161], v[182:185], v[98:101]
	v_mfma_f32_16x16x32_bf16 v[88:91], v[166:169], v[182:185], v[88:91]
	v_mfma_f32_16x16x32_bf16 v[80:83], v[158:161], v[194:197], v[80:83]
	v_mfma_f32_16x16x32_bf16 v[72:75], v[166:169], v[194:197], v[72:75]
	v_mfma_f32_16x16x32_bf16 v[68:71], v[158:161], v[206:209], v[68:71]
	v_mfma_f32_16x16x32_bf16 v[64:67], v[166:169], v[206:209], v[64:67]
	s_setprio 1
	s_barrier
	s_add_i32 s18, s35, s72
	s_mov_b32 m0, s18
	ds_read_b128 v[170:173], v200 offset:49152
	ds_read_b128 v[174:177], v200 offset:50176
	ds_read_b128 v[178:181], v200 offset:51200
	ds_read_b128 v[182:185], v200 offset:52224
	ds_read_b128 v[190:193], v200 offset:53248
	ds_read_b128 v[194:197], v200 offset:54272
	ds_read_b128 v[202:205], v200 offset:55296
	ds_read_b128 v[206:209], v200 offset:56320
	global_load_lds_dwordx4 v132, s[68:69]
	s_add_i32 m0, s18, 0x2000
	s_add_u32 s18, s68, 0x40000
	s_addc_u32 s19, s69, 0
	s_add_i32 s35, s44, s72
	global_load_lds_dwordx4 v136, s[68:69]
	s_mov_b32 m0, s35
	s_nop 0
	global_load_lds_dwordx4 v132, s[18:19]
	s_add_i32 m0, s35, 0x2000
	s_nop 0
	global_load_lds_dwordx4 v136, s[18:19]
	s_waitcnt vmcnt(6)
	s_waitcnt lgkmcnt(0)
	s_barrier
	s_setprio 0
	s_waitcnt lgkmcnt(0)
	v_mfma_f32_16x16x32_bf16 v[60:63], v[138:141], v[170:173], v[60:63]
	v_mfma_f32_16x16x32_bf16 v[56:59], v[146:149], v[170:173], v[56:59]
	v_mfma_f32_16x16x32_bf16 v[52:55], v[138:141], v[178:181], v[52:55]
	v_mfma_f32_16x16x32_bf16 v[44:47], v[146:149], v[178:181], v[44:47]
	v_mfma_f32_16x16x32_bf16 v[36:39], v[138:141], v[190:193], v[36:39]
	v_mfma_f32_16x16x32_bf16 v[28:31], v[146:149], v[190:193], v[28:31]
	v_mfma_f32_16x16x32_bf16 v[20:23], v[138:141], v[202:205], v[20:23]
	v_mfma_f32_16x16x32_bf16 v[12:15], v[146:149], v[202:205], v[12:15]
	v_mfma_f32_16x16x32_bf16 v[60:63], v[142:145], v[174:177], v[60:63]
	v_mfma_f32_16x16x32_bf16 v[56:59], v[150:153], v[174:177], v[56:59]
	v_mfma_f32_16x16x32_bf16 v[52:55], v[142:145], v[182:185], v[52:55]
	v_mfma_f32_16x16x32_bf16 v[44:47], v[150:153], v[182:185], v[44:47]
	v_mfma_f32_16x16x32_bf16 v[36:39], v[142:145], v[194:197], v[36:39]
	v_mfma_f32_16x16x32_bf16 v[28:31], v[150:153], v[194:197], v[28:31]
	v_mfma_f32_16x16x32_bf16 v[20:23], v[142:145], v[206:209], v[20:23]
	v_mfma_f32_16x16x32_bf16 v[12:15], v[150:153], v[206:209], v[12:15]
	v_mfma_f32_16x16x32_bf16 v[48:51], v[154:157], v[170:173], v[48:51]
	v_mfma_f32_16x16x32_bf16 v[40:43], v[162:165], v[170:173], v[40:43]
	v_mfma_f32_16x16x32_bf16 v[32:35], v[154:157], v[178:181], v[32:35]
	v_mfma_f32_16x16x32_bf16 v[24:27], v[162:165], v[178:181], v[24:27]
	v_mfma_f32_16x16x32_bf16 v[16:19], v[154:157], v[190:193], v[16:19]
	v_mfma_f32_16x16x32_bf16 v[8:11], v[162:165], v[190:193], v[8:11]
	v_mfma_f32_16x16x32_bf16 v[4:7], v[154:157], v[202:205], v[4:7]
	v_mfma_f32_16x16x32_bf16 v[0:3], v[162:165], v[202:205], v[0:3]
	v_mfma_f32_16x16x32_bf16 v[48:51], v[158:161], v[174:177], v[48:51]
	v_mfma_f32_16x16x32_bf16 v[40:43], v[166:169], v[174:177], v[40:43]
	v_mfma_f32_16x16x32_bf16 v[32:35], v[158:161], v[182:185], v[32:35]
	v_mfma_f32_16x16x32_bf16 v[24:27], v[166:169], v[182:185], v[24:27]
	v_mfma_f32_16x16x32_bf16 v[16:19], v[158:161], v[194:197], v[16:19]
	v_mfma_f32_16x16x32_bf16 v[8:11], v[166:169], v[194:197], v[8:11]
	v_mfma_f32_16x16x32_bf16 v[4:7], v[158:161], v[206:209], v[4:7]
	v_mfma_f32_16x16x32_bf16 v[0:3], v[166:169], v[206:209], v[0:3]
	s_setprio 1
	s_barrier
	s_add_i32 s92, s92, 2
	s_add_u32 vcc_hi, vcc_hi, 0x100
	s_addc_u32 s94, s94, 0
	s_cmp_gt_u32 s92, 13
	s_cbranch_scc0 .LBB0_433
	s_and_b64 vcc, exec, s[76:77]
	s_cbranch_vccz .LBB0_436
	s_barrier

.LBB0_703:
	s_cmp_eq_u32 s85, 40
	s_cselect_b32 s42, s8, s81
	s_cselect_b32 s43, s9, s82
	s_cselect_b32 s45, s59, s84
	s_cselect_b32 s44, s58, s83
	s_add_u32 s38, s42, 0x80
	s_addc_u32 s39, s43, 0
	s_add_u32 s62, s44, 0x80
	s_addc_u32 s63, s45, 0
	s_add_i32 s35, 0, 0x10000
	s_mov_b64 s[18:19], s[60:61]
	v_add_u32_e32 v140, s35, v142
	s_add_i32 s49, 0, 0x14000
	ds_read_b128 v[136:139], v140
	ds_read_b128 v[144:147], v140 offset:1024
	ds_read_b128 v[148:151], v140 offset:2048
	ds_read_b128 v[152:155], v140 offset:3072
	v_add_u32_e32 v140, s49, v142
	ds_read_b128 v[156:159], v140
	ds_read_b128 v[160:163], v140 offset:1024
	ds_read_b128 v[164:167], v140 offset:2048
	ds_read_b128 v[168:171], v140 offset:3072
	s_mov_b32 m0, s74
	ds_read_b128 v[172:175], v143
	ds_read_b128 v[176:179], v143 offset:1024
	ds_read_b128 v[180:183], v143 offset:2048
	ds_read_b128 v[190:193], v143 offset:3072
	ds_read_b128 v[194:197], v143 offset:4096
	ds_read_b128 v[198:201], v143 offset:5120
	ds_read_b128 v[202:205], v143 offset:6144
	ds_read_b128 v[206:209], v143 offset:7168
	global_load_lds_dwordx4 v130, s[18:19]
	s_mov_b32 m0, s75
	s_nop 0
	global_load_lds_dwordx4 v132, s[18:19]
	s_add_u32 s18, s18, 0xb0000
	s_addc_u32 s19, s19, 0
	s_add_i32 m0, s66, 0xc000
	s_nop 0
	global_load_lds_dwordx4 v130, s[18:19]
	s_add_i32 m0, s66, 0xe000
	s_nop 0
	global_load_lds_dwordx4 v132, s[18:19]
	s_waitcnt vmcnt(8)
	s_waitcnt lgkmcnt(0)
	s_barrier
	s_setprio 0
	s_waitcnt lgkmcnt(0)
	v_mfma_f32_16x16x32_bf16 v[126:129], v[136:139], v[172:175], v[126:129]
	v_mfma_f32_16x16x32_bf16 v[122:125], v[148:151], v[172:175], v[122:125]
	v_mfma_f32_16x16x32_bf16 v[110:113], v[136:139], v[180:183], v[110:113]
	v_mfma_f32_16x16x32_bf16 v[106:109], v[148:151], v[180:183], v[106:109]
	v_mfma_f32_16x16x32_bf16 v[92:95], v[136:139], v[194:197], v[92:95]
	v_mfma_f32_16x16x32_bf16 v[88:91], v[148:151], v[194:197], v[88:91]
	v_mfma_f32_16x16x32_bf16 v[76:79], v[136:139], v[202:205], v[76:79]
	v_mfma_f32_16x16x32_bf16 v[72:75], v[148:151], v[202:205], v[72:75]
	v_mfma_f32_16x16x32_bf16 v[126:129], v[144:147], v[176:179], v[126:129]
	v_mfma_f32_16x16x32_bf16 v[122:125], v[152:155], v[176:179], v[122:125]
	v_mfma_f32_16x16x32_bf16 v[110:113], v[144:147], v[190:193], v[110:113]
	v_mfma_f32_16x16x32_bf16 v[106:109], v[152:155], v[190:193], v[106:109]
	v_mfma_f32_16x16x32_bf16 v[92:95], v[144:147], v[198:201], v[92:95]
	v_mfma_f32_16x16x32_bf16 v[88:91], v[152:155], v[198:201], v[88:91]
	v_mfma_f32_16x16x32_bf16 v[76:79], v[144:147], v[206:209], v[76:79]
	v_mfma_f32_16x16x32_bf16 v[72:75], v[152:155], v[206:209], v[72:75]
	v_mfma_f32_16x16x32_bf16 v[118:121], v[156:159], v[172:175], v[118:121]
	v_mfma_f32_16x16x32_bf16 v[114:117], v[164:167], v[172:175], v[114:117]
	v_mfma_f32_16x16x32_bf16 v[102:105], v[156:159], v[180:183], v[102:105]
	v_mfma_f32_16x16x32_bf16 v[98:101], v[164:167], v[180:183], v[98:101]
	v_mfma_f32_16x16x32_bf16 v[84:87], v[156:159], v[194:197], v[84:87]
	v_mfma_f32_16x16x32_bf16 v[80:83], v[164:167], v[194:197], v[80:83]
	v_mfma_f32_16x16x32_bf16 v[68:71], v[156:159], v[202:205], v[68:71]
	v_mfma_f32_16x16x32_bf16 v[64:67], v[164:167], v[202:205], v[64:67]
	v_mfma_f32_16x16x32_bf16 v[118:121], v[160:163], v[176:179], v[118:121]
	v_mfma_f32_16x16x32_bf16 v[114:117], v[168:171], v[176:179], v[114:117]
	v_mfma_f32_16x16x32_bf16 v[102:105], v[160:163], v[190:193], v[102:105]
	v_mfma_f32_16x16x32_bf16 v[98:101], v[168:171], v[190:193], v[98:101]
	v_mfma_f32_16x16x32_bf16 v[84:87], v[160:163], v[198:201], v[84:87]
	v_mfma_f32_16x16x32_bf16 v[80:83], v[168:171], v[198:201], v[80:83]
	v_mfma_f32_16x16x32_bf16 v[68:71], v[160:163], v[206:209], v[68:71]
	v_mfma_f32_16x16x32_bf16 v[64:67], v[168:171], v[206:209], v[64:67]
	s_setprio 1
	s_barrier
	s_add_i32 s18, s35, s14
	s_mov_b32 m0, s18
	ds_read_b128 v[172:175], v143 offset:16384
	ds_read_b128 v[176:179], v143 offset:17408
	ds_read_b128 v[180:183], v143 offset:18432
	ds_read_b128 v[190:193], v143 offset:19456
	ds_read_b128 v[194:197], v143 offset:20480
	ds_read_b128 v[198:201], v143 offset:21504
	ds_read_b128 v[202:205], v143 offset:22528
	ds_read_b128 v[206:209], v143 offset:23552
	global_load_lds_dwordx4 v96, s[44:45]
	s_add_i32 m0, s18, 0x2000
	s_add_u32 s18, s44, 0xb0000
	s_addc_u32 s19, s45, 0
	s_add_i32 s35, s49, s14
	global_load_lds_dwordx4 v134, s[44:45]
	s_mov_b32 m0, s35
	s_nop 0
	global_load_lds_dwordx4 v96, s[18:19]
	s_add_i32 m0, s35, 0x2000
	s_nop 0
	global_load_lds_dwordx4 v134, s[18:19]
	s_waitcnt vmcnt(6)
	s_waitcnt lgkmcnt(0)
	s_barrier
	s_setprio 0
	s_waitcnt lgkmcnt(0)
	v_mfma_f32_16x16x32_bf16 v[60:63], v[136:139], v[172:175], v[60:63]
	v_mfma_f32_16x16x32_bf16 v[56:59], v[148:151], v[172:175], v[56:59]
	v_mfma_f32_16x16x32_bf16 v[44:47], v[136:139], v[180:183], v[44:47]
	v_mfma_f32_16x16x32_bf16 v[40:43], v[148:151], v[180:183], v[40:43]
	v_mfma_f32_16x16x32_bf16 v[28:31], v[136:139], v[194:197], v[28:31]
	v_mfma_f32_16x16x32_bf16 v[24:27], v[148:151], v[194:197], v[24:27]
	v_mfma_f32_16x16x32_bf16 v[12:15], v[136:139], v[202:205], v[12:15]
	v_mfma_f32_16x16x32_bf16 v[8:11], v[148:151], v[202:205], v[8:11]
	v_mfma_f32_16x16x32_bf16 v[60:63], v[144:147], v[176:179], v[60:63]
	v_mfma_f32_16x16x32_bf16 v[56:59], v[152:155], v[176:179], v[56:59]
	v_mfma_f32_16x16x32_bf16 v[44:47], v[144:147], v[190:193], v[44:47]
	v_mfma_f32_16x16x32_bf16 v[40:43], v[152:155], v[190:193], v[40:43]
	v_mfma_f32_16x16x32_bf16 v[28:31], v[144:147], v[198:201], v[28:31]
	v_mfma_f32_16x16x32_bf16 v[24:27], v[152:155], v[198:201], v[24:27]
	v_mfma_f32_16x16x32_bf16 v[12:15], v[144:147], v[206:209], v[12:15]
	v_mfma_f32_16x16x32_bf16 v[8:11], v[152:155], v[206:209], v[8:11]
	v_mfma_f32_16x16x32_bf16 v[52:55], v[156:159], v[172:175], v[52:55]
	v_mfma_f32_16x16x32_bf16 v[48:51], v[164:167], v[172:175], v[48:51]
	v_mfma_f32_16x16x32_bf16 v[36:39], v[156:159], v[180:183], v[36:39]
	v_mfma_f32_16x16x32_bf16 v[32:35], v[164:167], v[180:183], v[32:35]
	v_mfma_f32_16x16x32_bf16 v[20:23], v[156:159], v[194:197], v[20:23]
	v_mfma_f32_16x16x32_bf16 v[16:19], v[164:167], v[194:197], v[16:19]
	v_mfma_f32_16x16x32_bf16 v[4:7], v[156:159], v[202:205], v[4:7]
	v_mfma_f32_16x16x32_bf16 v[0:3], v[164:167], v[202:205], v[0:3]
	v_mfma_f32_16x16x32_bf16 v[52:55], v[160:163], v[176:179], v[52:55]
	v_mfma_f32_16x16x32_bf16 v[48:51], v[168:171], v[176:179], v[48:51]
	v_mfma_f32_16x16x32_bf16 v[36:39], v[160:163], v[190:193], v[36:39]
	v_mfma_f32_16x16x32_bf16 v[32:35], v[168:171], v[190:193], v[32:35]
	v_mfma_f32_16x16x32_bf16 v[20:23], v[160:163], v[198:201], v[20:23]
	v_mfma_f32_16x16x32_bf16 v[16:19], v[168:171], v[198:201], v[16:19]
	v_mfma_f32_16x16x32_bf16 v[4:7], v[160:163], v[206:209], v[4:7]
	v_mfma_f32_16x16x32_bf16 v[0:3], v[168:171], v[206:209], v[0:3]
	s_setprio 1
	s_barrier
	s_add_i32 s35, 0, 0x18000
	v_add_u32_e32 v140, s35, v142
	s_add_i32 s44, 0, 0x1c000
	ds_read_b128 v[136:139], v140
	ds_read_b128 v[144:147], v140 offset:1024
	ds_read_b128 v[148:151], v140 offset:2048
	ds_read_b128 v[152:155], v140 offset:3072
	v_add_u32_e32 v140, s44, v142
	ds_read_b128 v[156:159], v140
	ds_read_b128 v[160:163], v140 offset:1024
	ds_read_b128 v[164:167], v140 offset:2048
	ds_read_b128 v[168:171], v140 offset:3072
	s_mov_b32 m0, s66
	s_nop 0
	global_load_lds_dwordx4 v130, s[42:43]
	s_mov_b32 m0, s67
	s_nop 0
	global_load_lds_dwordx4 v132, s[42:43]
	s_add_u32 s18, s42, 0xb0000
	s_addc_u32 s19, s43, 0
	s_mov_b32 m0, s68
	ds_read_b128 v[172:175], v143 offset:32768
	ds_read_b128 v[176:179], v143 offset:33792
	ds_read_b128 v[180:183], v143 offset:34816
	ds_read_b128 v[190:193], v143 offset:35840
	ds_read_b128 v[194:197], v143 offset:36864
	ds_read_b128 v[198:201], v143 offset:37888
	ds_read_b128 v[202:205], v143 offset:38912
	ds_read_b128 v[206:209], v143 offset:39936
	global_load_lds_dwordx4 v130, s[18:19]
	s_mov_b32 m0, s69
	s_nop 0
	global_load_lds_dwordx4 v132, s[18:19]
	s_waitcnt vmcnt(8)
	s_waitcnt lgkmcnt(0)
	s_barrier
	s_setprio 0
	s_waitcnt lgkmcnt(0)
	v_mfma_f32_16x16x32_bf16 v[126:129], v[136:139], v[172:175], v[126:129]
	v_mfma_f32_16x16x32_bf16 v[122:125], v[148:151], v[172:175], v[122:125]
	v_mfma_f32_16x16x32_bf16 v[110:113], v[136:139], v[180:183], v[110:113]
	v_mfma_f32_16x16x32_bf16 v[106:109], v[148:151], v[180:183], v[106:109]
	v_mfma_f32_16x16x32_bf16 v[92:95], v[136:139], v[194:197], v[92:95]
	v_mfma_f32_16x16x32_bf16 v[88:91], v[148:151], v[194:197], v[88:91]
	v_mfma_f32_16x16x32_bf16 v[76:79], v[136:139], v[202:205], v[76:79]
	v_mfma_f32_16x16x32_bf16 v[72:75], v[148:151], v[202:205], v[72:75]
	v_mfma_f32_16x16x32_bf16 v[126:129], v[144:147], v[176:179], v[126:129]
	v_mfma_f32_16x16x32_bf16 v[122:125], v[152:155], v[176:179], v[122:125]
	v_mfma_f32_16x16x32_bf16 v[110:113], v[144:147], v[190:193], v[110:113]
	v_mfma_f32_16x16x32_bf16 v[106:109], v[152:155], v[190:193], v[106:109]
	v_mfma_f32_16x16x32_bf16 v[92:95], v[144:147], v[198:201], v[92:95]
	v_mfma_f32_16x16x32_bf16 v[88:91], v[152:155], v[198:201], v[88:91]
	v_mfma_f32_16x16x32_bf16 v[76:79], v[144:147], v[206:209], v[76:79]
	v_mfma_f32_16x16x32_bf16 v[72:75], v[152:155], v[206:209], v[72:75]
	v_mfma_f32_16x16x32_bf16 v[118:121], v[156:159], v[172:175], v[118:121]
	v_mfma_f32_16x16x32_bf16 v[114:117], v[164:167], v[172:175], v[114:117]
	v_mfma_f32_16x16x32_bf16 v[102:105], v[156:159], v[180:183], v[102:105]
	v_mfma_f32_16x16x32_bf16 v[98:101], v[164:167], v[180:183], v[98:101]
	v_mfma_f32_16x16x32_bf16 v[84:87], v[156:159], v[194:197], v[84:87]
	v_mfma_f32_16x16x32_bf16 v[80:83], v[164:167], v[194:197], v[80:83]
	v_mfma_f32_16x16x32_bf16 v[68:71], v[156:159], v[202:205], v[68:71]
	v_mfma_f32_16x16x32_bf16 v[64:67], v[164:167], v[202:205], v[64:67]
	v_mfma_f32_16x16x32_bf16 v[118:121], v[160:163], v[176:179], v[118:121]
	v_mfma_f32_16x16x32_bf16 v[114:117], v[168:171], v[176:179], v[114:117]
	v_mfma_f32_16x16x32_bf16 v[102:105], v[160:163], v[190:193], v[102:105]
	v_mfma_f32_16x16x32_bf16 v[98:101], v[168:171], v[190:193], v[98:101]
	v_mfma_f32_16x16x32_bf16 v[84:87], v[160:163], v[198:201], v[84:87]
	v_mfma_f32_16x16x32_bf16 v[80:83], v[168:171], v[198:201], v[80:83]
	v_mfma_f32_16x16x32_bf16 v[68:71], v[160:163], v[206:209], v[68:71]
	v_mfma_f32_16x16x32_bf16 v[64:67], v[168:171], v[206:209], v[64:67]
	s_setprio 1
	s_barrier
	s_add_i32 s18, s35, s14
	s_mov_b32 m0, s18
	ds_read_b128 v[172:175], v143 offset:49152
	ds_read_b128 v[176:179], v143 offset:50176
	ds_read_b128 v[180:183], v143 offset:51200
	ds_read_b128 v[190:193], v143 offset:52224
	ds_read_b128 v[194:197], v143 offset:53248
	ds_read_b128 v[198:201], v143 offset:54272
	ds_read_b128 v[202:205], v143 offset:55296
	ds_read_b128 v[206:209], v143 offset:56320
	global_load_lds_dwordx4 v96, s[62:63]
	s_add_i32 m0, s18, 0x2000
	s_add_u32 s18, s62, 0xb0000
	s_addc_u32 s19, s63, 0
	s_add_i32 s35, s44, s14
	global_load_lds_dwordx4 v134, s[62:63]
	s_mov_b32 m0, s35
	s_nop 0
	global_load_lds_dwordx4 v96, s[18:19]
	s_add_i32 m0, s35, 0x2000
	s_nop 0
	global_load_lds_dwordx4 v134, s[18:19]
	s_waitcnt vmcnt(6)
	s_waitcnt lgkmcnt(0)
	s_barrier
	s_setprio 0
	s_waitcnt lgkmcnt(0)
	v_mfma_f32_16x16x32_bf16 v[60:63], v[136:139], v[172:175], v[60:63]
	v_mfma_f32_16x16x32_bf16 v[56:59], v[148:151], v[172:175], v[56:59]
	v_mfma_f32_16x16x32_bf16 v[44:47], v[136:139], v[180:183], v[44:47]
	v_mfma_f32_16x16x32_bf16 v[40:43], v[148:151], v[180:183], v[40:43]
	v_mfma_f32_16x16x32_bf16 v[28:31], v[136:139], v[194:197], v[28:31]
	v_mfma_f32_16x16x32_bf16 v[24:27], v[148:151], v[194:197], v[24:27]
	v_mfma_f32_16x16x32_bf16 v[12:15], v[136:139], v[202:205], v[12:15]
	v_mfma_f32_16x16x32_bf16 v[8:11], v[148:151], v[202:205], v[8:11]
	v_mfma_f32_16x16x32_bf16 v[60:63], v[144:147], v[176:179], v[60:63]
	v_mfma_f32_16x16x32_bf16 v[56:59], v[152:155], v[176:179], v[56:59]
	v_mfma_f32_16x16x32_bf16 v[44:47], v[144:147], v[190:193], v[44:47]
	v_mfma_f32_16x16x32_bf16 v[40:43], v[152:155], v[190:193], v[40:43]
	v_mfma_f32_16x16x32_bf16 v[28:31], v[144:147], v[198:201], v[28:31]
	v_mfma_f32_16x16x32_bf16 v[24:27], v[152:155], v[198:201], v[24:27]
	v_mfma_f32_16x16x32_bf16 v[12:15], v[144:147], v[206:209], v[12:15]
	v_mfma_f32_16x16x32_bf16 v[8:11], v[152:155], v[206:209], v[8:11]
	v_mfma_f32_16x16x32_bf16 v[52:55], v[156:159], v[172:175], v[52:55]
	v_mfma_f32_16x16x32_bf16 v[48:51], v[164:167], v[172:175], v[48:51]
	v_mfma_f32_16x16x32_bf16 v[36:39], v[156:159], v[180:183], v[36:39]
	v_mfma_f32_16x16x32_bf16 v[32:35], v[164:167], v[180:183], v[32:35]
	v_mfma_f32_16x16x32_bf16 v[20:23], v[156:159], v[194:197], v[20:23]
	v_mfma_f32_16x16x32_bf16 v[16:19], v[164:167], v[194:197], v[16:19]
	v_mfma_f32_16x16x32_bf16 v[4:7], v[156:159], v[202:205], v[4:7]
	v_mfma_f32_16x16x32_bf16 v[0:3], v[164:167], v[202:205], v[0:3]
	v_mfma_f32_16x16x32_bf16 v[52:55], v[160:163], v[176:179], v[52:55]
	v_mfma_f32_16x16x32_bf16 v[48:51], v[168:171], v[176:179], v[48:51]
	v_mfma_f32_16x16x32_bf16 v[36:39], v[160:163], v[190:193], v[36:39]
	v_mfma_f32_16x16x32_bf16 v[32:35], v[168:171], v[190:193], v[32:35]
	v_mfma_f32_16x16x32_bf16 v[20:23], v[160:163], v[198:201], v[20:23]
	v_mfma_f32_16x16x32_bf16 v[16:19], v[168:171], v[198:201], v[16:19]
	v_mfma_f32_16x16x32_bf16 v[4:7], v[160:163], v[206:209], v[4:7]
	v_mfma_f32_16x16x32_bf16 v[0:3], v[168:171], v[206:209], v[0:3]
	s_setprio 1
	s_barrier
	s_add_i32 s85, s85, 2
	s_add_u32 s81, s81, 0x100
	s_addc_u32 s82, s82, 0
	s_add_u32 s83, s83, 0x100
	s_addc_u32 s84, s84, 0
	s_add_u32 s60, s60, 0x100
	s_addc_u32 s61, s61, 0
	s_cmp_gt_u32 s85, 41
	s_cbranch_scc0 .LBB0_703
	s_and_b64 vcc, exec, s[30:31]
	s_cbranch_vccz .LBB0_706
	s_barrier

.LBB0_740:
	s_add_u32 s18, s66, 0x80
	s_addc_u32 s19, s67, 0
	s_add_u32 s66, s66, 0x100
	s_addc_u32 s67, s67, 0
	s_cmp_eq_u32 s85, 12
	s_cselect_b32 s42, s81, s66
	s_cselect_b32 s43, s59, s67
	s_cselect_b32 s45, s31, s84
	s_cselect_b32 s44, s82, s83
	s_add_u32 s38, s42, 0x80
	s_addc_u32 s39, s43, 0
	s_add_u32 s68, s44, 0x80
	s_addc_u32 s69, s45, 0
	s_add_i32 s35, 0, 0x10000
	s_add_i32 s49, 0, 0x14000
	v_add_u32_e32 v96, s35, v151
	v_add_u32_e32 v150, s49, v151
	ds_read_b128 v[138:141], v96
	ds_read_b128 v[142:145], v96 offset:1024
	ds_read_b128 v[146:149], v96 offset:2048
	ds_read_b128 v[156:159], v96 offset:3072
	ds_read_b128 v[160:163], v150
	ds_read_b128 v[164:167], v150 offset:1024
	ds_read_b128 v[168:171], v150 offset:2048
	ds_read_b128 v[172:175], v150 offset:3072
	s_mov_b32 m0, s77
	ds_read_b128 v[176:179], v155
	ds_read_b128 v[180:183], v155 offset:1024
	ds_read_b128 v[190:193], v155 offset:2048
	ds_read_b128 v[194:197], v155 offset:3072
	ds_read_b128 v[198:201], v155 offset:4096
	ds_read_b128 v[202:205], v155 offset:5120
	ds_read_b128 v[206:209], v155 offset:6144
	ds_read_b128 v[210:213], v155 offset:7168
	global_load_lds_dwordx4 v136, s[18:19]
	s_mov_b32 m0, s78
	s_nop 0
	global_load_lds_dwordx4 v132, s[18:19]
	s_add_u32 s18, s18, 0x40000
	s_addc_u32 s19, s19, 0
	s_add_i32 m0, s65, 0xc000
	s_nop 0
	global_load_lds_dwordx4 v136, s[18:19]
	s_add_i32 m0, s65, 0xe000
	s_nop 0
	global_load_lds_dwordx4 v132, s[18:19]
	s_waitcnt vmcnt(8)
	s_waitcnt lgkmcnt(0)
	s_barrier
	s_setprio 0
	s_waitcnt lgkmcnt(0)
	v_mfma_f32_16x16x32_bf16 v[126:129], v[138:141], v[176:179], v[126:129]
	v_mfma_f32_16x16x32_bf16 v[118:121], v[146:149], v[176:179], v[118:121]
	v_mfma_f32_16x16x32_bf16 v[110:113], v[138:141], v[190:193], v[110:113]
	v_mfma_f32_16x16x32_bf16 v[102:105], v[146:149], v[190:193], v[102:105]
	v_mfma_f32_16x16x32_bf16 v[92:95], v[138:141], v[198:201], v[92:95]
	v_mfma_f32_16x16x32_bf16 v[84:87], v[146:149], v[198:201], v[84:87]
	v_mfma_f32_16x16x32_bf16 v[76:79], v[138:141], v[206:209], v[76:79]
	v_mfma_f32_16x16x32_bf16 v[68:71], v[146:149], v[206:209], v[68:71]
	v_mfma_f32_16x16x32_bf16 v[126:129], v[142:145], v[180:183], v[126:129]
	v_mfma_f32_16x16x32_bf16 v[118:121], v[156:159], v[180:183], v[118:121]
	v_mfma_f32_16x16x32_bf16 v[110:113], v[142:145], v[194:197], v[110:113]
	v_mfma_f32_16x16x32_bf16 v[102:105], v[156:159], v[194:197], v[102:105]
	v_mfma_f32_16x16x32_bf16 v[92:95], v[142:145], v[202:205], v[92:95]
	v_mfma_f32_16x16x32_bf16 v[84:87], v[156:159], v[202:205], v[84:87]
	v_mfma_f32_16x16x32_bf16 v[76:79], v[142:145], v[210:213], v[76:79]
	v_mfma_f32_16x16x32_bf16 v[68:71], v[156:159], v[210:213], v[68:71]
	v_mfma_f32_16x16x32_bf16 v[122:125], v[160:163], v[176:179], v[122:125]
	v_mfma_f32_16x16x32_bf16 v[114:117], v[168:171], v[176:179], v[114:117]
	v_mfma_f32_16x16x32_bf16 v[106:109], v[160:163], v[190:193], v[106:109]
	v_mfma_f32_16x16x32_bf16 v[98:101], v[168:171], v[190:193], v[98:101]
	v_mfma_f32_16x16x32_bf16 v[88:91], v[160:163], v[198:201], v[88:91]
	v_mfma_f32_16x16x32_bf16 v[80:83], v[168:171], v[198:201], v[80:83]
	v_mfma_f32_16x16x32_bf16 v[72:75], v[160:163], v[206:209], v[72:75]
	v_mfma_f32_16x16x32_bf16 v[64:67], v[168:171], v[206:209], v[64:67]
	v_mfma_f32_16x16x32_bf16 v[122:125], v[164:167], v[180:183], v[122:125]
	v_mfma_f32_16x16x32_bf16 v[114:117], v[172:175], v[180:183], v[114:117]
	v_mfma_f32_16x16x32_bf16 v[106:109], v[164:167], v[194:197], v[106:109]
	v_mfma_f32_16x16x32_bf16 v[98:101], v[172:175], v[194:197], v[98:101]
	v_mfma_f32_16x16x32_bf16 v[88:91], v[164:167], v[202:205], v[88:91]
	v_mfma_f32_16x16x32_bf16 v[80:83], v[172:175], v[202:205], v[80:83]
	v_mfma_f32_16x16x32_bf16 v[72:75], v[164:167], v[210:213], v[72:75]
	v_mfma_f32_16x16x32_bf16 v[64:67], v[172:175], v[210:213], v[64:67]
	s_setprio 1
	s_barrier
	s_add_i32 s18, s35, s47
	s_mov_b32 m0, s18
	ds_read_b128 v[176:179], v155 offset:16384
	ds_read_b128 v[180:183], v155 offset:17408
	ds_read_b128 v[190:193], v155 offset:18432
	ds_read_b128 v[194:197], v155 offset:19456
	ds_read_b128 v[198:201], v155 offset:20480
	ds_read_b128 v[202:205], v155 offset:21504
	ds_read_b128 v[206:209], v155 offset:22528
	ds_read_b128 v[210:213], v155 offset:23552
	global_load_lds_dwordx4 v134, s[44:45]
	s_add_i32 m0, s18, 0x2000
	s_add_u32 s18, s44, 0x40000
	s_addc_u32 s19, s45, 0
	s_add_i32 s35, s49, s47
	global_load_lds_dwordx4 v130, s[44:45]
	s_mov_b32 m0, s35
	s_nop 0
	global_load_lds_dwordx4 v134, s[18:19]
	s_add_i32 m0, s35, 0x2000
	s_nop 0
	global_load_lds_dwordx4 v130, s[18:19]
	s_waitcnt vmcnt(6)
	s_waitcnt lgkmcnt(0)
	s_barrier
	s_setprio 0
	s_waitcnt lgkmcnt(0)
	v_mfma_f32_16x16x32_bf16 v[60:63], v[138:141], v[176:179], v[60:63]
	v_mfma_f32_16x16x32_bf16 v[52:55], v[146:149], v[176:179], v[52:55]
	v_mfma_f32_16x16x32_bf16 v[44:47], v[138:141], v[190:193], v[44:47]
	v_mfma_f32_16x16x32_bf16 v[36:39], v[146:149], v[190:193], v[36:39]
	v_mfma_f32_16x16x32_bf16 v[28:31], v[138:141], v[198:201], v[28:31]
	v_mfma_f32_16x16x32_bf16 v[20:23], v[146:149], v[198:201], v[20:23]
	v_mfma_f32_16x16x32_bf16 v[12:15], v[138:141], v[206:209], v[12:15]
	v_mfma_f32_16x16x32_bf16 v[4:7], v[146:149], v[206:209], v[4:7]
	v_mfma_f32_16x16x32_bf16 v[60:63], v[142:145], v[180:183], v[60:63]
	v_mfma_f32_16x16x32_bf16 v[52:55], v[156:159], v[180:183], v[52:55]
	v_mfma_f32_16x16x32_bf16 v[44:47], v[142:145], v[194:197], v[44:47]
	v_mfma_f32_16x16x32_bf16 v[36:39], v[156:159], v[194:197], v[36:39]
	v_mfma_f32_16x16x32_bf16 v[28:31], v[142:145], v[202:205], v[28:31]
	v_mfma_f32_16x16x32_bf16 v[20:23], v[156:159], v[202:205], v[20:23]
	v_mfma_f32_16x16x32_bf16 v[12:15], v[142:145], v[210:213], v[12:15]
	v_mfma_f32_16x16x32_bf16 v[4:7], v[156:159], v[210:213], v[4:7]
	v_mfma_f32_16x16x32_bf16 v[56:59], v[160:163], v[176:179], v[56:59]
	v_mfma_f32_16x16x32_bf16 v[48:51], v[168:171], v[176:179], v[48:51]
	v_mfma_f32_16x16x32_bf16 v[40:43], v[160:163], v[190:193], v[40:43]
	v_mfma_f32_16x16x32_bf16 v[32:35], v[168:171], v[190:193], v[32:35]
	v_mfma_f32_16x16x32_bf16 v[24:27], v[160:163], v[198:201], v[24:27]
	v_mfma_f32_16x16x32_bf16 v[16:19], v[168:171], v[198:201], v[16:19]
	v_mfma_f32_16x16x32_bf16 v[8:11], v[160:163], v[206:209], v[8:11]
	v_mfma_f32_16x16x32_bf16 v[0:3], v[168:171], v[206:209], v[0:3]
	v_mfma_f32_16x16x32_bf16 v[56:59], v[164:167], v[180:183], v[56:59]
	v_mfma_f32_16x16x32_bf16 v[48:51], v[172:175], v[180:183], v[48:51]
	v_mfma_f32_16x16x32_bf16 v[40:43], v[164:167], v[194:197], v[40:43]
	v_mfma_f32_16x16x32_bf16 v[32:35], v[172:175], v[194:197], v[32:35]
	v_mfma_f32_16x16x32_bf16 v[24:27], v[164:167], v[202:205], v[24:27]
	v_mfma_f32_16x16x32_bf16 v[16:19], v[172:175], v[202:205], v[16:19]
	v_mfma_f32_16x16x32_bf16 v[8:11], v[164:167], v[210:213], v[8:11]
	v_mfma_f32_16x16x32_bf16 v[0:3], v[172:175], v[210:213], v[0:3]
	s_setprio 1
	s_barrier
	s_add_i32 s35, 0, 0x18000
	v_add_u32_e32 v96, s35, v151
	s_add_i32 s44, 0, 0x1c000
	ds_read_b128 v[138:141], v96
	ds_read_b128 v[142:145], v96 offset:1024
	ds_read_b128 v[146:149], v96 offset:2048
	ds_read_b128 v[156:159], v96 offset:3072
	v_add_u32_e32 v96, s44, v151
	ds_read_b128 v[160:163], v96
	ds_read_b128 v[164:167], v96 offset:1024
	ds_read_b128 v[168:171], v96 offset:2048
	ds_read_b128 v[172:175], v96 offset:3072
	s_mov_b32 m0, s65
	s_nop 0
	global_load_lds_dwordx4 v136, s[42:43]
	s_mov_b32 m0, s72
	s_nop 0
	global_load_lds_dwordx4 v132, s[42:43]
	s_add_u32 s18, s42, 0x40000
	s_addc_u32 s19, s43, 0
	s_mov_b32 m0, s73
	ds_read_b128 v[176:179], v155 offset:32768
	ds_read_b128 v[180:183], v155 offset:33792
	ds_read_b128 v[190:193], v155 offset:34816
	ds_read_b128 v[194:197], v155 offset:35840
	ds_read_b128 v[198:201], v155 offset:36864
	ds_read_b128 v[202:205], v155 offset:37888
	ds_read_b128 v[206:209], v155 offset:38912
	ds_read_b128 v[210:213], v155 offset:39936
	global_load_lds_dwordx4 v136, s[18:19]
	s_mov_b32 m0, s74
	s_nop 0
	global_load_lds_dwordx4 v132, s[18:19]
	s_waitcnt vmcnt(8)
	s_waitcnt lgkmcnt(0)
	s_barrier
	s_setprio 0
	s_waitcnt lgkmcnt(0)
	v_mfma_f32_16x16x32_bf16 v[126:129], v[138:141], v[176:179], v[126:129]
	v_mfma_f32_16x16x32_bf16 v[118:121], v[146:149], v[176:179], v[118:121]
	v_mfma_f32_16x16x32_bf16 v[110:113], v[138:141], v[190:193], v[110:113]
	v_mfma_f32_16x16x32_bf16 v[102:105], v[146:149], v[190:193], v[102:105]
	v_mfma_f32_16x16x32_bf16 v[92:95], v[138:141], v[198:201], v[92:95]
	v_mfma_f32_16x16x32_bf16 v[84:87], v[146:149], v[198:201], v[84:87]
	v_mfma_f32_16x16x32_bf16 v[76:79], v[138:141], v[206:209], v[76:79]
	v_mfma_f32_16x16x32_bf16 v[68:71], v[146:149], v[206:209], v[68:71]
	v_mfma_f32_16x16x32_bf16 v[126:129], v[142:145], v[180:183], v[126:129]
	v_mfma_f32_16x16x32_bf16 v[118:121], v[156:159], v[180:183], v[118:121]
	v_mfma_f32_16x16x32_bf16 v[110:113], v[142:145], v[194:197], v[110:113]
	v_mfma_f32_16x16x32_bf16 v[102:105], v[156:159], v[194:197], v[102:105]
	v_mfma_f32_16x16x32_bf16 v[92:95], v[142:145], v[202:205], v[92:95]
	v_mfma_f32_16x16x32_bf16 v[84:87], v[156:159], v[202:205], v[84:87]
	v_mfma_f32_16x16x32_bf16 v[76:79], v[142:145], v[210:213], v[76:79]
	v_mfma_f32_16x16x32_bf16 v[68:71], v[156:159], v[210:213], v[68:71]
	v_mfma_f32_16x16x32_bf16 v[122:125], v[160:163], v[176:179], v[122:125]
	v_mfma_f32_16x16x32_bf16 v[114:117], v[168:171], v[176:179], v[114:117]
	v_mfma_f32_16x16x32_bf16 v[106:109], v[160:163], v[190:193], v[106:109]
	v_mfma_f32_16x16x32_bf16 v[98:101], v[168:171], v[190:193], v[98:101]
	v_mfma_f32_16x16x32_bf16 v[88:91], v[160:163], v[198:201], v[88:91]
	v_mfma_f32_16x16x32_bf16 v[80:83], v[168:171], v[198:201], v[80:83]
	v_mfma_f32_16x16x32_bf16 v[72:75], v[160:163], v[206:209], v[72:75]
	v_mfma_f32_16x16x32_bf16 v[64:67], v[168:171], v[206:209], v[64:67]
	v_mfma_f32_16x16x32_bf16 v[122:125], v[164:167], v[180:183], v[122:125]
	v_mfma_f32_16x16x32_bf16 v[114:117], v[172:175], v[180:183], v[114:117]
	v_mfma_f32_16x16x32_bf16 v[106:109], v[164:167], v[194:197], v[106:109]
	v_mfma_f32_16x16x32_bf16 v[98:101], v[172:175], v[194:197], v[98:101]
	v_mfma_f32_16x16x32_bf16 v[88:91], v[164:167], v[202:205], v[88:91]
	v_mfma_f32_16x16x32_bf16 v[80:83], v[172:175], v[202:205], v[80:83]
	v_mfma_f32_16x16x32_bf16 v[72:75], v[164:167], v[210:213], v[72:75]
	v_mfma_f32_16x16x32_bf16 v[64:67], v[172:175], v[210:213], v[64:67]
	s_setprio 1
	s_barrier
	s_add_i32 s18, s35, s47
	s_mov_b32 m0, s18
	ds_read_b128 v[176:179], v155 offset:49152
	ds_read_b128 v[180:183], v155 offset:50176
	ds_read_b128 v[190:193], v155 offset:51200
	ds_read_b128 v[194:197], v155 offset:52224
	ds_read_b128 v[198:201], v155 offset:53248
	ds_read_b128 v[202:205], v155 offset:54272
	ds_read_b128 v[206:209], v155 offset:55296
	ds_read_b128 v[210:213], v155 offset:56320
	global_load_lds_dwordx4 v134, s[68:69]
	s_add_i32 m0, s18, 0x2000
	s_add_u32 s18, s68, 0x40000
	s_addc_u32 s19, s69, 0
	s_add_i32 s35, s44, s47
	global_load_lds_dwordx4 v130, s[68:69]
	s_mov_b32 m0, s35
	s_nop 0
	global_load_lds_dwordx4 v134, s[18:19]
	s_add_i32 m0, s35, 0x2000
	s_nop 0
	global_load_lds_dwordx4 v130, s[18:19]
	s_waitcnt vmcnt(6)
	s_cmp_lg_u32 s85, 12
	s_cbranch_scc1 .Lswi_ssq_skip
	global_load_dwordx4 v[220:223], v[252:253], off
	global_load_dwordx4 v[224:227], v[252:253], off offset:1024
	global_load_dwordx4 v[228:231], v[252:253], off offset:2048
	global_load_dwordx4 v[232:235], v[252:253], off offset:3072
	global_load_dwordx4 v[236:239], v[184:185], off
	global_load_dwordx4 v[240:243], v[184:185], off offset:1024
	global_load_dwordx4 v[244:247], v[184:185], off offset:2048
	global_load_dwordx4 v[248:251], v[184:185], off offset:3072
.Lswi_ssq_skip:
	s_waitcnt lgkmcnt(0)
	s_barrier
	s_setprio 0
	s_waitcnt lgkmcnt(0)
	v_mfma_f32_16x16x32_bf16 v[60:63], v[138:141], v[176:179], v[60:63]
	v_mfma_f32_16x16x32_bf16 v[52:55], v[146:149], v[176:179], v[52:55]
	v_mfma_f32_16x16x32_bf16 v[44:47], v[138:141], v[190:193], v[44:47]
	v_mfma_f32_16x16x32_bf16 v[36:39], v[146:149], v[190:193], v[36:39]
	v_mfma_f32_16x16x32_bf16 v[28:31], v[138:141], v[198:201], v[28:31]
	v_mfma_f32_16x16x32_bf16 v[20:23], v[146:149], v[198:201], v[20:23]
	v_mfma_f32_16x16x32_bf16 v[12:15], v[138:141], v[206:209], v[12:15]
	v_mfma_f32_16x16x32_bf16 v[4:7], v[146:149], v[206:209], v[4:7]
	v_mfma_f32_16x16x32_bf16 v[60:63], v[142:145], v[180:183], v[60:63]
	v_mfma_f32_16x16x32_bf16 v[52:55], v[156:159], v[180:183], v[52:55]
	v_mfma_f32_16x16x32_bf16 v[44:47], v[142:145], v[194:197], v[44:47]
	v_mfma_f32_16x16x32_bf16 v[36:39], v[156:159], v[194:197], v[36:39]
	v_mfma_f32_16x16x32_bf16 v[28:31], v[142:145], v[202:205], v[28:31]
	v_mfma_f32_16x16x32_bf16 v[20:23], v[156:159], v[202:205], v[20:23]
	v_mfma_f32_16x16x32_bf16 v[12:15], v[142:145], v[210:213], v[12:15]
	v_mfma_f32_16x16x32_bf16 v[4:7], v[156:159], v[210:213], v[4:7]
	v_mfma_f32_16x16x32_bf16 v[56:59], v[160:163], v[176:179], v[56:59]
	v_mfma_f32_16x16x32_bf16 v[48:51], v[168:171], v[176:179], v[48:51]
	v_mfma_f32_16x16x32_bf16 v[40:43], v[160:163], v[190:193], v[40:43]
	v_mfma_f32_16x16x32_bf16 v[32:35], v[168:171], v[190:193], v[32:35]
	v_mfma_f32_16x16x32_bf16 v[24:27], v[160:163], v[198:201], v[24:27]
	v_mfma_f32_16x16x32_bf16 v[16:19], v[168:171], v[198:201], v[16:19]
	v_mfma_f32_16x16x32_bf16 v[8:11], v[160:163], v[206:209], v[8:11]
	v_mfma_f32_16x16x32_bf16 v[0:3], v[168:171], v[206:209], v[0:3]
	v_mfma_f32_16x16x32_bf16 v[56:59], v[164:167], v[180:183], v[56:59]
	v_mfma_f32_16x16x32_bf16 v[48:51], v[172:175], v[180:183], v[48:51]
	v_mfma_f32_16x16x32_bf16 v[40:43], v[164:167], v[194:197], v[40:43]
	v_mfma_f32_16x16x32_bf16 v[32:35], v[172:175], v[194:197], v[32:35]
	v_mfma_f32_16x16x32_bf16 v[24:27], v[164:167], v[202:205], v[24:27]
	v_mfma_f32_16x16x32_bf16 v[16:19], v[172:175], v[202:205], v[16:19]
	v_mfma_f32_16x16x32_bf16 v[8:11], v[164:167], v[210:213], v[8:11]
	v_mfma_f32_16x16x32_bf16 v[0:3], v[172:175], v[210:213], v[0:3]
	s_setprio 1
	s_barrier
	s_add_i32 s85, s85, 2
	s_add_u32 s83, s83, 0x100
	s_addc_u32 s84, s84, 0
	s_cmp_gt_u32 s85, 13
	s_cbranch_scc0 .LBB0_740
	s_and_b64 vcc, exec, s[28:29]
	s_cbranch_vccz .LBB0_743
	s_barrier
